# code placement: every 16-MFMA K-loop burst starts on an 8-byte boundary (14 s_nop 0 pads at load-segment starts)
# speedup vs baseline: 1.0098x; 1.0098x over previous
.LBB0_124:
	s_nop 0
	s_ashr_i32 s79, s78, 31
	s_lshl_b64 s[10:11], s[78:79], 19
	s_add_u32 s80, s54, s10
	v_cmp_lt_i64_e32 vcc, s[72:73], v[178:179]
	s_addc_u32 s81, s55, s11
	s_and_b64 s[10:11], vcc, exec
	s_cselect_b32 s1, s81, s87
	s_cselect_b32 s10, s80, s86
	s_ashr_i32 s77, s76, 31
	s_lshl_b64 s[36:37], s[76:77], 19
	s_add_u32 s72, s66, s36
	s_addc_u32 s73, s59, s37
	s_and_b64 s[36:37], vcc, exec
	s_cselect_b32 s11, s73, s83
	s_cselect_b32 s25, s72, s82
	s_add_u32 s86, s86, 0x40080
	s_addc_u32 s87, s87, 0
	s_add_u32 s33, s82, 0x100
	s_addc_u32 s36, s83, 0
	s_mov_b32 s37, -2
	s_add_u32 s27, s86, 0xfffc0080
	s_addc_u32 s56, s87, -1
	s_add_i32 s57, 0, 0x10000
	ds_read_b128 v[64:67], v217
	ds_read_b128 v[68:71], v217 offset:1024
	ds_read_b128 v[72:75], v217 offset:2048
	ds_read_b128 v[76:79], v217 offset:3072
	s_cmp_eq_u32 s37, 12
	s_cselect_b32 vcc_hi, s1, s56
	s_cselect_b32 vcc_lo, s10, s27
	s_cselect_b32 s83, s11, s36
	s_cselect_b32 s82, s25, s33
	s_add_i32 m0, s75, 0xc000
	ds_read_b128 v[80:83], v220
	ds_read_b128 v[84:87], v220 offset:1024
	ds_read_b128 v[88:91], v220 offset:2048
	ds_read_b128 v[92:95], v220 offset:3072
	ds_read_b128 v[188:191], v220 offset:4096
	ds_read_b128 v[192:195], v220 offset:5120
	ds_read_b128 v[196:199], v220 offset:6144
	ds_read_b128 v[200:203], v220 offset:7168
	global_load_lds_dwordx4 v164, s[86:87]
	s_add_i32 m0, s75, 0xe000
	s_nop 0
	global_load_lds_dwordx4 v166, s[86:87]
	s_waitcnt lgkmcnt(8)
	s_barrier
	s_waitcnt lgkmcnt(0)
	v_mfma_f32_16x16x32_bf16 v[146:149], v[64:67], v[80:83], 0
	v_mfma_f32_16x16x32_bf16 v[116:119], v[72:75], v[80:83], 0
	v_mfma_f32_16x16x32_bf16 v[158:161], v[64:67], v[88:91], 0
	v_mfma_f32_16x16x32_bf16 v[124:127], v[72:75], v[88:91], 0
	v_mfma_f32_16x16x32_bf16 v[154:157], v[64:67], v[188:191], 0
	v_mfma_f32_16x16x32_bf16 v[112:115], v[72:75], v[188:191], 0
	v_mfma_f32_16x16x32_bf16 v[150:153], v[64:67], v[196:199], 0
	v_mfma_f32_16x16x32_bf16 v[120:123], v[72:75], v[196:199], 0
	v_mfma_f32_16x16x32_bf16 v[146:149], v[68:71], v[84:87], v[146:149]
	v_mfma_f32_16x16x32_bf16 v[116:119], v[76:79], v[84:87], v[116:119]
	v_mfma_f32_16x16x32_bf16 v[158:161], v[68:71], v[92:95], v[158:161]
	v_mfma_f32_16x16x32_bf16 v[124:127], v[76:79], v[92:95], v[124:127]
	v_mfma_f32_16x16x32_bf16 v[154:157], v[68:71], v[192:195], v[154:157]
	v_mfma_f32_16x16x32_bf16 v[112:115], v[76:79], v[192:195], v[112:115]
	v_mfma_f32_16x16x32_bf16 v[150:153], v[68:71], v[200:203], v[150:153]
	v_mfma_f32_16x16x32_bf16 v[120:123], v[76:79], v[200:203], v[120:123]
	s_barrier
	s_add_i32 s27, 0, 0x14000
	s_add_i32 s56, s57, s74
	ds_read_b128 v[204:207], v217 offset:16384
	ds_read_b128 v[222:225], v217 offset:17408
	ds_read_b128 v[228:231], v217 offset:18432
	ds_read_b128 v[232:235], v217 offset:19456
	s_mov_b32 m0, s56
	global_load_lds_dwordx4 v144, s[82:83]
	s_add_i32 m0, s56, 0x2000
	s_nop 0
	global_load_lds_dwordx4 v162, s[82:83]
	s_barrier
	s_waitcnt lgkmcnt(0)
	v_mfma_f32_16x16x32_bf16 v[140:143], v[204:207], v[80:83], 0
	v_mfma_f32_16x16x32_bf16 v[80:83], v[228:231], v[80:83], 0
	v_mfma_f32_16x16x32_bf16 v[140:143], v[222:225], v[84:87], v[140:143]
	v_mfma_f32_16x16x32_bf16 v[80:83], v[232:235], v[84:87], v[80:83]
	v_mfma_f32_16x16x32_bf16 v[84:87], v[204:207], v[88:91], 0
	v_mfma_f32_16x16x32_bf16 v[88:91], v[228:231], v[88:91], 0
	v_mfma_f32_16x16x32_bf16 v[100:103], v[228:231], v[188:191], 0
	v_mfma_f32_16x16x32_bf16 v[104:107], v[204:207], v[196:199], 0
	v_mfma_f32_16x16x32_bf16 v[96:99], v[228:231], v[196:199], 0
	v_mfma_f32_16x16x32_bf16 v[84:87], v[222:225], v[92:95], v[84:87]
	v_mfma_f32_16x16x32_bf16 v[88:91], v[232:235], v[92:95], v[88:91]
	v_mfma_f32_16x16x32_bf16 v[92:95], v[204:207], v[188:191], 0
	v_mfma_f32_16x16x32_bf16 v[100:103], v[232:235], v[192:195], v[100:103]
	v_mfma_f32_16x16x32_bf16 v[128:131], v[222:225], v[200:203], v[104:107]
	v_mfma_f32_16x16x32_bf16 v[96:99], v[232:235], v[200:203], v[96:99]
	v_mfma_f32_16x16x32_bf16 v[92:95], v[222:225], v[192:195], v[92:95]
	s_barrier
	s_mov_b32 m0, s75
	ds_read_b128 v[104:107], v220 offset:16384
	ds_read_b128 v[108:111], v220 offset:17408
	ds_read_b128 v[132:135], v220 offset:18432
	ds_read_b128 v[136:139], v220 offset:19456
	ds_read_b128 v[188:191], v220 offset:20480
	ds_read_b128 v[192:195], v220 offset:21504
	ds_read_b128 v[196:199], v220 offset:22528
	ds_read_b128 v[200:203], v220 offset:23552
	global_load_lds_dwordx4 v144, vcc
	s_mov_b32 m0, s85
	s_nop 0
	global_load_lds_dwordx4 v162, vcc
	s_barrier
	s_waitcnt lgkmcnt(0)
	v_mfma_f32_16x16x32_bf16 v[48:51], v[64:67], v[104:107], 0
	v_mfma_f32_16x16x32_bf16 v[20:23], v[72:75], v[104:107], 0
	v_mfma_f32_16x16x32_bf16 v[60:63], v[64:67], v[132:135], 0
	v_mfma_f32_16x16x32_bf16 v[28:31], v[72:75], v[132:135], 0
	v_mfma_f32_16x16x32_bf16 v[56:59], v[64:67], v[188:191], 0
	v_mfma_f32_16x16x32_bf16 v[16:19], v[72:75], v[188:191], 0
	v_mfma_f32_16x16x32_bf16 v[52:55], v[64:67], v[196:199], 0
	v_mfma_f32_16x16x32_bf16 v[24:27], v[72:75], v[196:199], 0
	v_mfma_f32_16x16x32_bf16 v[48:51], v[68:71], v[108:111], v[48:51]
	v_mfma_f32_16x16x32_bf16 v[20:23], v[76:79], v[108:111], v[20:23]
	v_mfma_f32_16x16x32_bf16 v[60:63], v[68:71], v[136:139], v[60:63]
	v_mfma_f32_16x16x32_bf16 v[28:31], v[76:79], v[136:139], v[28:31]
	v_mfma_f32_16x16x32_bf16 v[56:59], v[68:71], v[192:195], v[56:59]
	v_mfma_f32_16x16x32_bf16 v[16:19], v[76:79], v[192:195], v[16:19]
	v_mfma_f32_16x16x32_bf16 v[52:55], v[68:71], v[200:203], v[52:55]
	v_mfma_f32_16x16x32_bf16 v[24:27], v[76:79], v[200:203], v[24:27]
	s_barrier
	s_add_u32 s56, s82, 0x40000
	s_addc_u32 s57, s83, 0
	s_add_i32 s27, s27, s74
	s_mov_b32 m0, s27
	s_nop 0
	global_load_lds_dwordx4 v144, s[56:57]
	s_add_i32 m0, s27, 0x2000
	s_nop 0
	global_load_lds_dwordx4 v162, s[56:57]
	s_waitcnt vmcnt(6)
	s_barrier
	v_mfma_f32_16x16x32_bf16 v[44:47], v[204:207], v[104:107], 0
	v_mfma_f32_16x16x32_bf16 v[12:15], v[228:231], v[104:107], 0
	v_mfma_f32_16x16x32_bf16 v[40:43], v[204:207], v[132:135], 0
	v_mfma_f32_16x16x32_bf16 v[8:11], v[228:231], v[132:135], 0
	v_mfma_f32_16x16x32_bf16 v[36:39], v[204:207], v[188:191], 0
	v_mfma_f32_16x16x32_bf16 v[4:7], v[228:231], v[188:191], 0
	v_mfma_f32_16x16x32_bf16 v[32:35], v[204:207], v[196:199], 0
	v_mfma_f32_16x16x32_bf16 v[0:3], v[228:231], v[196:199], 0
	v_mfma_f32_16x16x32_bf16 v[44:47], v[222:225], v[108:111], v[44:47]
	v_mfma_f32_16x16x32_bf16 v[12:15], v[232:235], v[108:111], v[12:15]
	v_mfma_f32_16x16x32_bf16 v[40:43], v[222:225], v[136:139], v[40:43]
	v_mfma_f32_16x16x32_bf16 v[8:11], v[232:235], v[136:139], v[8:11]
	v_mfma_f32_16x16x32_bf16 v[36:39], v[222:225], v[192:195], v[36:39]
	v_mfma_f32_16x16x32_bf16 v[4:7], v[232:235], v[192:195], v[4:7]
	v_mfma_f32_16x16x32_bf16 v[32:35], v[222:225], v[200:203], v[32:35]
	v_mfma_f32_16x16x32_bf16 v[0:3], v[232:235], v[200:203], v[0:3]
	s_barrier
	s_add_i32 s27, 0, 0x18000
	ds_read_b128 v[64:67], v217 offset:32768
	ds_read_b128 v[68:71], v217 offset:33792
	ds_read_b128 v[72:75], v217 offset:34816
	ds_read_b128 v[76:79], v217 offset:35840
	s_add_u32 s56, vcc_lo, 0x40000
	s_addc_u32 s57, vcc_hi, 0
	s_mov_b32 m0, s98
	ds_read_b128 v[104:107], v220 offset:32768
	ds_read_b128 v[108:111], v220 offset:33792
	ds_read_b128 v[132:135], v220 offset:34816
	ds_read_b128 v[188:191], v220 offset:35840
	ds_read_b128 v[192:195], v220 offset:36864
	ds_read_b128 v[196:199], v220 offset:37888
	ds_read_b128 v[200:203], v220 offset:38912
	ds_read_b128 v[204:207], v220 offset:39936
	global_load_lds_dwordx4 v144, s[56:57]
	s_mov_b32 m0, s29
	s_nop 0
	global_load_lds_dwordx4 v162, s[56:57]
	s_waitcnt lgkmcnt(8)
	s_barrier
	s_waitcnt lgkmcnt(0)
	v_mfma_f32_16x16x32_bf16 v[136:139], v[64:67], v[104:107], v[146:149]
	v_mfma_f32_16x16x32_bf16 v[146:149], v[68:71], v[108:111], v[136:139]
	v_mfma_f32_16x16x32_bf16 v[136:139], v[64:67], v[132:135], v[158:161]
	v_mfma_f32_16x16x32_bf16 v[158:161], v[68:71], v[188:191], v[136:139]
	v_mfma_f32_16x16x32_bf16 v[136:139], v[64:67], v[192:195], v[154:157]
	v_mfma_f32_16x16x32_bf16 v[116:119], v[72:75], v[104:107], v[116:119]
	v_mfma_f32_16x16x32_bf16 v[124:127], v[72:75], v[132:135], v[124:127]
	v_mfma_f32_16x16x32_bf16 v[154:157], v[68:71], v[196:199], v[136:139]
	v_mfma_f32_16x16x32_bf16 v[112:115], v[72:75], v[192:195], v[112:115]
	v_mfma_f32_16x16x32_bf16 v[136:139], v[64:67], v[200:203], v[150:153]
	v_mfma_f32_16x16x32_bf16 v[120:123], v[72:75], v[200:203], v[120:123]
	v_mfma_f32_16x16x32_bf16 v[116:119], v[76:79], v[108:111], v[116:119]
	v_mfma_f32_16x16x32_bf16 v[124:127], v[76:79], v[188:191], v[124:127]
	v_mfma_f32_16x16x32_bf16 v[112:115], v[76:79], v[196:199], v[112:115]
	v_mfma_f32_16x16x32_bf16 v[150:153], v[68:71], v[204:207], v[136:139]
	v_mfma_f32_16x16x32_bf16 v[120:123], v[76:79], v[204:207], v[120:123]
	s_barrier
	s_nop 0
	s_add_i32 s58, 0, 0x1c000
	s_add_i32 s27, s27, s74
	ds_read_b128 v[222:225], v217 offset:49152
	ds_read_b128 v[228:231], v217 offset:50176
	ds_read_b128 v[232:235], v217 offset:51200
	ds_read_b128 v[236:239], v217 offset:52224
	s_add_u32 s56, s82, s18
	s_addc_u32 s57, s83, s19
	s_mov_b32 m0, s27
	s_nop 0
	global_load_lds_dwordx4 v144, s[56:57]
	s_add_u32 s56, s82, s18
	s_addc_u32 s57, s83, s19
	s_add_i32 m0, s27, 0x2000
	s_nop 0
	global_load_lds_dwordx4 v162, s[56:57]
	s_barrier
	s_waitcnt lgkmcnt(0)
	v_mfma_f32_16x16x32_bf16 v[136:139], v[222:225], v[104:107], v[140:143]
	v_mfma_f32_16x16x32_bf16 v[80:83], v[232:235], v[104:107], v[80:83]
	v_mfma_f32_16x16x32_bf16 v[140:143], v[228:231], v[108:111], v[136:139]
	v_mfma_f32_16x16x32_bf16 v[108:111], v[236:239], v[108:111], v[80:83]
	v_mfma_f32_16x16x32_bf16 v[80:83], v[222:225], v[132:135], v[84:87]
	v_mfma_f32_16x16x32_bf16 v[136:139], v[228:231], v[188:191], v[80:83]
	v_mfma_f32_16x16x32_bf16 v[80:83], v[232:235], v[132:135], v[88:91]
	v_mfma_f32_16x16x32_bf16 v[104:107], v[236:239], v[188:191], v[80:83]
	v_mfma_f32_16x16x32_bf16 v[80:83], v[222:225], v[192:195], v[92:95]
	v_mfma_f32_16x16x32_bf16 v[132:135], v[228:231], v[196:199], v[80:83]
	v_mfma_f32_16x16x32_bf16 v[80:83], v[232:235], v[192:195], v[100:103]
	v_mfma_f32_16x16x32_bf16 v[100:103], v[236:239], v[196:199], v[80:83]
	v_mfma_f32_16x16x32_bf16 v[80:83], v[222:225], v[200:203], v[128:131]
	v_mfma_f32_16x16x32_bf16 v[128:131], v[228:231], v[204:207], v[80:83]
	v_mfma_f32_16x16x32_bf16 v[80:83], v[232:235], v[200:203], v[96:99]
	v_mfma_f32_16x16x32_bf16 v[96:99], v[236:239], v[204:207], v[80:83]
	s_barrier
	s_nop 0
	s_mov_b32 m0, s31
	s_add_u32 s56, vcc_lo, s18
	s_addc_u32 s57, vcc_hi, s19
	s_nop 2
	ds_read_b128 v[80:83], v220 offset:49152
	ds_read_b128 v[84:87], v220 offset:50176
	ds_read_b128 v[88:91], v220 offset:51200
	ds_read_b128 v[92:95], v220 offset:52224
	ds_read_b128 v[188:191], v220 offset:53248
	ds_read_b128 v[192:195], v220 offset:54272
	ds_read_b128 v[196:199], v220 offset:55296
	ds_read_b128 v[200:203], v220 offset:56320
	global_load_lds_dwordx4 v144, s[56:57]
	s_add_u32 s56, vcc_lo, s18
	s_addc_u32 s57, vcc_hi, s19
	s_mov_b32 m0, s34
	s_nop 0
	global_load_lds_dwordx4 v162, s[56:57]
	s_barrier
	s_waitcnt lgkmcnt(0)
	v_mfma_f32_16x16x32_bf16 v[48:51], v[64:67], v[80:83], v[48:51]
	v_mfma_f32_16x16x32_bf16 v[20:23], v[72:75], v[80:83], v[20:23]
	v_mfma_f32_16x16x32_bf16 v[60:63], v[64:67], v[88:91], v[60:63]
	v_mfma_f32_16x16x32_bf16 v[28:31], v[72:75], v[88:91], v[28:31]
	v_mfma_f32_16x16x32_bf16 v[56:59], v[64:67], v[188:191], v[56:59]
	v_mfma_f32_16x16x32_bf16 v[16:19], v[72:75], v[188:191], v[16:19]
	v_mfma_f32_16x16x32_bf16 v[52:55], v[64:67], v[196:199], v[52:55]
	v_mfma_f32_16x16x32_bf16 v[24:27], v[72:75], v[196:199], v[24:27]
	v_mfma_f32_16x16x32_bf16 v[48:51], v[68:71], v[84:87], v[48:51]
	v_mfma_f32_16x16x32_bf16 v[20:23], v[76:79], v[84:87], v[20:23]
	v_mfma_f32_16x16x32_bf16 v[60:63], v[68:71], v[92:95], v[60:63]
	v_mfma_f32_16x16x32_bf16 v[28:31], v[76:79], v[92:95], v[28:31]
	v_mfma_f32_16x16x32_bf16 v[56:59], v[68:71], v[192:195], v[56:59]
	v_mfma_f32_16x16x32_bf16 v[16:19], v[76:79], v[192:195], v[16:19]
	v_mfma_f32_16x16x32_bf16 v[52:55], v[68:71], v[200:203], v[52:55]
	v_mfma_f32_16x16x32_bf16 v[24:27], v[76:79], v[200:203], v[24:27]
	s_barrier
	s_add_u32 s56, s82, 0x40080
	s_addc_u32 s57, s83, 0
	s_add_i32 s27, s58, s74
	s_mov_b32 m0, s27
	s_nop 0
	global_load_lds_dwordx4 v144, s[56:57]
	s_add_i32 m0, s27, 0x2000
	s_nop 0
	global_load_lds_dwordx4 v162, s[56:57]
	s_waitcnt vmcnt(6)
	s_barrier
	v_mfma_f32_16x16x32_bf16 v[44:47], v[222:225], v[80:83], v[44:47]
	v_mfma_f32_16x16x32_bf16 v[12:15], v[232:235], v[80:83], v[12:15]
	v_mfma_f32_16x16x32_bf16 v[40:43], v[222:225], v[88:91], v[40:43]
	v_mfma_f32_16x16x32_bf16 v[8:11], v[232:235], v[88:91], v[8:11]
	v_mfma_f32_16x16x32_bf16 v[36:39], v[222:225], v[188:191], v[36:39]
	v_mfma_f32_16x16x32_bf16 v[4:7], v[232:235], v[188:191], v[4:7]
	v_mfma_f32_16x16x32_bf16 v[32:35], v[222:225], v[196:199], v[32:35]
	v_mfma_f32_16x16x32_bf16 v[0:3], v[232:235], v[196:199], v[0:3]
	v_mfma_f32_16x16x32_bf16 v[44:47], v[228:231], v[84:87], v[44:47]
	v_mfma_f32_16x16x32_bf16 v[12:15], v[236:239], v[84:87], v[12:15]
	v_mfma_f32_16x16x32_bf16 v[40:43], v[228:231], v[92:95], v[40:43]
	v_mfma_f32_16x16x32_bf16 v[8:11], v[236:239], v[92:95], v[8:11]
	v_mfma_f32_16x16x32_bf16 v[36:39], v[228:231], v[192:195], v[36:39]
	v_mfma_f32_16x16x32_bf16 v[4:7], v[236:239], v[192:195], v[4:7]
	v_mfma_f32_16x16x32_bf16 v[32:35], v[228:231], v[200:203], v[32:35]
	v_mfma_f32_16x16x32_bf16 v[0:3], v[236:239], v[200:203], v[0:3]
	s_barrier
	s_add_i32 s37, s37, 2
	s_add_u32 s86, s86, 0x100
	s_addc_u32 s87, s87, 0
	s_add_u32 s33, s33, 0x100
	s_addc_u32 s36, s36, 0
	s_cmp_gt_u32 s37, 13
.LBB0_125:
	s_nop 0
	s_add_u32 s27, s86, 0xfffc0080
	s_addc_u32 s56, s87, -1
	s_add_i32 s57, 0, 0x10000
	ds_read_b128 v[64:67], v217
	ds_read_b128 v[68:71], v217 offset:1024
	ds_read_b128 v[72:75], v217 offset:2048
	ds_read_b128 v[76:79], v217 offset:3072
	s_cmp_eq_u32 s37, 12
	s_cselect_b32 vcc_hi, s1, s56
	s_cselect_b32 vcc_lo, s10, s27
	s_cselect_b32 s83, s11, s36
	s_cselect_b32 s82, s25, s33
	s_add_i32 m0, s75, 0xc000
	ds_read_b128 v[80:83], v220
	ds_read_b128 v[84:87], v220 offset:1024
	ds_read_b128 v[88:91], v220 offset:2048
	ds_read_b128 v[92:95], v220 offset:3072
	ds_read_b128 v[188:191], v220 offset:4096
	ds_read_b128 v[192:195], v220 offset:5120
	ds_read_b128 v[196:199], v220 offset:6144
	ds_read_b128 v[200:203], v220 offset:7168
	global_load_lds_dwordx4 v164, s[86:87]
	s_add_i32 m0, s75, 0xe000
	s_nop 0
	global_load_lds_dwordx4 v166, s[86:87]
	s_waitcnt lgkmcnt(8)
	s_barrier
	s_waitcnt lgkmcnt(0)
	v_mfma_f32_16x16x32_bf16 v[146:149], v[64:67], v[80:83], v[146:149]
	v_mfma_f32_16x16x32_bf16 v[116:119], v[72:75], v[80:83], v[116:119]
	v_mfma_f32_16x16x32_bf16 v[158:161], v[64:67], v[88:91], v[158:161]
	v_mfma_f32_16x16x32_bf16 v[124:127], v[72:75], v[88:91], v[124:127]
	v_mfma_f32_16x16x32_bf16 v[154:157], v[64:67], v[188:191], v[154:157]
	v_mfma_f32_16x16x32_bf16 v[112:115], v[72:75], v[188:191], v[112:115]
	v_mfma_f32_16x16x32_bf16 v[150:153], v[64:67], v[196:199], v[150:153]
	v_mfma_f32_16x16x32_bf16 v[120:123], v[72:75], v[196:199], v[120:123]
	v_mfma_f32_16x16x32_bf16 v[146:149], v[68:71], v[84:87], v[146:149]
	v_mfma_f32_16x16x32_bf16 v[116:119], v[76:79], v[84:87], v[116:119]
	v_mfma_f32_16x16x32_bf16 v[158:161], v[68:71], v[92:95], v[158:161]
	v_mfma_f32_16x16x32_bf16 v[124:127], v[76:79], v[92:95], v[124:127]
	v_mfma_f32_16x16x32_bf16 v[154:157], v[68:71], v[192:195], v[154:157]
	v_mfma_f32_16x16x32_bf16 v[112:115], v[76:79], v[192:195], v[112:115]
	v_mfma_f32_16x16x32_bf16 v[150:153], v[68:71], v[200:203], v[150:153]
	v_mfma_f32_16x16x32_bf16 v[120:123], v[76:79], v[200:203], v[120:123]
	s_barrier
	s_add_i32 s27, 0, 0x14000
	s_add_i32 s56, s57, s74
	ds_read_b128 v[204:207], v217 offset:16384
	ds_read_b128 v[222:225], v217 offset:17408
	ds_read_b128 v[228:231], v217 offset:18432
	ds_read_b128 v[232:235], v217 offset:19456
	s_mov_b32 m0, s56
	global_load_lds_dwordx4 v144, s[82:83]
	s_add_i32 m0, s56, 0x2000
	s_nop 0
	global_load_lds_dwordx4 v162, s[82:83]
	s_barrier
	s_waitcnt lgkmcnt(0)
	v_mfma_f32_16x16x32_bf16 v[140:143], v[204:207], v[80:83], v[140:143]
	v_mfma_f32_16x16x32_bf16 v[80:83], v[228:231], v[80:83], v[108:111]
	v_mfma_f32_16x16x32_bf16 v[140:143], v[222:225], v[84:87], v[140:143]
	v_mfma_f32_16x16x32_bf16 v[80:83], v[232:235], v[84:87], v[80:83]
	v_mfma_f32_16x16x32_bf16 v[84:87], v[204:207], v[88:91], v[136:139]
	v_mfma_f32_16x16x32_bf16 v[88:91], v[228:231], v[88:91], v[104:107]
	v_mfma_f32_16x16x32_bf16 v[100:103], v[228:231], v[188:191], v[100:103]
	v_mfma_f32_16x16x32_bf16 v[104:107], v[204:207], v[196:199], v[128:131]
	v_mfma_f32_16x16x32_bf16 v[96:99], v[228:231], v[196:199], v[96:99]
	v_mfma_f32_16x16x32_bf16 v[84:87], v[222:225], v[92:95], v[84:87]
	v_mfma_f32_16x16x32_bf16 v[88:91], v[232:235], v[92:95], v[88:91]
	v_mfma_f32_16x16x32_bf16 v[92:95], v[204:207], v[188:191], v[132:135]
	v_mfma_f32_16x16x32_bf16 v[100:103], v[232:235], v[192:195], v[100:103]
	v_mfma_f32_16x16x32_bf16 v[128:131], v[222:225], v[200:203], v[104:107]
	v_mfma_f32_16x16x32_bf16 v[96:99], v[232:235], v[200:203], v[96:99]
	v_mfma_f32_16x16x32_bf16 v[92:95], v[222:225], v[192:195], v[92:95]
	s_barrier
	s_mov_b32 m0, s75
	ds_read_b128 v[104:107], v220 offset:16384
	ds_read_b128 v[108:111], v220 offset:17408
	ds_read_b128 v[132:135], v220 offset:18432
	ds_read_b128 v[136:139], v220 offset:19456
	ds_read_b128 v[188:191], v220 offset:20480
	ds_read_b128 v[192:195], v220 offset:21504
	ds_read_b128 v[196:199], v220 offset:22528
	ds_read_b128 v[200:203], v220 offset:23552
	global_load_lds_dwordx4 v144, vcc
	s_mov_b32 m0, s85
	s_nop 0
	global_load_lds_dwordx4 v162, vcc
	s_barrier
	s_waitcnt lgkmcnt(0)
	v_mfma_f32_16x16x32_bf16 v[48:51], v[64:67], v[104:107], v[48:51]
	v_mfma_f32_16x16x32_bf16 v[20:23], v[72:75], v[104:107], v[20:23]
	v_mfma_f32_16x16x32_bf16 v[60:63], v[64:67], v[132:135], v[60:63]
	v_mfma_f32_16x16x32_bf16 v[28:31], v[72:75], v[132:135], v[28:31]
	v_mfma_f32_16x16x32_bf16 v[56:59], v[64:67], v[188:191], v[56:59]
	v_mfma_f32_16x16x32_bf16 v[16:19], v[72:75], v[188:191], v[16:19]
	v_mfma_f32_16x16x32_bf16 v[52:55], v[64:67], v[196:199], v[52:55]
	v_mfma_f32_16x16x32_bf16 v[24:27], v[72:75], v[196:199], v[24:27]
	v_mfma_f32_16x16x32_bf16 v[48:51], v[68:71], v[108:111], v[48:51]
	v_mfma_f32_16x16x32_bf16 v[20:23], v[76:79], v[108:111], v[20:23]
	v_mfma_f32_16x16x32_bf16 v[60:63], v[68:71], v[136:139], v[60:63]
	v_mfma_f32_16x16x32_bf16 v[28:31], v[76:79], v[136:139], v[28:31]
	v_mfma_f32_16x16x32_bf16 v[56:59], v[68:71], v[192:195], v[56:59]
	v_mfma_f32_16x16x32_bf16 v[16:19], v[76:79], v[192:195], v[16:19]
	v_mfma_f32_16x16x32_bf16 v[52:55], v[68:71], v[200:203], v[52:55]
	v_mfma_f32_16x16x32_bf16 v[24:27], v[76:79], v[200:203], v[24:27]
	s_barrier
	s_add_u32 s56, s82, 0x40000
	s_addc_u32 s57, s83, 0
	s_add_i32 s27, s27, s74
	s_mov_b32 m0, s27
	s_nop 0
	global_load_lds_dwordx4 v144, s[56:57]
	s_add_i32 m0, s27, 0x2000
	s_nop 0
	global_load_lds_dwordx4 v162, s[56:57]
	s_waitcnt vmcnt(6)
	s_barrier
	v_mfma_f32_16x16x32_bf16 v[44:47], v[204:207], v[104:107], v[44:47]
	v_mfma_f32_16x16x32_bf16 v[12:15], v[228:231], v[104:107], v[12:15]
	v_mfma_f32_16x16x32_bf16 v[40:43], v[204:207], v[132:135], v[40:43]
	v_mfma_f32_16x16x32_bf16 v[8:11], v[228:231], v[132:135], v[8:11]
	v_mfma_f32_16x16x32_bf16 v[36:39], v[204:207], v[188:191], v[36:39]
	v_mfma_f32_16x16x32_bf16 v[4:7], v[228:231], v[188:191], v[4:7]
	v_mfma_f32_16x16x32_bf16 v[32:35], v[204:207], v[196:199], v[32:35]
	v_mfma_f32_16x16x32_bf16 v[0:3], v[228:231], v[196:199], v[0:3]
	v_mfma_f32_16x16x32_bf16 v[44:47], v[222:225], v[108:111], v[44:47]
	v_mfma_f32_16x16x32_bf16 v[12:15], v[232:235], v[108:111], v[12:15]
	v_mfma_f32_16x16x32_bf16 v[40:43], v[222:225], v[136:139], v[40:43]
	v_mfma_f32_16x16x32_bf16 v[8:11], v[232:235], v[136:139], v[8:11]
	v_mfma_f32_16x16x32_bf16 v[36:39], v[222:225], v[192:195], v[36:39]
	v_mfma_f32_16x16x32_bf16 v[4:7], v[232:235], v[192:195], v[4:7]
	v_mfma_f32_16x16x32_bf16 v[32:35], v[222:225], v[200:203], v[32:35]
	v_mfma_f32_16x16x32_bf16 v[0:3], v[232:235], v[200:203], v[0:3]
	s_barrier
	s_add_i32 s27, 0, 0x18000
	ds_read_b128 v[64:67], v217 offset:32768
	ds_read_b128 v[68:71], v217 offset:33792
	ds_read_b128 v[72:75], v217 offset:34816
	ds_read_b128 v[76:79], v217 offset:35840
	s_add_u32 s56, vcc_lo, 0x40000
	s_addc_u32 s57, vcc_hi, 0
	s_mov_b32 m0, s98
	ds_read_b128 v[104:107], v220 offset:32768
	ds_read_b128 v[108:111], v220 offset:33792
	ds_read_b128 v[132:135], v220 offset:34816
	ds_read_b128 v[188:191], v220 offset:35840
	ds_read_b128 v[192:195], v220 offset:36864
	ds_read_b128 v[196:199], v220 offset:37888
	ds_read_b128 v[200:203], v220 offset:38912
	ds_read_b128 v[204:207], v220 offset:39936
	global_load_lds_dwordx4 v144, s[56:57]
	s_mov_b32 m0, s29
	s_nop 0
	global_load_lds_dwordx4 v162, s[56:57]
	s_waitcnt lgkmcnt(8)
	s_barrier
	s_waitcnt lgkmcnt(0)
	v_mfma_f32_16x16x32_bf16 v[136:139], v[64:67], v[104:107], v[146:149]
	v_mfma_f32_16x16x32_bf16 v[146:149], v[68:71], v[108:111], v[136:139]
	v_mfma_f32_16x16x32_bf16 v[136:139], v[64:67], v[132:135], v[158:161]
	v_mfma_f32_16x16x32_bf16 v[158:161], v[68:71], v[188:191], v[136:139]
	v_mfma_f32_16x16x32_bf16 v[136:139], v[64:67], v[192:195], v[154:157]
	v_mfma_f32_16x16x32_bf16 v[116:119], v[72:75], v[104:107], v[116:119]
	v_mfma_f32_16x16x32_bf16 v[124:127], v[72:75], v[132:135], v[124:127]
	v_mfma_f32_16x16x32_bf16 v[154:157], v[68:71], v[196:199], v[136:139]
	v_mfma_f32_16x16x32_bf16 v[112:115], v[72:75], v[192:195], v[112:115]
	v_mfma_f32_16x16x32_bf16 v[136:139], v[64:67], v[200:203], v[150:153]
	v_mfma_f32_16x16x32_bf16 v[120:123], v[72:75], v[200:203], v[120:123]
	v_mfma_f32_16x16x32_bf16 v[116:119], v[76:79], v[108:111], v[116:119]
	v_mfma_f32_16x16x32_bf16 v[124:127], v[76:79], v[188:191], v[124:127]
	v_mfma_f32_16x16x32_bf16 v[112:115], v[76:79], v[196:199], v[112:115]
	v_mfma_f32_16x16x32_bf16 v[150:153], v[68:71], v[204:207], v[136:139]
	v_mfma_f32_16x16x32_bf16 v[120:123], v[76:79], v[204:207], v[120:123]
	s_barrier
	s_nop 0
	s_add_i32 s58, 0, 0x1c000
	s_add_i32 s27, s27, s74
	ds_read_b128 v[222:225], v217 offset:49152
	ds_read_b128 v[228:231], v217 offset:50176
	ds_read_b128 v[232:235], v217 offset:51200
	ds_read_b128 v[236:239], v217 offset:52224
	s_add_u32 s56, s82, s18
	s_addc_u32 s57, s83, s19
	s_mov_b32 m0, s27
	s_nop 0
	global_load_lds_dwordx4 v144, s[56:57]
	s_add_u32 s56, s82, s18
	s_addc_u32 s57, s83, s19
	s_add_i32 m0, s27, 0x2000
	s_nop 0
	global_load_lds_dwordx4 v162, s[56:57]
	s_barrier
	s_waitcnt lgkmcnt(0)
	v_mfma_f32_16x16x32_bf16 v[136:139], v[222:225], v[104:107], v[140:143]
	v_mfma_f32_16x16x32_bf16 v[80:83], v[232:235], v[104:107], v[80:83]
	v_mfma_f32_16x16x32_bf16 v[140:143], v[228:231], v[108:111], v[136:139]
	v_mfma_f32_16x16x32_bf16 v[108:111], v[236:239], v[108:111], v[80:83]
	v_mfma_f32_16x16x32_bf16 v[80:83], v[222:225], v[132:135], v[84:87]
	v_mfma_f32_16x16x32_bf16 v[136:139], v[228:231], v[188:191], v[80:83]
	v_mfma_f32_16x16x32_bf16 v[80:83], v[232:235], v[132:135], v[88:91]
	v_mfma_f32_16x16x32_bf16 v[104:107], v[236:239], v[188:191], v[80:83]
	v_mfma_f32_16x16x32_bf16 v[80:83], v[222:225], v[192:195], v[92:95]
	v_mfma_f32_16x16x32_bf16 v[132:135], v[228:231], v[196:199], v[80:83]
	v_mfma_f32_16x16x32_bf16 v[80:83], v[232:235], v[192:195], v[100:103]
	v_mfma_f32_16x16x32_bf16 v[100:103], v[236:239], v[196:199], v[80:83]
	v_mfma_f32_16x16x32_bf16 v[80:83], v[222:225], v[200:203], v[128:131]
	v_mfma_f32_16x16x32_bf16 v[128:131], v[228:231], v[204:207], v[80:83]
	v_mfma_f32_16x16x32_bf16 v[80:83], v[232:235], v[200:203], v[96:99]
	v_mfma_f32_16x16x32_bf16 v[96:99], v[236:239], v[204:207], v[80:83]
	s_barrier
	s_nop 0
	s_mov_b32 m0, s31
	s_add_u32 s56, vcc_lo, s18
	s_addc_u32 s57, vcc_hi, s19
	s_nop 2
	ds_read_b128 v[80:83], v220 offset:49152
	ds_read_b128 v[84:87], v220 offset:50176
	ds_read_b128 v[88:91], v220 offset:51200
	ds_read_b128 v[92:95], v220 offset:52224
	ds_read_b128 v[188:191], v220 offset:53248
	ds_read_b128 v[192:195], v220 offset:54272
	ds_read_b128 v[196:199], v220 offset:55296
	ds_read_b128 v[200:203], v220 offset:56320
	global_load_lds_dwordx4 v144, s[56:57]
	s_add_u32 s56, vcc_lo, s18
	s_addc_u32 s57, vcc_hi, s19
	s_mov_b32 m0, s34
	s_nop 0
	global_load_lds_dwordx4 v162, s[56:57]
	s_barrier
	s_waitcnt lgkmcnt(0)
	v_mfma_f32_16x16x32_bf16 v[48:51], v[64:67], v[80:83], v[48:51]
	v_mfma_f32_16x16x32_bf16 v[20:23], v[72:75], v[80:83], v[20:23]
	v_mfma_f32_16x16x32_bf16 v[60:63], v[64:67], v[88:91], v[60:63]
	v_mfma_f32_16x16x32_bf16 v[28:31], v[72:75], v[88:91], v[28:31]
	v_mfma_f32_16x16x32_bf16 v[56:59], v[64:67], v[188:191], v[56:59]
	v_mfma_f32_16x16x32_bf16 v[16:19], v[72:75], v[188:191], v[16:19]
	v_mfma_f32_16x16x32_bf16 v[52:55], v[64:67], v[196:199], v[52:55]
	v_mfma_f32_16x16x32_bf16 v[24:27], v[72:75], v[196:199], v[24:27]
	v_mfma_f32_16x16x32_bf16 v[48:51], v[68:71], v[84:87], v[48:51]
	v_mfma_f32_16x16x32_bf16 v[20:23], v[76:79], v[84:87], v[20:23]
	v_mfma_f32_16x16x32_bf16 v[60:63], v[68:71], v[92:95], v[60:63]
	v_mfma_f32_16x16x32_bf16 v[28:31], v[76:79], v[92:95], v[28:31]
	v_mfma_f32_16x16x32_bf16 v[56:59], v[68:71], v[192:195], v[56:59]
	v_mfma_f32_16x16x32_bf16 v[16:19], v[76:79], v[192:195], v[16:19]
	v_mfma_f32_16x16x32_bf16 v[52:55], v[68:71], v[200:203], v[52:55]
	v_mfma_f32_16x16x32_bf16 v[24:27], v[76:79], v[200:203], v[24:27]
	s_barrier
	s_add_u32 s56, s82, 0x40080
	s_addc_u32 s57, s83, 0
	s_add_i32 s27, s58, s74
	s_mov_b32 m0, s27
	s_nop 0
	global_load_lds_dwordx4 v144, s[56:57]
	s_add_i32 m0, s27, 0x2000
	s_nop 0
	global_load_lds_dwordx4 v162, s[56:57]
	s_waitcnt vmcnt(6)
	s_barrier
	v_mfma_f32_16x16x32_bf16 v[44:47], v[222:225], v[80:83], v[44:47]
	v_mfma_f32_16x16x32_bf16 v[12:15], v[232:235], v[80:83], v[12:15]
	v_mfma_f32_16x16x32_bf16 v[40:43], v[222:225], v[88:91], v[40:43]
	v_mfma_f32_16x16x32_bf16 v[8:11], v[232:235], v[88:91], v[8:11]
	v_mfma_f32_16x16x32_bf16 v[36:39], v[222:225], v[188:191], v[36:39]
	v_mfma_f32_16x16x32_bf16 v[4:7], v[232:235], v[188:191], v[4:7]
	v_mfma_f32_16x16x32_bf16 v[32:35], v[222:225], v[196:199], v[32:35]
	v_mfma_f32_16x16x32_bf16 v[0:3], v[232:235], v[196:199], v[0:3]
	v_mfma_f32_16x16x32_bf16 v[44:47], v[228:231], v[84:87], v[44:47]
	v_mfma_f32_16x16x32_bf16 v[12:15], v[236:239], v[84:87], v[12:15]
	v_mfma_f32_16x16x32_bf16 v[40:43], v[228:231], v[92:95], v[40:43]
	v_mfma_f32_16x16x32_bf16 v[8:11], v[236:239], v[92:95], v[8:11]
	v_mfma_f32_16x16x32_bf16 v[36:39], v[228:231], v[192:195], v[36:39]
	v_mfma_f32_16x16x32_bf16 v[4:7], v[236:239], v[192:195], v[4:7]
	v_mfma_f32_16x16x32_bf16 v[32:35], v[228:231], v[200:203], v[32:35]
	v_mfma_f32_16x16x32_bf16 v[0:3], v[236:239], v[200:203], v[0:3]
	s_barrier
	s_add_i32 s37, s37, 2
	s_add_u32 s86, s86, 0x100
	s_addc_u32 s87, s87, 0
	s_add_u32 s33, s33, 0x100
	s_addc_u32 s36, s36, 0
	s_cmp_gt_u32 s37, 13
	s_cbranch_scc0 .LBB0_125
	s_lshl_b32 s1, s84, 8
	v_readlane_b32 s10, v254, 61
	s_add_i32 s1, s1, s10
	v_or_b32_e32 v198, s1, v216
	s_add_i32 s10, s1, 0x80
	v_or_b32_e32 v168, s10, v216
	v_lshl_or_b32 v188, s0, 7, v219
	v_lshlrev_b32_e32 v190, 2, v188
	v_lshlrev_b32_e32 v189, 1, v188
	s_ashr_i32 s11, s1, 5
	s_movk_i32 s10, 0xb00
	s_movk_i32 s20, 0x1600
	s_mov_b32 s101, 0xbfb8aa3b
	s_cmp_eq_u32 s84, s100
	s_cbranch_scc1 .Ldepi_w
	v_ashrrev_i32_e32 v199, 31, v198
	v_ashrrev_i32_e32 v169, 31, v168
	v_lshl_add_u64 v[170:171], v[198:199], 3, s[48:49]
	v_lshl_add_u64 v[172:173], v[168:169], 3, s[48:49]
	global_load_dwordx2 v[176:177], v[170:171], off
	global_load_dwordx2 v[202:203], v[170:171], off offset:128
	global_load_dwordx2 v[206:207], v[170:171], off offset:256
	global_load_dwordx2 v[222:223], v[170:171], off offset:384
	global_load_dwordx2 v[200:201], v[172:173], off
	global_load_dwordx2 v[196:197], v[172:173], off offset:128
	global_load_dwordx2 v[194:195], v[172:173], off offset:256
	global_load_dwordx2 v[192:193], v[172:173], off offset:384

.LBB0_195:
	s_add_u32 s42, s78, 0x80
	s_addc_u32 s43, s79, 0
	s_add_u32 s33, s44, 0x100
	s_addc_u32 s37, s45, 0
	s_mov_b32 s27, 0
	s_waitcnt lgkmcnt(0)
	s_add_i32 s56, s27, 2
	s_add_u32 s44, s42, 0x80
	s_addc_u32 s45, s43, 0
	s_add_i32 s57, 0, 0x10000
	ds_read_b128 v[128:131], v207
	ds_read_b128 v[132:135], v207 offset:1024
	ds_read_b128 v[136:139], v207 offset:2048
	ds_read_b128 v[140:143], v207 offset:3072
	s_cmp_eq_u32 s82, s27
	s_cselect_b32 s45, s77, s45
	s_cselect_b32 s44, s76, s44
	s_cselect_b32 s79, s1, s37
	s_cselect_b32 s78, s0, s33
	v_lshl_add_u64 v[176:177], s[42:43], 0, v[190:191]
	s_add_i32 m0, s85, 0xc000
	ds_read_b128 v[146:149], v217
	ds_read_b128 v[150:153], v217 offset:1024
	ds_read_b128 v[154:157], v217 offset:2048
	ds_read_b128 v[158:161], v217 offset:3072
	ds_read_b128 v[162:165], v217 offset:4096
	ds_read_b128 v[166:169], v217 offset:5120
	ds_read_b128 v[194:197], v217 offset:6144
	ds_read_b128 v[198:201], v217 offset:7168
	global_load_lds_dwordx4 v[176:177], off
	v_lshl_add_u64 v[176:177], s[42:43], 0, v[192:193]
	s_add_i32 m0, s85, 0xe000
	s_nop 0
	global_load_lds_dwordx4 v[176:177], off
	s_waitcnt lgkmcnt(8)
	s_barrier
	s_waitcnt lgkmcnt(0)
	v_mfma_f32_16x16x32_bf16 v[124:127], v[128:131], v[146:149], 0
	v_mfma_f32_16x16x32_bf16 v[120:123], v[136:139], v[146:149], 0
	v_mfma_f32_16x16x32_bf16 v[108:111], v[128:131], v[154:157], 0
	v_mfma_f32_16x16x32_bf16 v[104:107], v[136:139], v[154:157], 0
	v_mfma_f32_16x16x32_bf16 v[92:95], v[128:131], v[162:165], 0
	v_mfma_f32_16x16x32_bf16 v[88:91], v[136:139], v[162:165], 0
	v_mfma_f32_16x16x32_bf16 v[76:79], v[128:131], v[194:197], 0
	v_mfma_f32_16x16x32_bf16 v[72:75], v[136:139], v[194:197], 0
	v_mfma_f32_16x16x32_bf16 v[124:127], v[132:135], v[150:153], v[124:127]
	v_mfma_f32_16x16x32_bf16 v[120:123], v[140:143], v[150:153], v[120:123]
	v_mfma_f32_16x16x32_bf16 v[108:111], v[132:135], v[158:161], v[108:111]
	v_mfma_f32_16x16x32_bf16 v[104:107], v[140:143], v[158:161], v[104:107]
	v_mfma_f32_16x16x32_bf16 v[92:95], v[132:135], v[166:169], v[92:95]
	v_mfma_f32_16x16x32_bf16 v[88:91], v[140:143], v[166:169], v[88:91]
	v_mfma_f32_16x16x32_bf16 v[76:79], v[132:135], v[198:201], v[76:79]
	v_mfma_f32_16x16x32_bf16 v[72:75], v[140:143], v[198:201], v[72:75]
	s_barrier
	s_add_i32 s27, 0, 0x14000
	s_add_i32 s57, s57, s84
	ds_read_b128 v[202:205], v207 offset:16384
	ds_read_b128 v[218:221], v207 offset:17408
	ds_read_b128 v[222:225], v207 offset:18432
	ds_read_b128 v[228:231], v207 offset:19456
	v_lshl_add_u64 v[176:177], s[78:79], 0, v[144:145]
	s_mov_b32 m0, s57
	v_lshl_add_u64 v[232:233], s[78:79], 0, v[188:189]
	global_load_lds_dwordx4 v[176:177], off
	s_add_i32 m0, s57, 0x2000
	s_nop 0
	global_load_lds_dwordx4 v[232:233], off
	s_barrier
	s_waitcnt lgkmcnt(0)
	v_mfma_f32_16x16x32_bf16 v[116:119], v[202:205], v[146:149], 0
	v_mfma_f32_16x16x32_bf16 v[112:115], v[222:225], v[146:149], 0
	v_mfma_f32_16x16x32_bf16 v[100:103], v[202:205], v[154:157], 0
	v_mfma_f32_16x16x32_bf16 v[96:99], v[222:225], v[154:157], 0
	v_mfma_f32_16x16x32_bf16 v[84:87], v[202:205], v[162:165], 0
	v_mfma_f32_16x16x32_bf16 v[80:83], v[222:225], v[162:165], 0
	v_mfma_f32_16x16x32_bf16 v[68:71], v[202:205], v[194:197], 0
	v_mfma_f32_16x16x32_bf16 v[64:67], v[222:225], v[194:197], 0
	v_mfma_f32_16x16x32_bf16 v[116:119], v[218:221], v[150:153], v[116:119]
	v_mfma_f32_16x16x32_bf16 v[112:115], v[228:231], v[150:153], v[112:115]
	v_mfma_f32_16x16x32_bf16 v[100:103], v[218:221], v[158:161], v[100:103]
	v_mfma_f32_16x16x32_bf16 v[96:99], v[228:231], v[158:161], v[96:99]
	v_mfma_f32_16x16x32_bf16 v[84:87], v[218:221], v[166:169], v[84:87]
	v_mfma_f32_16x16x32_bf16 v[80:83], v[228:231], v[166:169], v[80:83]
	v_mfma_f32_16x16x32_bf16 v[68:71], v[218:221], v[198:201], v[68:71]
	v_mfma_f32_16x16x32_bf16 v[64:67], v[228:231], v[198:201], v[64:67]
	s_barrier
	s_mov_b32 m0, s85
	v_lshl_add_u64 v[234:235], s[44:45], 0, v[144:145]
	ds_read_b128 v[146:149], v217 offset:16384
	ds_read_b128 v[150:153], v217 offset:17408
	ds_read_b128 v[154:157], v217 offset:18432
	ds_read_b128 v[158:161], v217 offset:19456
	ds_read_b128 v[162:165], v217 offset:20480
	ds_read_b128 v[166:169], v217 offset:21504
	ds_read_b128 v[194:197], v217 offset:22528
	ds_read_b128 v[198:201], v217 offset:23552
	global_load_lds_dwordx4 v[234:235], off
	v_lshl_add_u64 v[236:237], s[44:45], 0, v[188:189]
	s_mov_b32 m0, s86
	s_nop 0
	global_load_lds_dwordx4 v[236:237], off
	s_barrier
	s_waitcnt lgkmcnt(0)
	v_mfma_f32_16x16x32_bf16 v[60:63], v[128:131], v[146:149], 0
	v_mfma_f32_16x16x32_bf16 v[56:59], v[136:139], v[146:149], 0
	v_mfma_f32_16x16x32_bf16 v[44:47], v[128:131], v[154:157], 0
	v_mfma_f32_16x16x32_bf16 v[40:43], v[136:139], v[154:157], 0
	v_mfma_f32_16x16x32_bf16 v[28:31], v[128:131], v[162:165], 0
	v_mfma_f32_16x16x32_bf16 v[24:27], v[136:139], v[162:165], 0
	v_mfma_f32_16x16x32_bf16 v[12:15], v[128:131], v[194:197], 0
	v_mfma_f32_16x16x32_bf16 v[8:11], v[136:139], v[194:197], 0
	v_mfma_f32_16x16x32_bf16 v[60:63], v[132:135], v[150:153], v[60:63]
	v_mfma_f32_16x16x32_bf16 v[56:59], v[140:143], v[150:153], v[56:59]
	v_mfma_f32_16x16x32_bf16 v[44:47], v[132:135], v[158:161], v[44:47]
	v_mfma_f32_16x16x32_bf16 v[40:43], v[140:143], v[158:161], v[40:43]
	v_mfma_f32_16x16x32_bf16 v[28:31], v[132:135], v[166:169], v[28:31]
	v_mfma_f32_16x16x32_bf16 v[24:27], v[140:143], v[166:169], v[24:27]
	v_mfma_f32_16x16x32_bf16 v[12:15], v[132:135], v[198:201], v[12:15]
	v_mfma_f32_16x16x32_bf16 v[8:11], v[140:143], v[198:201], v[8:11]
	s_barrier
	s_add_u32 s58, s78, s98
	s_addc_u32 s59, s79, 0
	s_add_i32 s27, s27, s84
	v_lshl_add_u64 v[238:239], s[58:59], 0, v[144:145]
	s_mov_b32 m0, s27
	v_lshl_add_u64 v[240:241], s[58:59], 0, v[188:189]
	global_load_lds_dwordx4 v[238:239], off
	s_add_i32 m0, s27, 0x2000
	s_nop 0
	global_load_lds_dwordx4 v[240:241], off
	s_waitcnt vmcnt(6)
	s_barrier
	v_mfma_f32_16x16x32_bf16 v[52:55], v[202:205], v[146:149], 0
	v_mfma_f32_16x16x32_bf16 v[48:51], v[222:225], v[146:149], 0
	v_mfma_f32_16x16x32_bf16 v[36:39], v[202:205], v[154:157], 0
	v_mfma_f32_16x16x32_bf16 v[32:35], v[222:225], v[154:157], 0
	v_mfma_f32_16x16x32_bf16 v[20:23], v[202:205], v[162:165], 0
	v_mfma_f32_16x16x32_bf16 v[16:19], v[222:225], v[162:165], 0
	v_mfma_f32_16x16x32_bf16 v[4:7], v[202:205], v[194:197], 0
	v_mfma_f32_16x16x32_bf16 v[0:3], v[222:225], v[194:197], 0
	v_mfma_f32_16x16x32_bf16 v[52:55], v[218:221], v[150:153], v[52:55]
	v_mfma_f32_16x16x32_bf16 v[48:51], v[228:231], v[150:153], v[48:51]
	v_mfma_f32_16x16x32_bf16 v[36:39], v[218:221], v[158:161], v[36:39]
	v_mfma_f32_16x16x32_bf16 v[32:35], v[228:231], v[158:161], v[32:35]
	v_mfma_f32_16x16x32_bf16 v[20:23], v[218:221], v[166:169], v[20:23]
	v_mfma_f32_16x16x32_bf16 v[16:19], v[228:231], v[166:169], v[16:19]
	v_mfma_f32_16x16x32_bf16 v[4:7], v[218:221], v[198:201], v[4:7]
	v_mfma_f32_16x16x32_bf16 v[0:3], v[228:231], v[198:201], v[0:3]
	s_barrier
	s_nop 0
	s_add_i32 s27, 0, 0x18000
	ds_read_b128 v[128:131], v207 offset:32768
	ds_read_b128 v[132:135], v207 offset:33792
	ds_read_b128 v[136:139], v207 offset:34816
	ds_read_b128 v[140:143], v207 offset:35840
	s_add_u32 s44, s44, s98
	s_addc_u32 s45, s45, 0
	s_mov_b32 m0, s87
	ds_read_b128 v[146:149], v217 offset:32768
	ds_read_b128 v[150:153], v217 offset:33792
	ds_read_b128 v[154:157], v217 offset:34816
	ds_read_b128 v[158:161], v217 offset:35840
	ds_read_b128 v[162:165], v217 offset:36864
	ds_read_b128 v[166:169], v217 offset:37888
	ds_read_b128 v[194:197], v217 offset:38912
	ds_read_b128 v[198:201], v217 offset:39936
	global_load_lds_dwordx4 v144, s[44:45]
	s_mov_b32 m0, s80
	s_nop 0
	global_load_lds_dwordx4 v188, s[44:45]
	s_waitcnt lgkmcnt(8)
	s_barrier
	s_waitcnt lgkmcnt(0)
	v_mfma_f32_16x16x32_bf16 v[124:127], v[128:131], v[146:149], v[124:127]
	v_mfma_f32_16x16x32_bf16 v[120:123], v[136:139], v[146:149], v[120:123]
	v_mfma_f32_16x16x32_bf16 v[108:111], v[128:131], v[154:157], v[108:111]
	v_mfma_f32_16x16x32_bf16 v[104:107], v[136:139], v[154:157], v[104:107]
	v_mfma_f32_16x16x32_bf16 v[92:95], v[128:131], v[162:165], v[92:95]
	v_mfma_f32_16x16x32_bf16 v[88:91], v[136:139], v[162:165], v[88:91]
	v_mfma_f32_16x16x32_bf16 v[76:79], v[128:131], v[194:197], v[76:79]
	v_mfma_f32_16x16x32_bf16 v[72:75], v[136:139], v[194:197], v[72:75]
	v_mfma_f32_16x16x32_bf16 v[124:127], v[132:135], v[150:153], v[124:127]
	v_mfma_f32_16x16x32_bf16 v[120:123], v[140:143], v[150:153], v[120:123]
	v_mfma_f32_16x16x32_bf16 v[108:111], v[132:135], v[158:161], v[108:111]
	v_mfma_f32_16x16x32_bf16 v[104:107], v[140:143], v[158:161], v[104:107]
	v_mfma_f32_16x16x32_bf16 v[92:95], v[132:135], v[166:169], v[92:95]
	v_mfma_f32_16x16x32_bf16 v[88:91], v[140:143], v[166:169], v[88:91]
	v_mfma_f32_16x16x32_bf16 v[76:79], v[132:135], v[198:201], v[76:79]
	v_mfma_f32_16x16x32_bf16 v[72:75], v[140:143], v[198:201], v[72:75]
	s_barrier
	s_add_i32 s44, 0, 0x1c000
	s_add_i32 s27, s27, s84
	v_lshl_add_u64 v[176:177], v[176:177], 0, s[18:19]
	s_mov_b32 m0, s27
	ds_read_b128 v[202:205], v207 offset:49152
	ds_read_b128 v[218:221], v207 offset:50176
	ds_read_b128 v[222:225], v207 offset:51200
	ds_read_b128 v[228:231], v207 offset:52224
	global_load_lds_dwordx4 v[176:177], off
	v_lshl_add_u64 v[176:177], v[232:233], 0, s[18:19]
	s_add_i32 m0, s27, 0x2000
	s_nop 0
	global_load_lds_dwordx4 v[176:177], off
	s_barrier
	s_waitcnt lgkmcnt(0)
	v_mfma_f32_16x16x32_bf16 v[116:119], v[202:205], v[146:149], v[116:119]
	v_mfma_f32_16x16x32_bf16 v[112:115], v[222:225], v[146:149], v[112:115]
	v_mfma_f32_16x16x32_bf16 v[100:103], v[202:205], v[154:157], v[100:103]
	v_mfma_f32_16x16x32_bf16 v[96:99], v[222:225], v[154:157], v[96:99]
	v_mfma_f32_16x16x32_bf16 v[84:87], v[202:205], v[162:165], v[84:87]
	v_mfma_f32_16x16x32_bf16 v[80:83], v[222:225], v[162:165], v[80:83]
	v_mfma_f32_16x16x32_bf16 v[68:71], v[202:205], v[194:197], v[68:71]
	v_mfma_f32_16x16x32_bf16 v[64:67], v[222:225], v[194:197], v[64:67]
	v_mfma_f32_16x16x32_bf16 v[116:119], v[218:221], v[150:153], v[116:119]
	v_mfma_f32_16x16x32_bf16 v[112:115], v[228:231], v[150:153], v[112:115]
	v_mfma_f32_16x16x32_bf16 v[100:103], v[218:221], v[158:161], v[100:103]
	v_mfma_f32_16x16x32_bf16 v[96:99], v[228:231], v[158:161], v[96:99]
	v_mfma_f32_16x16x32_bf16 v[84:87], v[218:221], v[166:169], v[84:87]
	v_mfma_f32_16x16x32_bf16 v[80:83], v[228:231], v[166:169], v[80:83]
	v_mfma_f32_16x16x32_bf16 v[68:71], v[218:221], v[198:201], v[68:71]
	v_mfma_f32_16x16x32_bf16 v[64:67], v[228:231], v[198:201], v[64:67]
	s_barrier
	s_mov_b32 m0, s30
	v_lshl_add_u64 v[176:177], v[234:235], 0, s[18:19]
	ds_read_b128 v[146:149], v217 offset:49152
	ds_read_b128 v[150:153], v217 offset:50176
	ds_read_b128 v[154:157], v217 offset:51200
	ds_read_b128 v[158:161], v217 offset:52224
	ds_read_b128 v[162:165], v217 offset:53248
	ds_read_b128 v[166:169], v217 offset:54272
	ds_read_b128 v[194:197], v217 offset:55296
	ds_read_b128 v[198:201], v217 offset:56320
	global_load_lds_dwordx4 v[176:177], off
	v_lshl_add_u64 v[176:177], v[236:237], 0, s[18:19]
	s_mov_b32 m0, s31
	s_nop 0
	global_load_lds_dwordx4 v[176:177], off
	s_barrier
	s_waitcnt lgkmcnt(0)
	v_mfma_f32_16x16x32_bf16 v[60:63], v[128:131], v[146:149], v[60:63]
	v_mfma_f32_16x16x32_bf16 v[56:59], v[136:139], v[146:149], v[56:59]
	v_mfma_f32_16x16x32_bf16 v[44:47], v[128:131], v[154:157], v[44:47]
	v_mfma_f32_16x16x32_bf16 v[40:43], v[136:139], v[154:157], v[40:43]
	v_mfma_f32_16x16x32_bf16 v[28:31], v[128:131], v[162:165], v[28:31]
	v_mfma_f32_16x16x32_bf16 v[24:27], v[136:139], v[162:165], v[24:27]
	v_mfma_f32_16x16x32_bf16 v[12:15], v[128:131], v[194:197], v[12:15]
	v_mfma_f32_16x16x32_bf16 v[8:11], v[136:139], v[194:197], v[8:11]
	v_mfma_f32_16x16x32_bf16 v[60:63], v[132:135], v[150:153], v[60:63]
	v_mfma_f32_16x16x32_bf16 v[56:59], v[140:143], v[150:153], v[56:59]
	v_mfma_f32_16x16x32_bf16 v[44:47], v[132:135], v[158:161], v[44:47]
	v_mfma_f32_16x16x32_bf16 v[40:43], v[140:143], v[158:161], v[40:43]
	v_mfma_f32_16x16x32_bf16 v[28:31], v[132:135], v[166:169], v[28:31]
	v_mfma_f32_16x16x32_bf16 v[24:27], v[140:143], v[166:169], v[24:27]
	v_mfma_f32_16x16x32_bf16 v[12:15], v[132:135], v[198:201], v[12:15]
	v_mfma_f32_16x16x32_bf16 v[8:11], v[140:143], v[198:201], v[8:11]
	s_barrier
	s_nop 0
	s_add_i32 s27, s44, s84
	v_lshl_add_u64 v[128:129], v[238:239], 0, s[18:19]
	s_mov_b32 m0, s27
	s_nop 0
	global_load_lds_dwordx4 v[128:129], off
	v_lshl_add_u64 v[128:129], v[240:241], 0, s[18:19]
	s_add_i32 m0, s27, 0x2000
	s_nop 0
	global_load_lds_dwordx4 v[128:129], off
	s_waitcnt vmcnt(6)
	s_barrier
	v_mfma_f32_16x16x32_bf16 v[52:55], v[202:205], v[146:149], v[52:55]
	v_mfma_f32_16x16x32_bf16 v[48:51], v[222:225], v[146:149], v[48:51]
	v_mfma_f32_16x16x32_bf16 v[36:39], v[202:205], v[154:157], v[36:39]
	v_mfma_f32_16x16x32_bf16 v[32:35], v[222:225], v[154:157], v[32:35]
	v_mfma_f32_16x16x32_bf16 v[20:23], v[202:205], v[162:165], v[20:23]
	v_mfma_f32_16x16x32_bf16 v[16:19], v[222:225], v[162:165], v[16:19]
	v_mfma_f32_16x16x32_bf16 v[4:7], v[202:205], v[194:197], v[4:7]
	v_mfma_f32_16x16x32_bf16 v[0:3], v[222:225], v[194:197], v[0:3]
	v_mfma_f32_16x16x32_bf16 v[52:55], v[218:221], v[150:153], v[52:55]
	v_mfma_f32_16x16x32_bf16 v[48:51], v[228:231], v[150:153], v[48:51]
	v_mfma_f32_16x16x32_bf16 v[36:39], v[218:221], v[158:161], v[36:39]
	v_mfma_f32_16x16x32_bf16 v[32:35], v[228:231], v[158:161], v[32:35]
	v_mfma_f32_16x16x32_bf16 v[20:23], v[218:221], v[166:169], v[20:23]
	v_mfma_f32_16x16x32_bf16 v[16:19], v[228:231], v[166:169], v[16:19]
	v_mfma_f32_16x16x32_bf16 v[4:7], v[218:221], v[198:201], v[4:7]
	v_mfma_f32_16x16x32_bf16 v[0:3], v[228:231], v[198:201], v[0:3]
	s_barrier
	s_add_u32 s42, s42, 0x100
	s_addc_u32 s43, s43, 0
	s_add_u32 s33, s33, 0x100
	s_addc_u32 s37, s37, 0
	s_cmp_ge_u32 s56, s34
	s_mov_b32 s27, s56
.LBB0_196:
	s_add_i32 s56, s27, 2
	s_add_u32 s44, s42, 0x80
	s_addc_u32 s45, s43, 0
	s_add_i32 s57, 0, 0x10000
	ds_read_b128 v[128:131], v207
	ds_read_b128 v[132:135], v207 offset:1024
	ds_read_b128 v[136:139], v207 offset:2048
	ds_read_b128 v[140:143], v207 offset:3072
	s_cmp_eq_u32 s82, s27
	s_cselect_b32 s45, s77, s45
	s_cselect_b32 s44, s76, s44
	s_cselect_b32 s79, s1, s37
	s_cselect_b32 s78, s0, s33
	v_lshl_add_u64 v[176:177], s[42:43], 0, v[190:191]
	s_add_i32 m0, s85, 0xc000
	ds_read_b128 v[146:149], v217
	ds_read_b128 v[150:153], v217 offset:1024
	ds_read_b128 v[154:157], v217 offset:2048
	ds_read_b128 v[158:161], v217 offset:3072
	ds_read_b128 v[162:165], v217 offset:4096
	ds_read_b128 v[166:169], v217 offset:5120
	ds_read_b128 v[194:197], v217 offset:6144
	ds_read_b128 v[198:201], v217 offset:7168
	global_load_lds_dwordx4 v[176:177], off
	v_lshl_add_u64 v[176:177], s[42:43], 0, v[192:193]
	s_add_i32 m0, s85, 0xe000
	s_nop 0
	global_load_lds_dwordx4 v[176:177], off
	s_waitcnt lgkmcnt(8)
	s_barrier
	s_waitcnt lgkmcnt(0)
	v_mfma_f32_16x16x32_bf16 v[124:127], v[128:131], v[146:149], v[124:127]
	v_mfma_f32_16x16x32_bf16 v[120:123], v[136:139], v[146:149], v[120:123]
	v_mfma_f32_16x16x32_bf16 v[108:111], v[128:131], v[154:157], v[108:111]
	v_mfma_f32_16x16x32_bf16 v[104:107], v[136:139], v[154:157], v[104:107]
	v_mfma_f32_16x16x32_bf16 v[92:95], v[128:131], v[162:165], v[92:95]
	v_mfma_f32_16x16x32_bf16 v[88:91], v[136:139], v[162:165], v[88:91]
	v_mfma_f32_16x16x32_bf16 v[76:79], v[128:131], v[194:197], v[76:79]
	v_mfma_f32_16x16x32_bf16 v[72:75], v[136:139], v[194:197], v[72:75]
	v_mfma_f32_16x16x32_bf16 v[124:127], v[132:135], v[150:153], v[124:127]
	v_mfma_f32_16x16x32_bf16 v[120:123], v[140:143], v[150:153], v[120:123]
	v_mfma_f32_16x16x32_bf16 v[108:111], v[132:135], v[158:161], v[108:111]
	v_mfma_f32_16x16x32_bf16 v[104:107], v[140:143], v[158:161], v[104:107]
	v_mfma_f32_16x16x32_bf16 v[92:95], v[132:135], v[166:169], v[92:95]
	v_mfma_f32_16x16x32_bf16 v[88:91], v[140:143], v[166:169], v[88:91]
	v_mfma_f32_16x16x32_bf16 v[76:79], v[132:135], v[198:201], v[76:79]
	v_mfma_f32_16x16x32_bf16 v[72:75], v[140:143], v[198:201], v[72:75]
	s_barrier
	s_add_i32 s27, 0, 0x14000
	s_add_i32 s57, s57, s84
	ds_read_b128 v[202:205], v207 offset:16384
	ds_read_b128 v[218:221], v207 offset:17408
	ds_read_b128 v[222:225], v207 offset:18432
	ds_read_b128 v[228:231], v207 offset:19456
	v_lshl_add_u64 v[176:177], s[78:79], 0, v[144:145]
	s_mov_b32 m0, s57
	v_lshl_add_u64 v[232:233], s[78:79], 0, v[188:189]
	global_load_lds_dwordx4 v[176:177], off
	s_add_i32 m0, s57, 0x2000
	s_nop 0
	global_load_lds_dwordx4 v[232:233], off
	s_barrier
	s_waitcnt lgkmcnt(0)
	v_mfma_f32_16x16x32_bf16 v[116:119], v[202:205], v[146:149], v[116:119]
	v_mfma_f32_16x16x32_bf16 v[112:115], v[222:225], v[146:149], v[112:115]
	v_mfma_f32_16x16x32_bf16 v[100:103], v[202:205], v[154:157], v[100:103]
	v_mfma_f32_16x16x32_bf16 v[96:99], v[222:225], v[154:157], v[96:99]
	v_mfma_f32_16x16x32_bf16 v[84:87], v[202:205], v[162:165], v[84:87]
	v_mfma_f32_16x16x32_bf16 v[80:83], v[222:225], v[162:165], v[80:83]
	v_mfma_f32_16x16x32_bf16 v[68:71], v[202:205], v[194:197], v[68:71]
	v_mfma_f32_16x16x32_bf16 v[64:67], v[222:225], v[194:197], v[64:67]
	v_mfma_f32_16x16x32_bf16 v[116:119], v[218:221], v[150:153], v[116:119]
	v_mfma_f32_16x16x32_bf16 v[112:115], v[228:231], v[150:153], v[112:115]
	v_mfma_f32_16x16x32_bf16 v[100:103], v[218:221], v[158:161], v[100:103]
	v_mfma_f32_16x16x32_bf16 v[96:99], v[228:231], v[158:161], v[96:99]
	v_mfma_f32_16x16x32_bf16 v[84:87], v[218:221], v[166:169], v[84:87]
	v_mfma_f32_16x16x32_bf16 v[80:83], v[228:231], v[166:169], v[80:83]
	v_mfma_f32_16x16x32_bf16 v[68:71], v[218:221], v[198:201], v[68:71]
	v_mfma_f32_16x16x32_bf16 v[64:67], v[228:231], v[198:201], v[64:67]
	s_barrier
	s_mov_b32 m0, s85
	v_lshl_add_u64 v[234:235], s[44:45], 0, v[144:145]
	ds_read_b128 v[146:149], v217 offset:16384
	ds_read_b128 v[150:153], v217 offset:17408
	ds_read_b128 v[154:157], v217 offset:18432
	ds_read_b128 v[158:161], v217 offset:19456
	ds_read_b128 v[162:165], v217 offset:20480
	ds_read_b128 v[166:169], v217 offset:21504
	ds_read_b128 v[194:197], v217 offset:22528
	ds_read_b128 v[198:201], v217 offset:23552
	global_load_lds_dwordx4 v[234:235], off
	v_lshl_add_u64 v[236:237], s[44:45], 0, v[188:189]
	s_mov_b32 m0, s86
	s_nop 0
	global_load_lds_dwordx4 v[236:237], off
	s_barrier
	s_waitcnt lgkmcnt(0)
	v_mfma_f32_16x16x32_bf16 v[60:63], v[128:131], v[146:149], v[60:63]
	v_mfma_f32_16x16x32_bf16 v[56:59], v[136:139], v[146:149], v[56:59]
	v_mfma_f32_16x16x32_bf16 v[44:47], v[128:131], v[154:157], v[44:47]
	v_mfma_f32_16x16x32_bf16 v[40:43], v[136:139], v[154:157], v[40:43]
	v_mfma_f32_16x16x32_bf16 v[28:31], v[128:131], v[162:165], v[28:31]
	v_mfma_f32_16x16x32_bf16 v[24:27], v[136:139], v[162:165], v[24:27]
	v_mfma_f32_16x16x32_bf16 v[12:15], v[128:131], v[194:197], v[12:15]
	v_mfma_f32_16x16x32_bf16 v[8:11], v[136:139], v[194:197], v[8:11]
	v_mfma_f32_16x16x32_bf16 v[60:63], v[132:135], v[150:153], v[60:63]
	v_mfma_f32_16x16x32_bf16 v[56:59], v[140:143], v[150:153], v[56:59]
	v_mfma_f32_16x16x32_bf16 v[44:47], v[132:135], v[158:161], v[44:47]
	v_mfma_f32_16x16x32_bf16 v[40:43], v[140:143], v[158:161], v[40:43]
	v_mfma_f32_16x16x32_bf16 v[28:31], v[132:135], v[166:169], v[28:31]
	v_mfma_f32_16x16x32_bf16 v[24:27], v[140:143], v[166:169], v[24:27]
	v_mfma_f32_16x16x32_bf16 v[12:15], v[132:135], v[198:201], v[12:15]
	v_mfma_f32_16x16x32_bf16 v[8:11], v[140:143], v[198:201], v[8:11]
	s_barrier
	s_add_u32 s58, s78, s98
	s_addc_u32 s59, s79, 0
	s_add_i32 s27, s27, s84
	v_lshl_add_u64 v[238:239], s[58:59], 0, v[144:145]
	s_mov_b32 m0, s27
	v_lshl_add_u64 v[240:241], s[58:59], 0, v[188:189]
	global_load_lds_dwordx4 v[238:239], off
	s_add_i32 m0, s27, 0x2000
	s_nop 0
	global_load_lds_dwordx4 v[240:241], off
	s_waitcnt vmcnt(6)
	s_barrier
	v_mfma_f32_16x16x32_bf16 v[52:55], v[202:205], v[146:149], v[52:55]
	v_mfma_f32_16x16x32_bf16 v[48:51], v[222:225], v[146:149], v[48:51]
	v_mfma_f32_16x16x32_bf16 v[36:39], v[202:205], v[154:157], v[36:39]
	v_mfma_f32_16x16x32_bf16 v[32:35], v[222:225], v[154:157], v[32:35]
	v_mfma_f32_16x16x32_bf16 v[20:23], v[202:205], v[162:165], v[20:23]
	v_mfma_f32_16x16x32_bf16 v[16:19], v[222:225], v[162:165], v[16:19]
	v_mfma_f32_16x16x32_bf16 v[4:7], v[202:205], v[194:197], v[4:7]
	v_mfma_f32_16x16x32_bf16 v[0:3], v[222:225], v[194:197], v[0:3]
	v_mfma_f32_16x16x32_bf16 v[52:55], v[218:221], v[150:153], v[52:55]
	v_mfma_f32_16x16x32_bf16 v[48:51], v[228:231], v[150:153], v[48:51]
	v_mfma_f32_16x16x32_bf16 v[36:39], v[218:221], v[158:161], v[36:39]
	v_mfma_f32_16x16x32_bf16 v[32:35], v[228:231], v[158:161], v[32:35]
	v_mfma_f32_16x16x32_bf16 v[20:23], v[218:221], v[166:169], v[20:23]
	v_mfma_f32_16x16x32_bf16 v[16:19], v[228:231], v[166:169], v[16:19]
	v_mfma_f32_16x16x32_bf16 v[4:7], v[218:221], v[198:201], v[4:7]
	v_mfma_f32_16x16x32_bf16 v[0:3], v[228:231], v[198:201], v[0:3]
	s_barrier
	s_nop 0
	s_add_i32 s27, 0, 0x18000
	ds_read_b128 v[128:131], v207 offset:32768
	ds_read_b128 v[132:135], v207 offset:33792
	ds_read_b128 v[136:139], v207 offset:34816
	ds_read_b128 v[140:143], v207 offset:35840
	s_add_u32 s44, s44, s98
	s_addc_u32 s45, s45, 0
	s_mov_b32 m0, s87
	ds_read_b128 v[146:149], v217 offset:32768
	ds_read_b128 v[150:153], v217 offset:33792
	ds_read_b128 v[154:157], v217 offset:34816
	ds_read_b128 v[158:161], v217 offset:35840
	ds_read_b128 v[162:165], v217 offset:36864
	ds_read_b128 v[166:169], v217 offset:37888
	ds_read_b128 v[194:197], v217 offset:38912
	ds_read_b128 v[198:201], v217 offset:39936
	global_load_lds_dwordx4 v144, s[44:45]
	s_mov_b32 m0, s80
	s_nop 0
	global_load_lds_dwordx4 v188, s[44:45]
	s_waitcnt lgkmcnt(8)
	s_barrier
	s_waitcnt lgkmcnt(0)
	v_mfma_f32_16x16x32_bf16 v[124:127], v[128:131], v[146:149], v[124:127]
	v_mfma_f32_16x16x32_bf16 v[120:123], v[136:139], v[146:149], v[120:123]
	v_mfma_f32_16x16x32_bf16 v[108:111], v[128:131], v[154:157], v[108:111]
	v_mfma_f32_16x16x32_bf16 v[104:107], v[136:139], v[154:157], v[104:107]
	v_mfma_f32_16x16x32_bf16 v[92:95], v[128:131], v[162:165], v[92:95]
	v_mfma_f32_16x16x32_bf16 v[88:91], v[136:139], v[162:165], v[88:91]
	v_mfma_f32_16x16x32_bf16 v[76:79], v[128:131], v[194:197], v[76:79]
	v_mfma_f32_16x16x32_bf16 v[72:75], v[136:139], v[194:197], v[72:75]
	v_mfma_f32_16x16x32_bf16 v[124:127], v[132:135], v[150:153], v[124:127]
	v_mfma_f32_16x16x32_bf16 v[120:123], v[140:143], v[150:153], v[120:123]
	v_mfma_f32_16x16x32_bf16 v[108:111], v[132:135], v[158:161], v[108:111]
	v_mfma_f32_16x16x32_bf16 v[104:107], v[140:143], v[158:161], v[104:107]
	v_mfma_f32_16x16x32_bf16 v[92:95], v[132:135], v[166:169], v[92:95]
	v_mfma_f32_16x16x32_bf16 v[88:91], v[140:143], v[166:169], v[88:91]
	v_mfma_f32_16x16x32_bf16 v[76:79], v[132:135], v[198:201], v[76:79]
	v_mfma_f32_16x16x32_bf16 v[72:75], v[140:143], v[198:201], v[72:75]
	s_barrier
	s_add_i32 s44, 0, 0x1c000
	s_add_i32 s27, s27, s84
	v_lshl_add_u64 v[176:177], v[176:177], 0, s[18:19]
	s_mov_b32 m0, s27
	ds_read_b128 v[202:205], v207 offset:49152
	ds_read_b128 v[218:221], v207 offset:50176
	ds_read_b128 v[222:225], v207 offset:51200
	ds_read_b128 v[228:231], v207 offset:52224
	global_load_lds_dwordx4 v[176:177], off
	v_lshl_add_u64 v[176:177], v[232:233], 0, s[18:19]
	s_add_i32 m0, s27, 0x2000
	s_nop 0
	global_load_lds_dwordx4 v[176:177], off
	s_barrier
	s_waitcnt lgkmcnt(0)
	v_mfma_f32_16x16x32_bf16 v[116:119], v[202:205], v[146:149], v[116:119]
	v_mfma_f32_16x16x32_bf16 v[112:115], v[222:225], v[146:149], v[112:115]
	v_mfma_f32_16x16x32_bf16 v[100:103], v[202:205], v[154:157], v[100:103]
	v_mfma_f32_16x16x32_bf16 v[96:99], v[222:225], v[154:157], v[96:99]
	v_mfma_f32_16x16x32_bf16 v[84:87], v[202:205], v[162:165], v[84:87]
	v_mfma_f32_16x16x32_bf16 v[80:83], v[222:225], v[162:165], v[80:83]
	v_mfma_f32_16x16x32_bf16 v[68:71], v[202:205], v[194:197], v[68:71]
	v_mfma_f32_16x16x32_bf16 v[64:67], v[222:225], v[194:197], v[64:67]
	v_mfma_f32_16x16x32_bf16 v[116:119], v[218:221], v[150:153], v[116:119]
	v_mfma_f32_16x16x32_bf16 v[112:115], v[228:231], v[150:153], v[112:115]
	v_mfma_f32_16x16x32_bf16 v[100:103], v[218:221], v[158:161], v[100:103]
	v_mfma_f32_16x16x32_bf16 v[96:99], v[228:231], v[158:161], v[96:99]
	v_mfma_f32_16x16x32_bf16 v[84:87], v[218:221], v[166:169], v[84:87]
	v_mfma_f32_16x16x32_bf16 v[80:83], v[228:231], v[166:169], v[80:83]
	v_mfma_f32_16x16x32_bf16 v[68:71], v[218:221], v[198:201], v[68:71]
	v_mfma_f32_16x16x32_bf16 v[64:67], v[228:231], v[198:201], v[64:67]
	s_barrier
	s_mov_b32 m0, s30
	v_lshl_add_u64 v[176:177], v[234:235], 0, s[18:19]
	ds_read_b128 v[146:149], v217 offset:49152
	ds_read_b128 v[150:153], v217 offset:50176
	ds_read_b128 v[154:157], v217 offset:51200
	ds_read_b128 v[158:161], v217 offset:52224
	ds_read_b128 v[162:165], v217 offset:53248
	ds_read_b128 v[166:169], v217 offset:54272
	ds_read_b128 v[194:197], v217 offset:55296
	ds_read_b128 v[198:201], v217 offset:56320
	global_load_lds_dwordx4 v[176:177], off
	v_lshl_add_u64 v[176:177], v[236:237], 0, s[18:19]
	s_mov_b32 m0, s31
	s_nop 0
	global_load_lds_dwordx4 v[176:177], off
	s_barrier
	s_waitcnt lgkmcnt(0)
	v_mfma_f32_16x16x32_bf16 v[60:63], v[128:131], v[146:149], v[60:63]
	v_mfma_f32_16x16x32_bf16 v[56:59], v[136:139], v[146:149], v[56:59]
	v_mfma_f32_16x16x32_bf16 v[44:47], v[128:131], v[154:157], v[44:47]
	v_mfma_f32_16x16x32_bf16 v[40:43], v[136:139], v[154:157], v[40:43]
	v_mfma_f32_16x16x32_bf16 v[28:31], v[128:131], v[162:165], v[28:31]
	v_mfma_f32_16x16x32_bf16 v[24:27], v[136:139], v[162:165], v[24:27]
	v_mfma_f32_16x16x32_bf16 v[12:15], v[128:131], v[194:197], v[12:15]
	v_mfma_f32_16x16x32_bf16 v[8:11], v[136:139], v[194:197], v[8:11]
	v_mfma_f32_16x16x32_bf16 v[60:63], v[132:135], v[150:153], v[60:63]
	v_mfma_f32_16x16x32_bf16 v[56:59], v[140:143], v[150:153], v[56:59]
	v_mfma_f32_16x16x32_bf16 v[44:47], v[132:135], v[158:161], v[44:47]
	v_mfma_f32_16x16x32_bf16 v[40:43], v[140:143], v[158:161], v[40:43]
	v_mfma_f32_16x16x32_bf16 v[28:31], v[132:135], v[166:169], v[28:31]
	v_mfma_f32_16x16x32_bf16 v[24:27], v[140:143], v[166:169], v[24:27]
	v_mfma_f32_16x16x32_bf16 v[12:15], v[132:135], v[198:201], v[12:15]
	v_mfma_f32_16x16x32_bf16 v[8:11], v[140:143], v[198:201], v[8:11]
	s_barrier
	s_nop 0
	s_add_i32 s27, s44, s84
	v_lshl_add_u64 v[128:129], v[238:239], 0, s[18:19]
	s_mov_b32 m0, s27
	s_nop 0
	global_load_lds_dwordx4 v[128:129], off
	v_lshl_add_u64 v[128:129], v[240:241], 0, s[18:19]
	s_add_i32 m0, s27, 0x2000
	s_nop 0
	global_load_lds_dwordx4 v[128:129], off
	s_waitcnt vmcnt(6)
	s_barrier
	v_mfma_f32_16x16x32_bf16 v[52:55], v[202:205], v[146:149], v[52:55]
	v_mfma_f32_16x16x32_bf16 v[48:51], v[222:225], v[146:149], v[48:51]
	v_mfma_f32_16x16x32_bf16 v[36:39], v[202:205], v[154:157], v[36:39]
	v_mfma_f32_16x16x32_bf16 v[32:35], v[222:225], v[154:157], v[32:35]
	v_mfma_f32_16x16x32_bf16 v[20:23], v[202:205], v[162:165], v[20:23]
	v_mfma_f32_16x16x32_bf16 v[16:19], v[222:225], v[162:165], v[16:19]
	v_mfma_f32_16x16x32_bf16 v[4:7], v[202:205], v[194:197], v[4:7]
	v_mfma_f32_16x16x32_bf16 v[0:3], v[222:225], v[194:197], v[0:3]
	v_mfma_f32_16x16x32_bf16 v[52:55], v[218:221], v[150:153], v[52:55]
	v_mfma_f32_16x16x32_bf16 v[48:51], v[228:231], v[150:153], v[48:51]
	v_mfma_f32_16x16x32_bf16 v[36:39], v[218:221], v[158:161], v[36:39]
	v_mfma_f32_16x16x32_bf16 v[32:35], v[228:231], v[158:161], v[32:35]
	v_mfma_f32_16x16x32_bf16 v[20:23], v[218:221], v[166:169], v[20:23]
	v_mfma_f32_16x16x32_bf16 v[16:19], v[228:231], v[166:169], v[16:19]
	v_mfma_f32_16x16x32_bf16 v[4:7], v[218:221], v[198:201], v[4:7]
	v_mfma_f32_16x16x32_bf16 v[0:3], v[228:231], v[198:201], v[0:3]
	s_barrier
	s_add_u32 s42, s42, 0x100
	s_addc_u32 s43, s43, 0
	s_add_u32 s33, s33, 0x100
	s_addc_u32 s37, s37, 0
	s_cmp_ge_u32 s56, s34
	s_mov_b32 s27, s56
	s_cbranch_scc0 .LBB0_196
	v_lshl_add_u32 v194, s11, 8, v206
	v_ashrrev_i32_e32 v195, 31, v194
	v_lshl_or_b32 v196, s10, 8, v216
	v_lshlrev_b64 v[128:129], 11, v[194:195]
	v_ashrrev_i32_e32 v197, 31, v196
	s_and_b64 vcc, exec, s[92:93]
	v_or_b32_e32 v198, 16, v194
	v_lshl_add_u64 v[200:201], s[54:55], 0, v[128:129]
	s_cbranch_vccz .LBB0_215
	v_lshlrev_b64 v[128:129], 12, v[194:195]
	v_lshl_add_u64 v[128:129], s[50:51], 0, v[128:129]
	v_lshlrev_b64 v[130:131], 2, v[196:197]
	v_lshl_add_u64 v[128:129], v[128:129], 0, v[130:131]
	global_load_dwordx4 v[146:149], v[128:129], off offset:16
	global_load_dwordx4 v[150:153], v[128:129], off
	global_load_dwordx4 v[154:157], v[128:129], off offset:528
	global_load_dwordx4 v[158:161], v[128:129], off offset:512
	v_ashrrev_i32_e32 v199, 31, v198
	v_lshlrev_b64 v[128:129], 12, v[198:199]
	v_lshl_add_u64 v[128:129], s[50:51], 0, v[128:129]
	v_lshl_add_u64 v[132:133], v[128:129], 0, v[130:131]
	global_load_dwordx4 v[136:139], v[132:133], off offset:16
	global_load_dwordx4 v[140:143], v[132:133], off
	global_load_dwordx4 v[128:131], v[132:133], off offset:528
	s_nop 0
	global_load_dwordx4 v[132:135], v[132:133], off offset:512
	v_lshl_add_u64 v[166:167], v[196:197], 1, v[200:201]
	s_waitcnt vmcnt(0)
	v_pk_add_f32 v[164:165], v[120:121], v[146:147]
	v_pk_add_f32 v[152:153], v[126:127], v[152:153]
	v_pk_add_f32 v[150:151], v[124:125], v[150:151]
	v_pk_add_f32 v[162:163], v[122:123], v[148:149]
	v_cvt_pk_bf16_f32 v146, v150, v151
	v_cvt_pk_bf16_f32 v147, v152, v153
	v_cvt_pk_bf16_f32 v148, v164, v165
	v_pk_add_f32 v[156:157], v[114:115], v[156:157]
	v_cvt_pk_bf16_f32 v149, v162, v163
	global_store_dwordx4 v[166:167], v[146:149], off
	v_pk_add_f32 v[154:155], v[112:113], v[154:155]
	s_nop 0
	v_mul_f32_e32 v146, v151, v151
	v_mul_f32_e32 v147, v153, v153
	v_fmac_f32_e32 v146, v150, v150
	v_fmac_f32_e32 v147, v152, v152
	v_add_f32_e32 v146, v146, v147
	v_mul_f32_e32 v147, v165, v165
	v_mul_f32_e32 v148, v163, v163
	v_fmac_f32_e32 v147, v164, v164
	v_fmac_f32_e32 v148, v162, v162
	v_add_f32_e32 v147, v147, v148
	v_add_f32_e32 v162, v146, v147
	v_pk_add_f32 v[150:151], v[118:119], v[160:161]
	v_pk_add_f32 v[152:153], v[116:117], v[158:159]
	s_nop 0
	v_cvt_pk_bf16_f32 v146, v152, v153
	v_cvt_pk_bf16_f32 v147, v150, v151
	v_cvt_pk_bf16_f32 v148, v154, v155
	v_cvt_pk_bf16_f32 v149, v156, v157
	global_store_dwordx4 v[166:167], v[146:149], off offset:256
	s_nop 1
	v_mul_f32_e32 v146, v153, v153
	v_mul_f32_e32 v147, v151, v151
	v_fmac_f32_e32 v146, v152, v152
	v_fmac_f32_e32 v147, v150, v150
	v_add_f32_e32 v146, v146, v147
	v_mul_f32_e32 v147, v155, v155
	v_mul_f32_e32 v148, v157, v157
	v_fmac_f32_e32 v147, v154, v154
	v_fmac_f32_e32 v148, v156, v156
	v_add_f32_e32 v147, v147, v148
	v_and_b32_e32 v148, 64, v214
	v_add_f32_e32 v146, v146, v147
	v_xor_b32_e32 v147, 16, v214
	v_add_u32_e32 v148, 64, v148
	v_cmp_lt_i32_e32 vcc, v147, v148
	v_add_f32_e32 v146, v162, v146
	s_nop 0
	v_cndmask_b32_e32 v147, v214, v147, vcc
	v_lshlrev_b32_e32 v218, 2, v147
	ds_bpermute_b32 v147, v218, v146
	s_waitcnt lgkmcnt(0)
	v_add_f32_e32 v146, v146, v147
	v_xor_b32_e32 v147, 32, v214
	v_cmp_lt_i32_e32 vcc, v147, v148
	s_nop 1
	v_cndmask_b32_e32 v147, v214, v147, vcc
	v_lshlrev_b32_e32 v219, 2, v147
	ds_bpermute_b32 v147, v219, v146
	s_and_saveexec_b64 s[42:43], s[38:39]
	s_cbranch_execz .LBB0_200
	s_waitcnt lgkmcnt(0)
	v_add_f32_e32 v146, v146, v147
	v_fma_f32 v146, v146, s91, 0.5
	v_trunc_f32_e32 v146, v146
	v_mul_f32_e32 v147, 0x2f800000, v146
	v_floor_f32_e32 v147, v147
	v_fmac_f32_e32 v146, 0xcf800000, v147
	v_cvt_u32_f32_e32 v146, v146
	v_cvt_u32_f32_e32 v147, v147
	v_lshl_add_u64 v[148:149], v[194:195], 3, s[52:53]
	global_atomic_add_x2 v[148:149], v[146:147], off

.LBB0_325:
	s_nop 0
	s_ashr_i32 s93, s92, 31
	s_lshl_b64 s[30:31], s[92:93], 19
	s_add_u32 s94, s54, s30
	v_cmp_lt_i64_e32 vcc, s[50:51], v[186:187]
	s_addc_u32 s95, s55, s31
	s_and_b64 s[30:31], vcc, exec
	s_cselect_b32 s1, s95, s53
	s_cselect_b32 s11, s94, s52
	s_ashr_i32 s9, s8, 31
	s_lshl_b64 s[30:31], s[8:9], 19
	s_add_u32 s28, s80, s30
	s_addc_u32 s29, s78, s31
	s_and_b64 s[30:31], vcc, exec
	s_cselect_b32 s25, s29, s73
	s_cselect_b32 s30, s28, s72
	s_add_u32 s52, s52, 0x40080
	s_addc_u32 s53, s53, 0
	s_add_u32 s31, s72, 0x100
	s_addc_u32 s33, s73, 0
	s_mov_b32 s34, -2
	s_add_u32 s27, s52, 0xfffc0080
	s_addc_u32 s35, s53, -1
	s_add_i32 s36, 0, 0x10000
	ds_read_b128 v[128:131], v216
	ds_read_b128 v[132:135], v216 offset:1024
	ds_read_b128 v[136:139], v216 offset:2048
	ds_read_b128 v[140:143], v216 offset:3072
	s_cmp_eq_u32 s34, 12
	s_cselect_b32 s75, s1, s35
	s_cselect_b32 s74, s11, s27
	s_cselect_b32 s73, s25, s33
	s_cselect_b32 s72, s30, s31
	s_add_i32 m0, s83, 0xc000
	ds_read_b128 v[156:159], v217
	ds_read_b128 v[160:163], v217 offset:1024
	ds_read_b128 v[164:167], v217 offset:2048
	ds_read_b128 v[188:191], v217 offset:3072
	ds_read_b128 v[192:195], v217 offset:4096
	ds_read_b128 v[196:199], v217 offset:5120
	ds_read_b128 v[200:203], v217 offset:6144
	ds_read_b128 v[204:207], v217 offset:7168
	global_load_lds_dwordx4 v152, s[52:53]
	s_add_i32 m0, s83, 0xe000
	s_nop 0
	global_load_lds_dwordx4 v154, s[52:53]
	s_waitcnt lgkmcnt(8)
	s_barrier
	s_waitcnt lgkmcnt(0)
	v_mfma_f32_16x16x32_bf16 v[124:127], v[128:131], v[156:159], 0
	v_mfma_f32_16x16x32_bf16 v[120:123], v[136:139], v[156:159], 0
	v_mfma_f32_16x16x32_bf16 v[108:111], v[128:131], v[164:167], 0
	v_mfma_f32_16x16x32_bf16 v[104:107], v[136:139], v[164:167], 0
	v_mfma_f32_16x16x32_bf16 v[92:95], v[128:131], v[192:195], 0
	v_mfma_f32_16x16x32_bf16 v[88:91], v[136:139], v[192:195], 0
	v_mfma_f32_16x16x32_bf16 v[76:79], v[128:131], v[200:203], 0
	v_mfma_f32_16x16x32_bf16 v[72:75], v[136:139], v[200:203], 0
	v_mfma_f32_16x16x32_bf16 v[124:127], v[132:135], v[160:163], v[124:127]
	v_mfma_f32_16x16x32_bf16 v[120:123], v[140:143], v[160:163], v[120:123]
	v_mfma_f32_16x16x32_bf16 v[108:111], v[132:135], v[188:191], v[108:111]
	v_mfma_f32_16x16x32_bf16 v[104:107], v[140:143], v[188:191], v[104:107]
	v_mfma_f32_16x16x32_bf16 v[92:95], v[132:135], v[196:199], v[92:95]
	v_mfma_f32_16x16x32_bf16 v[88:91], v[140:143], v[196:199], v[88:91]
	v_mfma_f32_16x16x32_bf16 v[76:79], v[132:135], v[204:207], v[76:79]
	v_mfma_f32_16x16x32_bf16 v[72:75], v[140:143], v[204:207], v[72:75]
	s_barrier
	s_add_i32 s27, 0, 0x14000
	s_add_i32 s35, s36, s81
	s_mov_b32 m0, s35
	ds_read_b128 v[220:223], v216 offset:16384
	ds_read_b128 v[228:231], v216 offset:17408
	ds_read_b128 v[232:235], v216 offset:18432
	ds_read_b128 v[236:239], v216 offset:19456
	global_load_lds_dwordx4 v148, s[72:73]
	s_add_i32 m0, s35, 0x2000
	s_nop 0
	global_load_lds_dwordx4 v146, s[72:73]
	s_barrier
	s_waitcnt lgkmcnt(0)
	v_mfma_f32_16x16x32_bf16 v[116:119], v[220:223], v[156:159], 0
	v_mfma_f32_16x16x32_bf16 v[112:115], v[232:235], v[156:159], 0
	v_mfma_f32_16x16x32_bf16 v[100:103], v[220:223], v[164:167], 0
	v_mfma_f32_16x16x32_bf16 v[96:99], v[232:235], v[164:167], 0
	v_mfma_f32_16x16x32_bf16 v[84:87], v[220:223], v[192:195], 0
	v_mfma_f32_16x16x32_bf16 v[80:83], v[232:235], v[192:195], 0
	v_mfma_f32_16x16x32_bf16 v[68:71], v[220:223], v[200:203], 0
	v_mfma_f32_16x16x32_bf16 v[64:67], v[232:235], v[200:203], 0
	v_mfma_f32_16x16x32_bf16 v[116:119], v[228:231], v[160:163], v[116:119]
	v_mfma_f32_16x16x32_bf16 v[112:115], v[236:239], v[160:163], v[112:115]
	v_mfma_f32_16x16x32_bf16 v[100:103], v[228:231], v[188:191], v[100:103]
	v_mfma_f32_16x16x32_bf16 v[96:99], v[236:239], v[188:191], v[96:99]
	v_mfma_f32_16x16x32_bf16 v[84:87], v[228:231], v[196:199], v[84:87]
	v_mfma_f32_16x16x32_bf16 v[80:83], v[236:239], v[196:199], v[80:83]
	v_mfma_f32_16x16x32_bf16 v[68:71], v[228:231], v[204:207], v[68:71]
	v_mfma_f32_16x16x32_bf16 v[64:67], v[236:239], v[204:207], v[64:67]
	s_barrier
	s_mov_b32 m0, s83
	ds_read_b128 v[156:159], v217 offset:16384
	ds_read_b128 v[160:163], v217 offset:17408
	ds_read_b128 v[164:167], v217 offset:18432
	ds_read_b128 v[188:191], v217 offset:19456
	ds_read_b128 v[192:195], v217 offset:20480
	ds_read_b128 v[196:199], v217 offset:21504
	ds_read_b128 v[200:203], v217 offset:22528
	ds_read_b128 v[204:207], v217 offset:23552
	global_load_lds_dwordx4 v148, s[74:75]
	s_mov_b32 m0, s84
	s_nop 0
	global_load_lds_dwordx4 v146, s[74:75]
	s_barrier
	s_waitcnt lgkmcnt(0)
	v_mfma_f32_16x16x32_bf16 v[60:63], v[128:131], v[156:159], 0
	v_mfma_f32_16x16x32_bf16 v[56:59], v[136:139], v[156:159], 0
	v_mfma_f32_16x16x32_bf16 v[44:47], v[128:131], v[164:167], 0
	v_mfma_f32_16x16x32_bf16 v[40:43], v[136:139], v[164:167], 0
	v_mfma_f32_16x16x32_bf16 v[28:31], v[128:131], v[192:195], 0
	v_mfma_f32_16x16x32_bf16 v[24:27], v[136:139], v[192:195], 0
	v_mfma_f32_16x16x32_bf16 v[12:15], v[128:131], v[200:203], 0
	v_mfma_f32_16x16x32_bf16 v[8:11], v[136:139], v[200:203], 0
	v_mfma_f32_16x16x32_bf16 v[60:63], v[132:135], v[160:163], v[60:63]
	v_mfma_f32_16x16x32_bf16 v[56:59], v[140:143], v[160:163], v[56:59]
	v_mfma_f32_16x16x32_bf16 v[44:47], v[132:135], v[188:191], v[44:47]
	v_mfma_f32_16x16x32_bf16 v[40:43], v[140:143], v[188:191], v[40:43]
	v_mfma_f32_16x16x32_bf16 v[28:31], v[132:135], v[196:199], v[28:31]
	v_mfma_f32_16x16x32_bf16 v[24:27], v[140:143], v[196:199], v[24:27]
	v_mfma_f32_16x16x32_bf16 v[12:15], v[132:135], v[204:207], v[12:15]
	v_mfma_f32_16x16x32_bf16 v[8:11], v[140:143], v[204:207], v[8:11]
	s_barrier
	s_add_u32 s36, s72, 0x40000
	s_addc_u32 s37, s73, 0
	s_add_i32 s27, s27, s81
	s_mov_b32 m0, s27
	s_nop 0
	global_load_lds_dwordx4 v148, s[36:37]
	s_add_i32 m0, s27, 0x2000
	s_nop 0
	global_load_lds_dwordx4 v146, s[36:37]
	s_waitcnt vmcnt(6)
	s_barrier
	v_mfma_f32_16x16x32_bf16 v[52:55], v[220:223], v[156:159], 0
	v_mfma_f32_16x16x32_bf16 v[48:51], v[232:235], v[156:159], 0
	v_mfma_f32_16x16x32_bf16 v[36:39], v[220:223], v[164:167], 0
	v_mfma_f32_16x16x32_bf16 v[32:35], v[232:235], v[164:167], 0
	v_mfma_f32_16x16x32_bf16 v[20:23], v[220:223], v[192:195], 0
	v_mfma_f32_16x16x32_bf16 v[16:19], v[232:235], v[192:195], 0
	v_mfma_f32_16x16x32_bf16 v[4:7], v[220:223], v[200:203], 0
	v_mfma_f32_16x16x32_bf16 v[0:3], v[232:235], v[200:203], 0
	v_mfma_f32_16x16x32_bf16 v[52:55], v[228:231], v[160:163], v[52:55]
	v_mfma_f32_16x16x32_bf16 v[48:51], v[236:239], v[160:163], v[48:51]
	v_mfma_f32_16x16x32_bf16 v[36:39], v[228:231], v[188:191], v[36:39]
	v_mfma_f32_16x16x32_bf16 v[32:35], v[236:239], v[188:191], v[32:35]
	v_mfma_f32_16x16x32_bf16 v[20:23], v[228:231], v[196:199], v[20:23]
	v_mfma_f32_16x16x32_bf16 v[16:19], v[236:239], v[196:199], v[16:19]
	v_mfma_f32_16x16x32_bf16 v[4:7], v[228:231], v[204:207], v[4:7]
	v_mfma_f32_16x16x32_bf16 v[0:3], v[236:239], v[204:207], v[0:3]
	s_barrier
	s_add_i32 s27, 0, 0x18000
	ds_read_b128 v[128:131], v216 offset:32768
	ds_read_b128 v[132:135], v216 offset:33792
	ds_read_b128 v[136:139], v216 offset:34816
	ds_read_b128 v[140:143], v216 offset:35840
	s_add_u32 s36, s74, 0x40000
	s_addc_u32 s37, s75, 0
	s_mov_b32 m0, s85
	ds_read_b128 v[156:159], v217 offset:32768
	ds_read_b128 v[160:163], v217 offset:33792
	ds_read_b128 v[164:167], v217 offset:34816
	ds_read_b128 v[188:191], v217 offset:35840
	ds_read_b128 v[192:195], v217 offset:36864
	ds_read_b128 v[196:199], v217 offset:37888
	ds_read_b128 v[200:203], v217 offset:38912
	ds_read_b128 v[204:207], v217 offset:39936
	global_load_lds_dwordx4 v148, s[36:37]
	s_mov_b32 m0, s86
	s_nop 0
	global_load_lds_dwordx4 v146, s[36:37]
	s_waitcnt lgkmcnt(8)
	s_barrier
	s_waitcnt lgkmcnt(0)
	v_mfma_f32_16x16x32_bf16 v[124:127], v[128:131], v[156:159], v[124:127]
	v_mfma_f32_16x16x32_bf16 v[120:123], v[136:139], v[156:159], v[120:123]
	v_mfma_f32_16x16x32_bf16 v[108:111], v[128:131], v[164:167], v[108:111]
	v_mfma_f32_16x16x32_bf16 v[104:107], v[136:139], v[164:167], v[104:107]
	v_mfma_f32_16x16x32_bf16 v[92:95], v[128:131], v[192:195], v[92:95]
	v_mfma_f32_16x16x32_bf16 v[88:91], v[136:139], v[192:195], v[88:91]
	v_mfma_f32_16x16x32_bf16 v[76:79], v[128:131], v[200:203], v[76:79]
	v_mfma_f32_16x16x32_bf16 v[72:75], v[136:139], v[200:203], v[72:75]
	v_mfma_f32_16x16x32_bf16 v[124:127], v[132:135], v[160:163], v[124:127]
	v_mfma_f32_16x16x32_bf16 v[120:123], v[140:143], v[160:163], v[120:123]
	v_mfma_f32_16x16x32_bf16 v[108:111], v[132:135], v[188:191], v[108:111]
	v_mfma_f32_16x16x32_bf16 v[104:107], v[140:143], v[188:191], v[104:107]
	v_mfma_f32_16x16x32_bf16 v[92:95], v[132:135], v[196:199], v[92:95]
	v_mfma_f32_16x16x32_bf16 v[88:91], v[140:143], v[196:199], v[88:91]
	v_mfma_f32_16x16x32_bf16 v[76:79], v[132:135], v[204:207], v[76:79]
	v_mfma_f32_16x16x32_bf16 v[72:75], v[140:143], v[204:207], v[72:75]
	s_barrier
	s_add_i32 s35, 0, 0x1c000
	s_add_i32 s27, s27, s81
	s_add_u32 s36, s72, s18
	s_addc_u32 s37, s73, s19
	s_mov_b32 m0, s27
	ds_read_b128 v[220:223], v216 offset:49152
	ds_read_b128 v[228:231], v216 offset:50176
	ds_read_b128 v[232:235], v216 offset:51200
	ds_read_b128 v[236:239], v216 offset:52224
	global_load_lds_dwordx4 v148, s[36:37]
	s_add_u32 s36, s72, s18
	s_addc_u32 s37, s73, s19
	s_add_i32 m0, s27, 0x2000
	s_nop 0
	global_load_lds_dwordx4 v146, s[36:37]
	s_barrier
	s_waitcnt lgkmcnt(0)
	v_mfma_f32_16x16x32_bf16 v[116:119], v[220:223], v[156:159], v[116:119]
	v_mfma_f32_16x16x32_bf16 v[112:115], v[232:235], v[156:159], v[112:115]
	v_mfma_f32_16x16x32_bf16 v[100:103], v[220:223], v[164:167], v[100:103]
	v_mfma_f32_16x16x32_bf16 v[96:99], v[232:235], v[164:167], v[96:99]
	v_mfma_f32_16x16x32_bf16 v[84:87], v[220:223], v[192:195], v[84:87]
	v_mfma_f32_16x16x32_bf16 v[80:83], v[232:235], v[192:195], v[80:83]
	v_mfma_f32_16x16x32_bf16 v[68:71], v[220:223], v[200:203], v[68:71]
	v_mfma_f32_16x16x32_bf16 v[64:67], v[232:235], v[200:203], v[64:67]
	v_mfma_f32_16x16x32_bf16 v[116:119], v[228:231], v[160:163], v[116:119]
	v_mfma_f32_16x16x32_bf16 v[112:115], v[236:239], v[160:163], v[112:115]
	v_mfma_f32_16x16x32_bf16 v[100:103], v[228:231], v[188:191], v[100:103]
	v_mfma_f32_16x16x32_bf16 v[96:99], v[236:239], v[188:191], v[96:99]
	v_mfma_f32_16x16x32_bf16 v[84:87], v[228:231], v[196:199], v[84:87]
	v_mfma_f32_16x16x32_bf16 v[80:83], v[236:239], v[196:199], v[80:83]
	v_mfma_f32_16x16x32_bf16 v[68:71], v[228:231], v[204:207], v[68:71]
	v_mfma_f32_16x16x32_bf16 v[64:67], v[236:239], v[204:207], v[64:67]
	s_barrier
	s_mov_b32 m0, s87
	s_add_u32 s36, s74, s18
	s_addc_u32 s37, s75, s19
	ds_read_b128 v[156:159], v217 offset:49152
	ds_read_b128 v[160:163], v217 offset:50176
	ds_read_b128 v[164:167], v217 offset:51200
	ds_read_b128 v[188:191], v217 offset:52224
	ds_read_b128 v[192:195], v217 offset:53248
	ds_read_b128 v[196:199], v217 offset:54272
	ds_read_b128 v[200:203], v217 offset:55296
	ds_read_b128 v[204:207], v217 offset:56320
	global_load_lds_dwordx4 v148, s[36:37]
	s_add_u32 s36, s74, s18
	s_addc_u32 s37, s75, s19
	s_mov_b32 m0, s79
	s_nop 0
	global_load_lds_dwordx4 v146, s[36:37]
	s_barrier
	s_waitcnt lgkmcnt(0)
	v_mfma_f32_16x16x32_bf16 v[60:63], v[128:131], v[156:159], v[60:63]
	v_mfma_f32_16x16x32_bf16 v[56:59], v[136:139], v[156:159], v[56:59]
	v_mfma_f32_16x16x32_bf16 v[44:47], v[128:131], v[164:167], v[44:47]
	v_mfma_f32_16x16x32_bf16 v[40:43], v[136:139], v[164:167], v[40:43]
	v_mfma_f32_16x16x32_bf16 v[28:31], v[128:131], v[192:195], v[28:31]
	v_mfma_f32_16x16x32_bf16 v[24:27], v[136:139], v[192:195], v[24:27]
	v_mfma_f32_16x16x32_bf16 v[12:15], v[128:131], v[200:203], v[12:15]
	v_mfma_f32_16x16x32_bf16 v[8:11], v[136:139], v[200:203], v[8:11]
	v_mfma_f32_16x16x32_bf16 v[60:63], v[132:135], v[160:163], v[60:63]
	v_mfma_f32_16x16x32_bf16 v[56:59], v[140:143], v[160:163], v[56:59]
	v_mfma_f32_16x16x32_bf16 v[44:47], v[132:135], v[188:191], v[44:47]
	v_mfma_f32_16x16x32_bf16 v[40:43], v[140:143], v[188:191], v[40:43]
	v_mfma_f32_16x16x32_bf16 v[28:31], v[132:135], v[196:199], v[28:31]
	v_mfma_f32_16x16x32_bf16 v[24:27], v[140:143], v[196:199], v[24:27]
	v_mfma_f32_16x16x32_bf16 v[12:15], v[132:135], v[204:207], v[12:15]
	v_mfma_f32_16x16x32_bf16 v[8:11], v[140:143], v[204:207], v[8:11]
	s_barrier
	s_add_u32 s36, s72, 0x40080
	s_addc_u32 s37, s73, 0
	s_add_i32 s27, s35, s81
	s_mov_b32 m0, s27
	s_nop 0
	global_load_lds_dwordx4 v148, s[36:37]
	s_add_i32 m0, s27, 0x2000
	s_nop 0
	global_load_lds_dwordx4 v146, s[36:37]
	s_waitcnt vmcnt(6)
	s_barrier
	v_mfma_f32_16x16x32_bf16 v[52:55], v[220:223], v[156:159], v[52:55]
	v_mfma_f32_16x16x32_bf16 v[48:51], v[232:235], v[156:159], v[48:51]
	v_mfma_f32_16x16x32_bf16 v[36:39], v[220:223], v[164:167], v[36:39]
	v_mfma_f32_16x16x32_bf16 v[32:35], v[232:235], v[164:167], v[32:35]
	v_mfma_f32_16x16x32_bf16 v[20:23], v[220:223], v[192:195], v[20:23]
	v_mfma_f32_16x16x32_bf16 v[16:19], v[232:235], v[192:195], v[16:19]
	v_mfma_f32_16x16x32_bf16 v[4:7], v[220:223], v[200:203], v[4:7]
	v_mfma_f32_16x16x32_bf16 v[0:3], v[232:235], v[200:203], v[0:3]
	v_mfma_f32_16x16x32_bf16 v[52:55], v[228:231], v[160:163], v[52:55]
	v_mfma_f32_16x16x32_bf16 v[48:51], v[236:239], v[160:163], v[48:51]
	v_mfma_f32_16x16x32_bf16 v[36:39], v[228:231], v[188:191], v[36:39]
	v_mfma_f32_16x16x32_bf16 v[32:35], v[236:239], v[188:191], v[32:35]
	v_mfma_f32_16x16x32_bf16 v[20:23], v[228:231], v[196:199], v[20:23]
	v_mfma_f32_16x16x32_bf16 v[16:19], v[236:239], v[196:199], v[16:19]
	v_mfma_f32_16x16x32_bf16 v[4:7], v[228:231], v[204:207], v[4:7]
	v_mfma_f32_16x16x32_bf16 v[0:3], v[236:239], v[204:207], v[0:3]
	s_barrier
	s_add_i32 s34, s34, 2
	s_add_u32 s52, s52, 0x100
	s_addc_u32 s53, s53, 0
	s_add_u32 s31, s31, 0x100
	s_addc_u32 s33, s33, 0
	s_cmp_gt_u32 s34, 13
.LBB0_326:
	s_nop 0
	s_add_u32 s27, s52, 0xfffc0080
	s_addc_u32 s35, s53, -1
	s_add_i32 s36, 0, 0x10000
	ds_read_b128 v[128:131], v216
	ds_read_b128 v[132:135], v216 offset:1024
	ds_read_b128 v[136:139], v216 offset:2048
	ds_read_b128 v[140:143], v216 offset:3072
	s_cmp_eq_u32 s34, 12
	s_cselect_b32 s75, s1, s35
	s_cselect_b32 s74, s11, s27
	s_cselect_b32 s73, s25, s33
	s_cselect_b32 s72, s30, s31
	s_add_i32 m0, s83, 0xc000
	ds_read_b128 v[156:159], v217
	ds_read_b128 v[160:163], v217 offset:1024
	ds_read_b128 v[164:167], v217 offset:2048
	ds_read_b128 v[188:191], v217 offset:3072
	ds_read_b128 v[192:195], v217 offset:4096
	ds_read_b128 v[196:199], v217 offset:5120
	ds_read_b128 v[200:203], v217 offset:6144
	ds_read_b128 v[204:207], v217 offset:7168
	global_load_lds_dwordx4 v152, s[52:53]
	s_add_i32 m0, s83, 0xe000
	s_nop 0
	global_load_lds_dwordx4 v154, s[52:53]
	s_waitcnt lgkmcnt(8)
	s_barrier
	s_waitcnt lgkmcnt(0)
	v_mfma_f32_16x16x32_bf16 v[124:127], v[128:131], v[156:159], v[124:127]
	v_mfma_f32_16x16x32_bf16 v[120:123], v[136:139], v[156:159], v[120:123]
	v_mfma_f32_16x16x32_bf16 v[108:111], v[128:131], v[164:167], v[108:111]
	v_mfma_f32_16x16x32_bf16 v[104:107], v[136:139], v[164:167], v[104:107]
	v_mfma_f32_16x16x32_bf16 v[92:95], v[128:131], v[192:195], v[92:95]
	v_mfma_f32_16x16x32_bf16 v[88:91], v[136:139], v[192:195], v[88:91]
	v_mfma_f32_16x16x32_bf16 v[76:79], v[128:131], v[200:203], v[76:79]
	v_mfma_f32_16x16x32_bf16 v[72:75], v[136:139], v[200:203], v[72:75]
	v_mfma_f32_16x16x32_bf16 v[124:127], v[132:135], v[160:163], v[124:127]
	v_mfma_f32_16x16x32_bf16 v[120:123], v[140:143], v[160:163], v[120:123]
	v_mfma_f32_16x16x32_bf16 v[108:111], v[132:135], v[188:191], v[108:111]
	v_mfma_f32_16x16x32_bf16 v[104:107], v[140:143], v[188:191], v[104:107]
	v_mfma_f32_16x16x32_bf16 v[92:95], v[132:135], v[196:199], v[92:95]
	v_mfma_f32_16x16x32_bf16 v[88:91], v[140:143], v[196:199], v[88:91]
	v_mfma_f32_16x16x32_bf16 v[76:79], v[132:135], v[204:207], v[76:79]
	v_mfma_f32_16x16x32_bf16 v[72:75], v[140:143], v[204:207], v[72:75]
	s_barrier
	s_add_i32 s27, 0, 0x14000
	s_add_i32 s35, s36, s81
	s_mov_b32 m0, s35
	ds_read_b128 v[220:223], v216 offset:16384
	ds_read_b128 v[228:231], v216 offset:17408
	ds_read_b128 v[232:235], v216 offset:18432
	ds_read_b128 v[236:239], v216 offset:19456
	global_load_lds_dwordx4 v148, s[72:73]
	s_add_i32 m0, s35, 0x2000
	s_nop 0
	global_load_lds_dwordx4 v146, s[72:73]
	s_barrier
	s_waitcnt lgkmcnt(0)
	v_mfma_f32_16x16x32_bf16 v[116:119], v[220:223], v[156:159], v[116:119]
	v_mfma_f32_16x16x32_bf16 v[112:115], v[232:235], v[156:159], v[112:115]
	v_mfma_f32_16x16x32_bf16 v[100:103], v[220:223], v[164:167], v[100:103]
	v_mfma_f32_16x16x32_bf16 v[96:99], v[232:235], v[164:167], v[96:99]
	v_mfma_f32_16x16x32_bf16 v[84:87], v[220:223], v[192:195], v[84:87]
	v_mfma_f32_16x16x32_bf16 v[80:83], v[232:235], v[192:195], v[80:83]
	v_mfma_f32_16x16x32_bf16 v[68:71], v[220:223], v[200:203], v[68:71]
	v_mfma_f32_16x16x32_bf16 v[64:67], v[232:235], v[200:203], v[64:67]
	v_mfma_f32_16x16x32_bf16 v[116:119], v[228:231], v[160:163], v[116:119]
	v_mfma_f32_16x16x32_bf16 v[112:115], v[236:239], v[160:163], v[112:115]
	v_mfma_f32_16x16x32_bf16 v[100:103], v[228:231], v[188:191], v[100:103]
	v_mfma_f32_16x16x32_bf16 v[96:99], v[236:239], v[188:191], v[96:99]
	v_mfma_f32_16x16x32_bf16 v[84:87], v[228:231], v[196:199], v[84:87]
	v_mfma_f32_16x16x32_bf16 v[80:83], v[236:239], v[196:199], v[80:83]
	v_mfma_f32_16x16x32_bf16 v[68:71], v[228:231], v[204:207], v[68:71]
	v_mfma_f32_16x16x32_bf16 v[64:67], v[236:239], v[204:207], v[64:67]
	s_barrier
	s_mov_b32 m0, s83
	ds_read_b128 v[156:159], v217 offset:16384
	ds_read_b128 v[160:163], v217 offset:17408
	ds_read_b128 v[164:167], v217 offset:18432
	ds_read_b128 v[188:191], v217 offset:19456
	ds_read_b128 v[192:195], v217 offset:20480
	ds_read_b128 v[196:199], v217 offset:21504
	ds_read_b128 v[200:203], v217 offset:22528
	ds_read_b128 v[204:207], v217 offset:23552
	global_load_lds_dwordx4 v148, s[74:75]
	s_mov_b32 m0, s84
	s_nop 0
	global_load_lds_dwordx4 v146, s[74:75]
	s_barrier
	s_waitcnt lgkmcnt(0)
	v_mfma_f32_16x16x32_bf16 v[60:63], v[128:131], v[156:159], v[60:63]
	v_mfma_f32_16x16x32_bf16 v[56:59], v[136:139], v[156:159], v[56:59]
	v_mfma_f32_16x16x32_bf16 v[44:47], v[128:131], v[164:167], v[44:47]
	v_mfma_f32_16x16x32_bf16 v[40:43], v[136:139], v[164:167], v[40:43]
	v_mfma_f32_16x16x32_bf16 v[28:31], v[128:131], v[192:195], v[28:31]
	v_mfma_f32_16x16x32_bf16 v[24:27], v[136:139], v[192:195], v[24:27]
	v_mfma_f32_16x16x32_bf16 v[12:15], v[128:131], v[200:203], v[12:15]
	v_mfma_f32_16x16x32_bf16 v[8:11], v[136:139], v[200:203], v[8:11]
	v_mfma_f32_16x16x32_bf16 v[60:63], v[132:135], v[160:163], v[60:63]
	v_mfma_f32_16x16x32_bf16 v[56:59], v[140:143], v[160:163], v[56:59]
	v_mfma_f32_16x16x32_bf16 v[44:47], v[132:135], v[188:191], v[44:47]
	v_mfma_f32_16x16x32_bf16 v[40:43], v[140:143], v[188:191], v[40:43]
	v_mfma_f32_16x16x32_bf16 v[28:31], v[132:135], v[196:199], v[28:31]
	v_mfma_f32_16x16x32_bf16 v[24:27], v[140:143], v[196:199], v[24:27]
	v_mfma_f32_16x16x32_bf16 v[12:15], v[132:135], v[204:207], v[12:15]
	v_mfma_f32_16x16x32_bf16 v[8:11], v[140:143], v[204:207], v[8:11]
	s_barrier
	s_add_u32 s36, s72, 0x40000
	s_addc_u32 s37, s73, 0
	s_add_i32 s27, s27, s81
	s_mov_b32 m0, s27
	s_nop 0
	global_load_lds_dwordx4 v148, s[36:37]
	s_add_i32 m0, s27, 0x2000
	s_nop 0
	global_load_lds_dwordx4 v146, s[36:37]
	s_waitcnt vmcnt(6)
	s_barrier
	v_mfma_f32_16x16x32_bf16 v[52:55], v[220:223], v[156:159], v[52:55]
	v_mfma_f32_16x16x32_bf16 v[48:51], v[232:235], v[156:159], v[48:51]
	v_mfma_f32_16x16x32_bf16 v[36:39], v[220:223], v[164:167], v[36:39]
	v_mfma_f32_16x16x32_bf16 v[32:35], v[232:235], v[164:167], v[32:35]
	v_mfma_f32_16x16x32_bf16 v[20:23], v[220:223], v[192:195], v[20:23]
	v_mfma_f32_16x16x32_bf16 v[16:19], v[232:235], v[192:195], v[16:19]
	v_mfma_f32_16x16x32_bf16 v[4:7], v[220:223], v[200:203], v[4:7]
	v_mfma_f32_16x16x32_bf16 v[0:3], v[232:235], v[200:203], v[0:3]
	v_mfma_f32_16x16x32_bf16 v[52:55], v[228:231], v[160:163], v[52:55]
	v_mfma_f32_16x16x32_bf16 v[48:51], v[236:239], v[160:163], v[48:51]
	v_mfma_f32_16x16x32_bf16 v[36:39], v[228:231], v[188:191], v[36:39]
	v_mfma_f32_16x16x32_bf16 v[32:35], v[236:239], v[188:191], v[32:35]
	v_mfma_f32_16x16x32_bf16 v[20:23], v[228:231], v[196:199], v[20:23]
	v_mfma_f32_16x16x32_bf16 v[16:19], v[236:239], v[196:199], v[16:19]
	v_mfma_f32_16x16x32_bf16 v[4:7], v[228:231], v[204:207], v[4:7]
	v_mfma_f32_16x16x32_bf16 v[0:3], v[236:239], v[204:207], v[0:3]
	s_barrier
	s_add_i32 s27, 0, 0x18000
	ds_read_b128 v[128:131], v216 offset:32768
	ds_read_b128 v[132:135], v216 offset:33792
	ds_read_b128 v[136:139], v216 offset:34816
	ds_read_b128 v[140:143], v216 offset:35840
	s_add_u32 s36, s74, 0x40000
	s_addc_u32 s37, s75, 0
	s_mov_b32 m0, s85
	ds_read_b128 v[156:159], v217 offset:32768
	ds_read_b128 v[160:163], v217 offset:33792
	ds_read_b128 v[164:167], v217 offset:34816
	ds_read_b128 v[188:191], v217 offset:35840
	ds_read_b128 v[192:195], v217 offset:36864
	ds_read_b128 v[196:199], v217 offset:37888
	ds_read_b128 v[200:203], v217 offset:38912
	ds_read_b128 v[204:207], v217 offset:39936
	global_load_lds_dwordx4 v148, s[36:37]
	s_mov_b32 m0, s86
	s_nop 0
	global_load_lds_dwordx4 v146, s[36:37]
	s_waitcnt lgkmcnt(8)
	s_barrier
	s_waitcnt lgkmcnt(0)
	v_mfma_f32_16x16x32_bf16 v[124:127], v[128:131], v[156:159], v[124:127]
	v_mfma_f32_16x16x32_bf16 v[120:123], v[136:139], v[156:159], v[120:123]
	v_mfma_f32_16x16x32_bf16 v[108:111], v[128:131], v[164:167], v[108:111]
	v_mfma_f32_16x16x32_bf16 v[104:107], v[136:139], v[164:167], v[104:107]
	v_mfma_f32_16x16x32_bf16 v[92:95], v[128:131], v[192:195], v[92:95]
	v_mfma_f32_16x16x32_bf16 v[88:91], v[136:139], v[192:195], v[88:91]
	v_mfma_f32_16x16x32_bf16 v[76:79], v[128:131], v[200:203], v[76:79]
	v_mfma_f32_16x16x32_bf16 v[72:75], v[136:139], v[200:203], v[72:75]
	v_mfma_f32_16x16x32_bf16 v[124:127], v[132:135], v[160:163], v[124:127]
	v_mfma_f32_16x16x32_bf16 v[120:123], v[140:143], v[160:163], v[120:123]
	v_mfma_f32_16x16x32_bf16 v[108:111], v[132:135], v[188:191], v[108:111]
	v_mfma_f32_16x16x32_bf16 v[104:107], v[140:143], v[188:191], v[104:107]
	v_mfma_f32_16x16x32_bf16 v[92:95], v[132:135], v[196:199], v[92:95]
	v_mfma_f32_16x16x32_bf16 v[88:91], v[140:143], v[196:199], v[88:91]
	v_mfma_f32_16x16x32_bf16 v[76:79], v[132:135], v[204:207], v[76:79]
	v_mfma_f32_16x16x32_bf16 v[72:75], v[140:143], v[204:207], v[72:75]
	s_barrier
	s_add_i32 s35, 0, 0x1c000
	s_add_i32 s27, s27, s81
	s_add_u32 s36, s72, s18
	s_addc_u32 s37, s73, s19
	s_mov_b32 m0, s27
	ds_read_b128 v[220:223], v216 offset:49152
	ds_read_b128 v[228:231], v216 offset:50176
	ds_read_b128 v[232:235], v216 offset:51200
	ds_read_b128 v[236:239], v216 offset:52224
	global_load_lds_dwordx4 v148, s[36:37]
	s_add_u32 s36, s72, s18
	s_addc_u32 s37, s73, s19
	s_add_i32 m0, s27, 0x2000
	s_nop 0
	global_load_lds_dwordx4 v146, s[36:37]
	s_barrier
	s_waitcnt lgkmcnt(0)
	v_mfma_f32_16x16x32_bf16 v[116:119], v[220:223], v[156:159], v[116:119]
	v_mfma_f32_16x16x32_bf16 v[112:115], v[232:235], v[156:159], v[112:115]
	v_mfma_f32_16x16x32_bf16 v[100:103], v[220:223], v[164:167], v[100:103]
	v_mfma_f32_16x16x32_bf16 v[96:99], v[232:235], v[164:167], v[96:99]
	v_mfma_f32_16x16x32_bf16 v[84:87], v[220:223], v[192:195], v[84:87]
	v_mfma_f32_16x16x32_bf16 v[80:83], v[232:235], v[192:195], v[80:83]
	v_mfma_f32_16x16x32_bf16 v[68:71], v[220:223], v[200:203], v[68:71]
	v_mfma_f32_16x16x32_bf16 v[64:67], v[232:235], v[200:203], v[64:67]
	v_mfma_f32_16x16x32_bf16 v[116:119], v[228:231], v[160:163], v[116:119]
	v_mfma_f32_16x16x32_bf16 v[112:115], v[236:239], v[160:163], v[112:115]
	v_mfma_f32_16x16x32_bf16 v[100:103], v[228:231], v[188:191], v[100:103]
	v_mfma_f32_16x16x32_bf16 v[96:99], v[236:239], v[188:191], v[96:99]
	v_mfma_f32_16x16x32_bf16 v[84:87], v[228:231], v[196:199], v[84:87]
	v_mfma_f32_16x16x32_bf16 v[80:83], v[236:239], v[196:199], v[80:83]
	v_mfma_f32_16x16x32_bf16 v[68:71], v[228:231], v[204:207], v[68:71]
	v_mfma_f32_16x16x32_bf16 v[64:67], v[236:239], v[204:207], v[64:67]
	s_barrier
	s_mov_b32 m0, s87
	s_add_u32 s36, s74, s18
	s_addc_u32 s37, s75, s19
	ds_read_b128 v[156:159], v217 offset:49152
	ds_read_b128 v[160:163], v217 offset:50176
	ds_read_b128 v[164:167], v217 offset:51200
	ds_read_b128 v[188:191], v217 offset:52224
	ds_read_b128 v[192:195], v217 offset:53248
	ds_read_b128 v[196:199], v217 offset:54272
	ds_read_b128 v[200:203], v217 offset:55296
	ds_read_b128 v[204:207], v217 offset:56320
	global_load_lds_dwordx4 v148, s[36:37]
	s_add_u32 s36, s74, s18
	s_addc_u32 s37, s75, s19
	s_mov_b32 m0, s79
	s_nop 0
	global_load_lds_dwordx4 v146, s[36:37]
	s_barrier
	s_waitcnt lgkmcnt(0)
	v_mfma_f32_16x16x32_bf16 v[60:63], v[128:131], v[156:159], v[60:63]
	v_mfma_f32_16x16x32_bf16 v[56:59], v[136:139], v[156:159], v[56:59]
	v_mfma_f32_16x16x32_bf16 v[44:47], v[128:131], v[164:167], v[44:47]
	v_mfma_f32_16x16x32_bf16 v[40:43], v[136:139], v[164:167], v[40:43]
	v_mfma_f32_16x16x32_bf16 v[28:31], v[128:131], v[192:195], v[28:31]
	v_mfma_f32_16x16x32_bf16 v[24:27], v[136:139], v[192:195], v[24:27]
	v_mfma_f32_16x16x32_bf16 v[12:15], v[128:131], v[200:203], v[12:15]
	v_mfma_f32_16x16x32_bf16 v[8:11], v[136:139], v[200:203], v[8:11]
	v_mfma_f32_16x16x32_bf16 v[60:63], v[132:135], v[160:163], v[60:63]
	v_mfma_f32_16x16x32_bf16 v[56:59], v[140:143], v[160:163], v[56:59]
	v_mfma_f32_16x16x32_bf16 v[44:47], v[132:135], v[188:191], v[44:47]
	v_mfma_f32_16x16x32_bf16 v[40:43], v[140:143], v[188:191], v[40:43]
	v_mfma_f32_16x16x32_bf16 v[28:31], v[132:135], v[196:199], v[28:31]
	v_mfma_f32_16x16x32_bf16 v[24:27], v[140:143], v[196:199], v[24:27]
	v_mfma_f32_16x16x32_bf16 v[12:15], v[132:135], v[204:207], v[12:15]
	v_mfma_f32_16x16x32_bf16 v[8:11], v[140:143], v[204:207], v[8:11]
	s_barrier
	s_add_u32 s36, s72, 0x40080
	s_addc_u32 s37, s73, 0
	s_add_i32 s27, s35, s81
	s_mov_b32 m0, s27
	s_nop 0
	global_load_lds_dwordx4 v148, s[36:37]
	s_add_i32 m0, s27, 0x2000
	s_nop 0
	global_load_lds_dwordx4 v146, s[36:37]
	s_waitcnt vmcnt(6)
	s_barrier
	v_mfma_f32_16x16x32_bf16 v[52:55], v[220:223], v[156:159], v[52:55]
	v_mfma_f32_16x16x32_bf16 v[48:51], v[232:235], v[156:159], v[48:51]
	v_mfma_f32_16x16x32_bf16 v[36:39], v[220:223], v[164:167], v[36:39]
	v_mfma_f32_16x16x32_bf16 v[32:35], v[232:235], v[164:167], v[32:35]
	v_mfma_f32_16x16x32_bf16 v[20:23], v[220:223], v[192:195], v[20:23]
	v_mfma_f32_16x16x32_bf16 v[16:19], v[232:235], v[192:195], v[16:19]
	v_mfma_f32_16x16x32_bf16 v[4:7], v[220:223], v[200:203], v[4:7]
	v_mfma_f32_16x16x32_bf16 v[0:3], v[232:235], v[200:203], v[0:3]
	v_mfma_f32_16x16x32_bf16 v[52:55], v[228:231], v[160:163], v[52:55]
	v_mfma_f32_16x16x32_bf16 v[48:51], v[236:239], v[160:163], v[48:51]
	v_mfma_f32_16x16x32_bf16 v[36:39], v[228:231], v[188:191], v[36:39]
	v_mfma_f32_16x16x32_bf16 v[32:35], v[236:239], v[188:191], v[32:35]
	v_mfma_f32_16x16x32_bf16 v[20:23], v[228:231], v[196:199], v[20:23]
	v_mfma_f32_16x16x32_bf16 v[16:19], v[236:239], v[196:199], v[16:19]
	v_mfma_f32_16x16x32_bf16 v[4:7], v[228:231], v[204:207], v[4:7]
	v_mfma_f32_16x16x32_bf16 v[0:3], v[236:239], v[204:207], v[0:3]
	s_barrier
	s_add_i32 s34, s34, 2
	s_add_u32 s52, s52, 0x100
	s_addc_u32 s53, s53, 0
	s_add_u32 s31, s31, 0x100
	s_addc_u32 s33, s33, 0
	s_cmp_gt_u32 s34, 13
	s_cbranch_scc0 .LBB0_326
	v_lshl_add_u32 v128, s0, 8, v151
	v_readlane_b32 s0, v252, 36
	v_ashrrev_i32_e32 v129, 31, v128
	v_readlane_b32 s1, v252, 37
	v_or_b32_e32 v132, 16, v128
	v_or_b32_e32 v136, 32, v128
	v_lshl_add_u64 v[130:131], v[128:129], 3, s[0:1]
	v_ashrrev_i32_e32 v133, 31, v132
	v_ashrrev_i32_e32 v137, 31, v136
	v_or_b32_e32 v140, 48, v128
	v_lshl_add_u64 v[134:135], v[132:133], 3, s[0:1]
	v_lshl_add_u64 v[138:139], v[136:137], 3, s[0:1]
	v_ashrrev_i32_e32 v141, 31, v140
	global_load_dwordx2 v[202:203], v[130:131], off
	global_load_dwordx2 v[200:201], v[134:135], off
	global_load_dwordx2 v[192:193], v[138:139], off
	global_load_dwordx2 v[166:167], v[130:131], off offset:1024
	v_add_u32_e32 v164, 0x90, v128
	v_add_u32_e32 v158, 0xa0, v128
	v_add_u32_e32 v156, 0xb0, v128
	v_lshl_add_u64 v[142:143], v[140:141], 3, s[0:1]
	v_ashrrev_i32_e32 v165, 31, v164
	v_ashrrev_i32_e32 v159, 31, v158
	v_ashrrev_i32_e32 v157, 31, v156
	v_lshl_add_u64 v[130:131], v[164:165], 3, s[0:1]
	v_lshl_add_u64 v[134:135], v[158:159], 3, s[0:1]
	v_lshl_add_u64 v[138:139], v[156:157], 3, s[0:1]
	global_load_dwordx2 v[196:197], v[142:143], off
	global_load_dwordx2 v[188:189], v[130:131], off
	global_load_dwordx2 v[162:163], v[134:135], off
	global_load_dwordx2 v[160:161], v[138:139], off
	v_add_u32_e32 v168, 0x80, v128
	s_mov_b64 s[0:1], -1
	s_cmp_gt_u32 s10, 1
	v_lshlrev_b32_e32 v144, 1, v150
	v_ashrrev_i32_e32 v169, 31, v168
	v_lshlrev_b64 v[204:205], 10, v[128:129]
	v_lshlrev_b64 v[198:199], 10, v[132:133]
	v_lshlrev_b64 v[194:195], 10, v[136:137]
	v_lshlrev_b64 v[190:191], 10, v[140:141]
	s_waitcnt vmcnt(0)
	v_ffbh_u32_e32 v222, v203
	v_ffbh_u32_e32 v221, v201
	v_ffbh_u32_e32 v220, v193
	v_ffbh_u32_e32 v219, v197
	s_cbranch_scc0 .LBB0_329
	s_cmp_lt_u32 s10, 4
	s_cselect_b64 vcc, -1, 0
	v_readlane_b32 s56, v254, 23
	s_and_b64 s[0:1], vcc, exec
	v_readlane_b32 s70, v254, 37
	v_readlane_b32 s36, v252, 15
	v_readlane_b32 s71, v254, 38
	v_readlane_b32 s37, v252, 16
	s_cselect_b32 s0, s70, s36
	s_mov_b32 s11, 0x4400000
	v_readlane_b32 s30, v254, 62
	s_cselect_b32 s1, s71, s37
	s_cselect_b32 s11, s11, 0x4800000
	v_readlane_b32 s31, v254, 63
	s_add_u32 s0, s0, s30
	s_addc_u32 s1, s1, s31
	global_load_dwordx4 v[136:139], v218, s[0:1] offset:16
	global_load_dwordx4 v[140:143], v218, s[0:1]
	global_load_dwordx4 v[128:131], v218, s[0:1] offset:144
	global_load_dwordx4 v[132:135], v218, s[0:1] offset:128
	v_and_b32_e32 v177, 64, v214
	v_xor_b32_e32 v176, 16, v214
	v_add_u32_e32 v177, 64, v177
	v_cndmask_b32_e32 v223, 1.0, v215, vcc
	v_cmp_lt_i32_e32 vcc, v176, v177
	v_readlane_b32 s9, v254, 52
	s_add_u32 s11, s9, s11
	v_cndmask_b32_e32 v176, v214, v176, vcc
	v_lshlrev_b32_e32 v225, 2, v176
	v_xor_b32_e32 v176, 32, v214
	v_cmp_lt_i32_e32 vcc, v176, v177
	v_readlane_b32 s9, v254, 61
	s_addc_u32 s25, s9, 0
	v_cndmask_b32_e32 v176, v214, v176, vcc
	v_lshlrev_b32_e32 v224, 2, v176
	v_min_u32_e32 v176, 32, v222
	v_lshlrev_b64 v[228:229], v176, v[202:203]
	v_min_u32_e32 v177, 1, v228
	v_or_b32_e32 v177, v229, v177
	v_cvt_f32_u32_e32 v177, v177
	v_sub_u32_e32 v176, 32, v176
	s_lshl_b32 s0, s10, 9
	s_and_b32 s0, s0, 0x200
	v_ldexp_f32 v176, v177, v176
	v_mul_f32_e32 v176, 0x35800000, v176
	v_fmamk_f32 v176, v176, 0x3a800000, v210
	s_add_u32 s0, s11, s0
	v_rsq_f32_e32 v176, v176
	s_addc_u32 s1, s25, 0
	v_lshl_add_u64 v[206:207], s[0:1], 0, v[144:145]
	v_readlane_b32 s48, v252, 27
	v_mov_b32_e32 v228, v176
	v_pk_mul_f32 v[230:231], v[124:125], v[228:229] op_sel_hi:[1,0]
	v_pk_mul_f32 v[232:233], v[126:127], v[228:229] op_sel_hi:[1,0]
	v_pk_mul_f32 v[236:237], v[230:231], v[230:231]
	v_pk_mul_f32 v[234:235], v[232:233], v[232:233]
	v_pk_mul_f32 v[250:251], v[114:115], v[228:229] op_sel_hi:[1,0]
	v_pk_mov_b32 v[238:239], v[236:237], v[234:235] op_sel:[1,0]
	v_mov_b32_e32 v237, v235
	v_pk_add_f32 v[234:235], v[238:239], v[236:237]
	v_pk_mul_f32 v[236:237], v[120:121], v[228:229] op_sel_hi:[1,0]
	v_pk_mul_f32 v[238:239], v[122:123], v[228:229] op_sel_hi:[1,0]
	v_pk_mul_f32 v[242:243], v[236:237], v[236:237]
	v_pk_mul_f32 v[240:241], v[238:239], v[238:239]
	v_pk_add_f32 v[234:235], v[234:235], v[234:235] op_sel_hi:[0,1]
	v_pk_mov_b32 v[244:245], v[242:243], v[240:241] op_sel:[1,0]
	v_mov_b32_e32 v243, v241
	v_pk_add_f32 v[240:241], v[244:245], v[242:243]
	v_pk_mul_f32 v[244:245], v[116:117], v[228:229] op_sel_hi:[1,0]
	v_pk_mul_f32 v[242:243], v[118:119], v[228:229] op_sel_hi:[1,0]
	v_mul_f32_e32 v234, v244, v244
	v_pk_fma_f32 v[246:247], v[244:245], v[244:245], v[234:235] op_sel_hi:[1,1,0]
	v_mul_f32_e32 v234, v242, v242
	v_pk_add_f32 v[240:241], v[240:241], v[240:241] op_sel_hi:[0,1]
	v_pk_fma_f32 v[248:249], v[242:243], v[242:243], v[234:235] op_sel_hi:[1,1,0]
	v_pk_mul_f32 v[176:177], v[112:113], v[228:229] op_sel_hi:[1,0]
	v_mul_f32_e32 v234, v250, v250
	v_mul_f32_e32 v246, v176, v176
	v_mul_f32_e32 v248, v177, v177
	v_mul_f32_e32 v240, v251, v251
	v_pk_add_f32 v[228:229], v[246:247], v[248:249]
	v_pk_add_f32 v[234:235], v[234:235], v[240:241]
	v_lshl_add_u64 v[240:241], v[206:207], 0, v[204:205]
	v_pk_add_f32 v[228:229], v[228:229], v[234:235]
	v_readlane_b32 s57, v254, 24
	v_add_f32_e32 v228, v228, v229
	ds_bpermute_b32 v229, v225, v228
	v_readlane_b32 s58, v254, 25
	v_readlane_b32 s59, v254, 26
	v_readlane_b32 s60, v254, 27
	v_readlane_b32 s61, v254, 28
	s_waitcnt lgkmcnt(0)
	v_add_f32_e32 v228, v228, v229
	ds_bpermute_b32 v229, v224, v228
	v_readlane_b32 s62, v254, 29
	v_readlane_b32 s63, v254, 30
	v_readlane_b32 s64, v254, 31
	v_readlane_b32 s65, v254, 32
	s_waitcnt lgkmcnt(0)
	v_add_f32_e32 v228, v228, v229
	v_fmamk_f32 v228, v228, 0x3c800000, v210
	v_readlane_b32 s66, v254, 33
	v_rsq_f32_e32 v228, v228
	v_readlane_b32 s67, v254, 34
	v_readlane_b32 s68, v254, 35
	v_readlane_b32 s69, v254, 36
	v_mul_f32_e32 v234, v223, v228
	v_pk_mul_f32 v[228:229], v[230:231], v[234:235] op_sel_hi:[1,0]
	v_pk_mul_f32 v[230:231], v[232:233], v[234:235] op_sel_hi:[1,0]
	s_waitcnt vmcnt(2)
	v_pk_mul_f32 v[228:229], v[140:141], v[228:229]
	v_pk_mul_f32 v[230:231], v[142:143], v[230:231]
	v_pk_mul_f32 v[232:233], v[236:237], v[234:235] op_sel_hi:[1,0]
	v_pk_mul_f32 v[236:237], v[238:239], v[234:235] op_sel_hi:[1,0]
	v_cvt_pk_bf16_f32 v228, v228, v229
	v_cvt_pk_bf16_f32 v229, v230, v231
	v_pk_mul_f32 v[232:233], v[136:137], v[232:233]
	v_pk_mul_f32 v[236:237], v[138:139], v[236:237]
	v_cvt_pk_bf16_f32 v230, v232, v233
	v_pk_mul_f32 v[176:177], v[176:177], v[234:235] op_sel_hi:[1,0]
	v_cvt_pk_bf16_f32 v231, v236, v237
	global_store_dwordx4 v[240:241], v[228:231], off
	v_pk_mul_f32 v[232:233], v[250:251], v[234:235] op_sel_hi:[1,0]
	s_waitcnt vmcnt(2)
	v_pk_mul_f32 v[176:177], v[128:129], v[176:177]
	v_pk_mul_f32 v[228:229], v[244:245], v[234:235] op_sel_hi:[1,0]
	v_pk_mul_f32 v[230:231], v[242:243], v[234:235] op_sel_hi:[1,0]
	s_waitcnt vmcnt(1)
	v_pk_mul_f32 v[228:229], v[132:133], v[228:229]
	v_pk_mul_f32 v[230:231], v[134:135], v[230:231]
	v_cvt_pk_bf16_f32 v228, v228, v229
	v_pk_mul_f32 v[232:233], v[130:131], v[232:233]
	v_cvt_pk_bf16_f32 v229, v230, v231
	v_cvt_pk_bf16_f32 v230, v176, v177
	s_nop 1
	v_readlane_b32 s38, v252, 17
	v_cvt_pk_bf16_f32 v231, v232, v233
	s_nop 1
	global_store_dwordx4 v[240:241], v[228:231], off offset:64
	v_readlane_b32 s39, v252, 18
	v_readlane_b32 s40, v252, 19
	v_min_u32_e32 v228, 32, v221
	v_lshlrev_b64 v[176:177], v228, v[200:201]
	v_min_u32_e32 v176, 1, v176
	v_or_b32_e32 v176, v177, v176
	v_cvt_f32_u32_e32 v176, v176
	v_sub_u32_e32 v177, 32, v228
	v_readlane_b32 s41, v252, 20
	v_readlane_b32 s42, v252, 21
	v_ldexp_f32 v176, v176, v177
	v_mul_f32_e32 v176, 0x35800000, v176
	v_fmamk_f32 v176, v176, 0x3a800000, v210
	v_readlane_b32 s43, v252, 22
	v_rsq_f32_e32 v176, v176
	v_readlane_b32 s44, v252, 23
	v_readlane_b32 s45, v252, 24
	v_readlane_b32 s46, v252, 25
	v_pk_mul_f32 v[228:229], v[108:109], v[176:177] op_sel_hi:[1,0]
	v_pk_mul_f32 v[230:231], v[110:111], v[176:177] op_sel_hi:[1,0]
	v_pk_mul_f32 v[234:235], v[228:229], v[228:229]
	v_pk_mul_f32 v[232:233], v[230:231], v[230:231]
	v_pk_mul_f32 v[248:249], v[98:99], v[176:177] op_sel_hi:[1,0]
	v_pk_mov_b32 v[236:237], v[234:235], v[232:233] op_sel:[1,0]
	v_mov_b32_e32 v235, v233
	v_pk_add_f32 v[232:233], v[236:237], v[234:235]
	v_pk_mul_f32 v[234:235], v[104:105], v[176:177] op_sel_hi:[1,0]
	v_pk_mul_f32 v[236:237], v[106:107], v[176:177] op_sel_hi:[1,0]
	v_pk_mul_f32 v[240:241], v[234:235], v[234:235]
	v_pk_mul_f32 v[238:239], v[236:237], v[236:237]
	v_pk_add_f32 v[232:233], v[232:233], v[232:233] op_sel_hi:[0,1]
	v_pk_mov_b32 v[242:243], v[240:241], v[238:239] op_sel:[1,0]
	v_mov_b32_e32 v241, v239
	v_pk_add_f32 v[238:239], v[242:243], v[240:241]
	v_pk_mul_f32 v[242:243], v[100:101], v[176:177] op_sel_hi:[1,0]
	v_pk_mul_f32 v[240:241], v[102:103], v[176:177] op_sel_hi:[1,0]
	v_mul_f32_e32 v232, v242, v242
	v_pk_fma_f32 v[244:245], v[242:243], v[242:243], v[232:233] op_sel_hi:[1,1,0]
	v_mul_f32_e32 v232, v240, v240
	v_pk_add_f32 v[238:239], v[238:239], v[238:239] op_sel_hi:[0,1]
	v_pk_fma_f32 v[246:247], v[240:241], v[240:241], v[232:233] op_sel_hi:[1,1,0]
	v_pk_mul_f32 v[176:177], v[96:97], v[176:177] op_sel_hi:[1,0]
	v_mul_f32_e32 v232, v248, v248
	v_mul_f32_e32 v244, v176, v176
	v_mul_f32_e32 v246, v177, v177
	v_mul_f32_e32 v238, v249, v249
	v_pk_add_f32 v[244:245], v[244:245], v[246:247]
	v_pk_add_f32 v[232:233], v[232:233], v[238:239]
	v_lshl_add_u64 v[238:239], v[206:207], 0, v[198:199]
	v_pk_add_f32 v[232:233], v[244:245], v[232:233]
	v_readlane_b32 s47, v252, 26
	v_add_f32_e32 v232, v232, v233
	ds_bpermute_b32 v233, v225, v232
	v_readlane_b32 s49, v252, 28
	v_readlane_b32 s50, v252, 29
	v_readlane_b32 s51, v252, 30
	v_readlane_b32 s48, v252, 40
	s_waitcnt lgkmcnt(0)
	v_add_f32_e32 v232, v232, v233
	ds_bpermute_b32 v233, v224, v232
	s_mov_b64 s[0:1], 0
	s_waitcnt lgkmcnt(0)
	v_add_f32_e32 v232, v232, v233
	v_fmamk_f32 v232, v232, 0x3c800000, v210
	s_nop 0
	v_rsq_f32_e32 v232, v232
	s_nop 0
	v_mul_f32_e32 v232, v223, v232
	v_pk_mul_f32 v[228:229], v[228:229], v[232:233] op_sel_hi:[1,0]
	v_pk_mul_f32 v[230:231], v[230:231], v[232:233] op_sel_hi:[1,0]
	v_pk_mul_f32 v[228:229], v[140:141], v[228:229]
	v_pk_mul_f32 v[230:231], v[142:143], v[230:231]
	v_pk_mul_f32 v[234:235], v[234:235], v[232:233] op_sel_hi:[1,0]
	v_pk_mul_f32 v[236:237], v[236:237], v[232:233] op_sel_hi:[1,0]
	v_cvt_pk_bf16_f32 v228, v228, v229
	v_cvt_pk_bf16_f32 v229, v230, v231
	v_pk_mul_f32 v[234:235], v[136:137], v[234:235]
	v_pk_mul_f32 v[236:237], v[138:139], v[236:237]
	v_cvt_pk_bf16_f32 v230, v234, v235
	v_pk_mul_f32 v[176:177], v[176:177], v[232:233] op_sel_hi:[1,0]
	v_cvt_pk_bf16_f32 v231, v236, v237
	global_store_dwordx4 v[238:239], v[228:231], off
	v_pk_mul_f32 v[176:177], v[128:129], v[176:177]
	s_nop 0
	v_pk_mul_f32 v[228:229], v[242:243], v[232:233] op_sel_hi:[1,0]
	v_pk_mul_f32 v[230:231], v[240:241], v[232:233] op_sel_hi:[1,0]
	v_pk_mul_f32 v[228:229], v[132:133], v[228:229]
	v_pk_mul_f32 v[230:231], v[134:135], v[230:231]
	v_pk_mul_f32 v[232:233], v[248:249], v[232:233] op_sel_hi:[1,0]
	v_cvt_pk_bf16_f32 v228, v228, v229
	v_cvt_pk_bf16_f32 v229, v230, v231
	v_cvt_pk_bf16_f32 v230, v176, v177
	s_nop 0
	v_pk_mul_f32 v[232:233], v[130:131], v[232:233]
	s_nop 0
	v_cvt_pk_bf16_f32 v231, v232, v233
	global_store_dwordx4 v[238:239], v[228:231], off offset:64
	s_nop 1
	v_min_u32_e32 v228, 32, v220
	v_lshlrev_b64 v[176:177], v228, v[192:193]
	v_min_u32_e32 v176, 1, v176
	v_or_b32_e32 v176, v177, v176
	v_cvt_f32_u32_e32 v176, v176
	v_sub_u32_e32 v177, 32, v228
	v_ldexp_f32 v176, v176, v177
	v_mul_f32_e32 v176, 0x35800000, v176
	v_fmamk_f32 v176, v176, 0x3a800000, v210
	s_nop 0
	v_rsq_f32_e32 v176, v176
	s_nop 0
	v_pk_mul_f32 v[228:229], v[92:93], v[176:177] op_sel_hi:[1,0]
	v_pk_mul_f32 v[230:231], v[94:95], v[176:177] op_sel_hi:[1,0]
	v_pk_mul_f32 v[234:235], v[228:229], v[228:229]
	v_pk_mul_f32 v[232:233], v[230:231], v[230:231]
	v_pk_mul_f32 v[248:249], v[82:83], v[176:177] op_sel_hi:[1,0]
	v_pk_mov_b32 v[236:237], v[234:235], v[232:233] op_sel:[1,0]
	v_mov_b32_e32 v235, v233
	v_pk_add_f32 v[232:233], v[236:237], v[234:235]
	v_pk_mul_f32 v[234:235], v[88:89], v[176:177] op_sel_hi:[1,0]
	v_pk_mul_f32 v[236:237], v[90:91], v[176:177] op_sel_hi:[1,0]
	v_pk_mul_f32 v[240:241], v[234:235], v[234:235]
	v_pk_mul_f32 v[238:239], v[236:237], v[236:237]
	v_pk_add_f32 v[232:233], v[232:233], v[232:233] op_sel_hi:[0,1]
	v_pk_mov_b32 v[242:243], v[240:241], v[238:239] op_sel:[1,0]
	v_mov_b32_e32 v241, v239
	v_pk_add_f32 v[238:239], v[242:243], v[240:241]
	v_pk_mul_f32 v[242:243], v[84:85], v[176:177] op_sel_hi:[1,0]
	v_pk_mul_f32 v[240:241], v[86:87], v[176:177] op_sel_hi:[1,0]
	v_mul_f32_e32 v232, v242, v242
	v_pk_fma_f32 v[244:245], v[242:243], v[242:243], v[232:233] op_sel_hi:[1,1,0]
	v_mul_f32_e32 v232, v240, v240
	v_pk_add_f32 v[238:239], v[238:239], v[238:239] op_sel_hi:[0,1]
	v_pk_fma_f32 v[246:247], v[240:241], v[240:241], v[232:233] op_sel_hi:[1,1,0]
	v_pk_mul_f32 v[176:177], v[80:81], v[176:177] op_sel_hi:[1,0]
	v_mul_f32_e32 v232, v248, v248
	v_mul_f32_e32 v244, v176, v176
	v_mul_f32_e32 v246, v177, v177
	v_mul_f32_e32 v238, v249, v249
	v_pk_add_f32 v[244:245], v[244:245], v[246:247]
	v_pk_add_f32 v[232:233], v[232:233], v[238:239]
	v_lshl_add_u64 v[238:239], v[206:207], 0, v[194:195]
	v_pk_add_f32 v[232:233], v[244:245], v[232:233]
	s_nop 0
	v_add_f32_e32 v232, v232, v233
	ds_bpermute_b32 v233, v225, v232
	s_waitcnt lgkmcnt(0)
	v_add_f32_e32 v232, v232, v233
	ds_bpermute_b32 v233, v224, v232
	s_waitcnt lgkmcnt(0)
	v_add_f32_e32 v232, v232, v233
	v_fmamk_f32 v232, v232, 0x3c800000, v210
	s_nop 0
	v_rsq_f32_e32 v232, v232
	s_nop 0
	v_mul_f32_e32 v232, v223, v232
	v_pk_mul_f32 v[228:229], v[228:229], v[232:233] op_sel_hi:[1,0]
	v_pk_mul_f32 v[230:231], v[230:231], v[232:233] op_sel_hi:[1,0]
	v_pk_mul_f32 v[228:229], v[140:141], v[228:229]
	v_pk_mul_f32 v[230:231], v[142:143], v[230:231]
	v_pk_mul_f32 v[234:235], v[234:235], v[232:233] op_sel_hi:[1,0]
	v_pk_mul_f32 v[236:237], v[236:237], v[232:233] op_sel_hi:[1,0]
	v_cvt_pk_bf16_f32 v228, v228, v229
	v_cvt_pk_bf16_f32 v229, v230, v231
	v_pk_mul_f32 v[234:235], v[136:137], v[234:235]
	v_pk_mul_f32 v[236:237], v[138:139], v[236:237]
	v_cvt_pk_bf16_f32 v230, v234, v235
	v_pk_mul_f32 v[176:177], v[176:177], v[232:233] op_sel_hi:[1,0]
	v_cvt_pk_bf16_f32 v231, v236, v237
	global_store_dwordx4 v[238:239], v[228:231], off
	v_pk_mul_f32 v[176:177], v[128:129], v[176:177]
	s_nop 0
	v_pk_mul_f32 v[228:229], v[242:243], v[232:233] op_sel_hi:[1,0]
	v_pk_mul_f32 v[230:231], v[240:241], v[232:233] op_sel_hi:[1,0]
	v_pk_mul_f32 v[228:229], v[132:133], v[228:229]
	v_pk_mul_f32 v[230:231], v[134:135], v[230:231]
	v_pk_mul_f32 v[232:233], v[248:249], v[232:233] op_sel_hi:[1,0]
	v_cvt_pk_bf16_f32 v228, v228, v229
	v_cvt_pk_bf16_f32 v229, v230, v231
	v_cvt_pk_bf16_f32 v230, v176, v177
	s_nop 0
	v_pk_mul_f32 v[232:233], v[130:131], v[232:233]
	s_nop 0
	v_cvt_pk_bf16_f32 v231, v232, v233
	global_store_dwordx4 v[238:239], v[228:231], off offset:64
	s_nop 1
	v_min_u32_e32 v228, 32, v219
	v_lshlrev_b64 v[176:177], v228, v[196:197]
	v_min_u32_e32 v176, 1, v176
	v_or_b32_e32 v176, v177, v176
	v_cvt_f32_u32_e32 v176, v176
	v_sub_u32_e32 v177, 32, v228
	v_ldexp_f32 v176, v176, v177
	v_mul_f32_e32 v176, 0x35800000, v176
	v_fmamk_f32 v176, v176, 0x3a800000, v210
	s_nop 0
	v_rsq_f32_e32 v176, v176
	s_nop 0
	v_pk_mul_f32 v[228:229], v[76:77], v[176:177] op_sel_hi:[1,0]
	v_pk_mul_f32 v[230:231], v[78:79], v[176:177] op_sel_hi:[1,0]
	v_pk_mul_f32 v[234:235], v[228:229], v[228:229]
	v_pk_mul_f32 v[232:233], v[230:231], v[230:231]
	v_pk_mul_f32 v[248:249], v[66:67], v[176:177] op_sel_hi:[1,0]
	v_pk_mov_b32 v[236:237], v[234:235], v[232:233] op_sel:[1,0]
	v_mov_b32_e32 v235, v233
	v_pk_add_f32 v[232:233], v[236:237], v[234:235]
	v_pk_mul_f32 v[234:235], v[72:73], v[176:177] op_sel_hi:[1,0]
	v_pk_mul_f32 v[236:237], v[74:75], v[176:177] op_sel_hi:[1,0]
	v_pk_mul_f32 v[240:241], v[234:235], v[234:235]
	v_pk_mul_f32 v[238:239], v[236:237], v[236:237]
	v_pk_add_f32 v[232:233], v[232:233], v[232:233] op_sel_hi:[0,1]
	v_pk_mov_b32 v[242:243], v[240:241], v[238:239] op_sel:[1,0]
	v_mov_b32_e32 v241, v239
	v_pk_add_f32 v[238:239], v[242:243], v[240:241]
	v_pk_mul_f32 v[242:243], v[68:69], v[176:177] op_sel_hi:[1,0]
	v_pk_mul_f32 v[240:241], v[70:71], v[176:177] op_sel_hi:[1,0]
	v_mul_f32_e32 v232, v242, v242
	v_pk_fma_f32 v[244:245], v[242:243], v[242:243], v[232:233] op_sel_hi:[1,1,0]
	v_mul_f32_e32 v232, v240, v240
	v_pk_add_f32 v[238:239], v[238:239], v[238:239] op_sel_hi:[0,1]
	v_pk_fma_f32 v[246:247], v[240:241], v[240:241], v[232:233] op_sel_hi:[1,1,0]
	v_pk_mul_f32 v[176:177], v[64:65], v[176:177] op_sel_hi:[1,0]
	v_mul_f32_e32 v232, v248, v248
	v_mul_f32_e32 v244, v176, v176
	v_mul_f32_e32 v246, v177, v177
	v_mul_f32_e32 v238, v249, v249
	v_pk_add_f32 v[244:245], v[244:245], v[246:247]
	v_pk_add_f32 v[232:233], v[232:233], v[238:239]
	v_lshl_add_u64 v[238:239], v[206:207], 0, v[190:191]
	v_pk_add_f32 v[232:233], v[244:245], v[232:233]
	s_nop 0
	v_add_f32_e32 v232, v232, v233
	ds_bpermute_b32 v233, v225, v232
	s_waitcnt lgkmcnt(0)
	v_add_f32_e32 v232, v232, v233
	ds_bpermute_b32 v233, v224, v232
	s_waitcnt lgkmcnt(0)
	v_add_f32_e32 v232, v232, v233
	v_fmamk_f32 v232, v232, 0x3c800000, v210
	s_nop 0
	v_rsq_f32_e32 v232, v232
	s_nop 0
	v_mul_f32_e32 v232, v223, v232
	v_pk_mul_f32 v[228:229], v[228:229], v[232:233] op_sel_hi:[1,0]
	v_pk_mul_f32 v[230:231], v[230:231], v[232:233] op_sel_hi:[1,0]
	v_pk_mul_f32 v[228:229], v[140:141], v[228:229]
	v_pk_mul_f32 v[230:231], v[142:143], v[230:231]
	v_pk_mul_f32 v[234:235], v[234:235], v[232:233] op_sel_hi:[1,0]
	v_pk_mul_f32 v[236:237], v[236:237], v[232:233] op_sel_hi:[1,0]
	v_pk_mul_f32 v[234:235], v[136:137], v[234:235]
	v_pk_mul_f32 v[236:237], v[138:139], v[236:237]
	v_cvt_pk_bf16_f32 v228, v228, v229
	v_cvt_pk_bf16_f32 v229, v230, v231
	v_cvt_pk_bf16_f32 v230, v234, v235
	v_pk_mul_f32 v[176:177], v[176:177], v[232:233] op_sel_hi:[1,0]
	v_cvt_pk_bf16_f32 v231, v236, v237
	global_store_dwordx4 v[238:239], v[228:231], off
	v_pk_mul_f32 v[176:177], v[128:129], v[176:177]
	s_nop 0
	v_pk_mul_f32 v[228:229], v[242:243], v[232:233] op_sel_hi:[1,0]
	v_pk_mul_f32 v[230:231], v[240:241], v[232:233] op_sel_hi:[1,0]
	v_pk_mul_f32 v[228:229], v[132:133], v[228:229]
	v_pk_mul_f32 v[230:231], v[134:135], v[230:231]
	v_pk_mul_f32 v[232:233], v[248:249], v[232:233] op_sel_hi:[1,0]
	v_cvt_pk_bf16_f32 v228, v228, v229
	v_cvt_pk_bf16_f32 v229, v230, v231
	v_cvt_pk_bf16_f32 v230, v176, v177
	v_ffbh_u32_e32 v176, v167
	v_pk_mul_f32 v[232:233], v[130:131], v[232:233]
	s_nop 0
	v_cvt_pk_bf16_f32 v231, v232, v233
	global_store_dwordx4 v[238:239], v[228:231], off offset:64
	s_nop 1
	v_min_u32_e32 v228, 32, v176
	v_lshlrev_b64 v[176:177], v228, v[166:167]
	v_min_u32_e32 v176, 1, v176
	v_or_b32_e32 v176, v177, v176
	v_cvt_f32_u32_e32 v176, v176
	v_sub_u32_e32 v177, 32, v228
	v_ldexp_f32 v176, v176, v177
	v_mul_f32_e32 v176, 0x35800000, v176
	v_fmamk_f32 v176, v176, 0x3a800000, v210
	s_nop 0
	v_rsq_f32_e32 v176, v176
	s_nop 0
	v_pk_mul_f32 v[228:229], v[60:61], v[176:177] op_sel_hi:[1,0]
	v_pk_mul_f32 v[230:231], v[62:63], v[176:177] op_sel_hi:[1,0]
	v_pk_mul_f32 v[234:235], v[228:229], v[228:229]
	v_pk_mul_f32 v[232:233], v[230:231], v[230:231]
	v_pk_mul_f32 v[248:249], v[50:51], v[176:177] op_sel_hi:[1,0]
	v_pk_mov_b32 v[236:237], v[234:235], v[232:233] op_sel:[1,0]
	v_mov_b32_e32 v235, v233
	v_pk_add_f32 v[232:233], v[236:237], v[234:235]
	v_pk_mul_f32 v[234:235], v[56:57], v[176:177] op_sel_hi:[1,0]
	v_pk_mul_f32 v[236:237], v[58:59], v[176:177] op_sel_hi:[1,0]
	v_pk_mul_f32 v[240:241], v[234:235], v[234:235]
	v_pk_mul_f32 v[238:239], v[236:237], v[236:237]
	v_pk_add_f32 v[232:233], v[232:233], v[232:233] op_sel_hi:[0,1]
	v_pk_mov_b32 v[242:243], v[240:241], v[238:239] op_sel:[1,0]
	v_mov_b32_e32 v241, v239
	v_pk_add_f32 v[238:239], v[242:243], v[240:241]
	v_pk_mul_f32 v[242:243], v[52:53], v[176:177] op_sel_hi:[1,0]
	v_pk_mul_f32 v[240:241], v[54:55], v[176:177] op_sel_hi:[1,0]
	v_mul_f32_e32 v232, v242, v242
	v_pk_fma_f32 v[244:245], v[242:243], v[242:243], v[232:233] op_sel_hi:[1,1,0]
	v_mul_f32_e32 v232, v240, v240
	v_pk_add_f32 v[238:239], v[238:239], v[238:239] op_sel_hi:[0,1]
	v_pk_fma_f32 v[246:247], v[240:241], v[240:241], v[232:233] op_sel_hi:[1,1,0]
	v_pk_mul_f32 v[176:177], v[48:49], v[176:177] op_sel_hi:[1,0]
	v_mul_f32_e32 v232, v248, v248
	v_mul_f32_e32 v244, v176, v176
	v_mul_f32_e32 v246, v177, v177
	v_mul_f32_e32 v238, v249, v249
	v_pk_add_f32 v[244:245], v[244:245], v[246:247]
	v_pk_add_f32 v[232:233], v[232:233], v[238:239]
	v_lshlrev_b64 v[238:239], 10, v[168:169]
	v_pk_add_f32 v[232:233], v[244:245], v[232:233]
	v_lshl_add_u64 v[238:239], v[206:207], 0, v[238:239]
	v_add_f32_e32 v232, v232, v233
	ds_bpermute_b32 v233, v225, v232
	s_waitcnt lgkmcnt(0)
	v_add_f32_e32 v232, v232, v233
	ds_bpermute_b32 v233, v224, v232
	s_waitcnt lgkmcnt(0)
	v_add_f32_e32 v232, v232, v233
	v_fmamk_f32 v232, v232, 0x3c800000, v210
	s_nop 0
	v_rsq_f32_e32 v232, v232
	s_nop 0
	v_mul_f32_e32 v232, v223, v232
	v_pk_mul_f32 v[228:229], v[228:229], v[232:233] op_sel_hi:[1,0]
	v_pk_mul_f32 v[230:231], v[230:231], v[232:233] op_sel_hi:[1,0]
	v_pk_mul_f32 v[228:229], v[140:141], v[228:229]
	v_pk_mul_f32 v[230:231], v[142:143], v[230:231]
	v_pk_mul_f32 v[234:235], v[234:235], v[232:233] op_sel_hi:[1,0]
	v_pk_mul_f32 v[236:237], v[236:237], v[232:233] op_sel_hi:[1,0]
	v_pk_mul_f32 v[234:235], v[136:137], v[234:235]
	v_pk_mul_f32 v[236:237], v[138:139], v[236:237]
	v_cvt_pk_bf16_f32 v228, v228, v229
	v_cvt_pk_bf16_f32 v229, v230, v231
	v_cvt_pk_bf16_f32 v230, v234, v235
	v_pk_mul_f32 v[176:177], v[176:177], v[232:233] op_sel_hi:[1,0]
	v_cvt_pk_bf16_f32 v231, v236, v237
	global_store_dwordx4 v[238:239], v[228:231], off
	v_pk_mul_f32 v[176:177], v[128:129], v[176:177]
	s_nop 0
	v_pk_mul_f32 v[228:229], v[242:243], v[232:233] op_sel_hi:[1,0]
	v_pk_mul_f32 v[230:231], v[240:241], v[232:233] op_sel_hi:[1,0]
	v_pk_mul_f32 v[228:229], v[132:133], v[228:229]
	v_pk_mul_f32 v[230:231], v[134:135], v[230:231]
	v_pk_mul_f32 v[232:233], v[248:249], v[232:233] op_sel_hi:[1,0]
	v_cvt_pk_bf16_f32 v228, v228, v229
	v_cvt_pk_bf16_f32 v229, v230, v231
	v_cvt_pk_bf16_f32 v230, v176, v177
	v_ffbh_u32_e32 v176, v189
	v_pk_mul_f32 v[232:233], v[130:131], v[232:233]
	s_nop 0
	v_cvt_pk_bf16_f32 v231, v232, v233
	global_store_dwordx4 v[238:239], v[228:231], off offset:64
	s_nop 1
	v_min_u32_e32 v228, 32, v176
	v_lshlrev_b64 v[176:177], v228, v[188:189]
	v_min_u32_e32 v176, 1, v176
	v_or_b32_e32 v176, v177, v176
	v_cvt_f32_u32_e32 v176, v176
	v_sub_u32_e32 v177, 32, v228
	v_ldexp_f32 v176, v176, v177
	v_mul_f32_e32 v176, 0x35800000, v176
	v_fmamk_f32 v176, v176, 0x3a800000, v210
	s_nop 0
	v_rsq_f32_e32 v176, v176
	s_nop 0
	v_pk_mul_f32 v[228:229], v[44:45], v[176:177] op_sel_hi:[1,0]
	v_pk_mul_f32 v[230:231], v[46:47], v[176:177] op_sel_hi:[1,0]
	v_pk_mul_f32 v[234:235], v[228:229], v[228:229]
	v_pk_mul_f32 v[232:233], v[230:231], v[230:231]
	v_pk_mul_f32 v[248:249], v[34:35], v[176:177] op_sel_hi:[1,0]
	v_pk_mov_b32 v[236:237], v[234:235], v[232:233] op_sel:[1,0]
	v_mov_b32_e32 v235, v233
	v_pk_add_f32 v[232:233], v[236:237], v[234:235]
	v_pk_mul_f32 v[234:235], v[40:41], v[176:177] op_sel_hi:[1,0]
	v_pk_mul_f32 v[236:237], v[42:43], v[176:177] op_sel_hi:[1,0]
	v_pk_mul_f32 v[240:241], v[234:235], v[234:235]
	v_pk_mul_f32 v[238:239], v[236:237], v[236:237]
	v_pk_add_f32 v[232:233], v[232:233], v[232:233] op_sel_hi:[0,1]
	v_pk_mov_b32 v[242:243], v[240:241], v[238:239] op_sel:[1,0]
	v_mov_b32_e32 v241, v239
	v_pk_add_f32 v[238:239], v[242:243], v[240:241]
	v_pk_mul_f32 v[242:243], v[36:37], v[176:177] op_sel_hi:[1,0]
	v_pk_mul_f32 v[240:241], v[38:39], v[176:177] op_sel_hi:[1,0]
	v_mul_f32_e32 v232, v242, v242
	v_pk_fma_f32 v[244:245], v[242:243], v[242:243], v[232:233] op_sel_hi:[1,1,0]
	v_mul_f32_e32 v232, v240, v240
	v_pk_add_f32 v[238:239], v[238:239], v[238:239] op_sel_hi:[0,1]
	v_pk_fma_f32 v[246:247], v[240:241], v[240:241], v[232:233] op_sel_hi:[1,1,0]
	v_pk_mul_f32 v[176:177], v[32:33], v[176:177] op_sel_hi:[1,0]
	v_mul_f32_e32 v232, v248, v248
	v_mul_f32_e32 v244, v176, v176
	v_mul_f32_e32 v246, v177, v177
	v_mul_f32_e32 v238, v249, v249
	v_pk_add_f32 v[244:245], v[244:245], v[246:247]
	v_pk_add_f32 v[232:233], v[232:233], v[238:239]
	v_lshlrev_b64 v[238:239], 10, v[164:165]
	v_pk_add_f32 v[232:233], v[244:245], v[232:233]
	v_lshl_add_u64 v[238:239], v[206:207], 0, v[238:239]
	v_add_f32_e32 v232, v232, v233
	ds_bpermute_b32 v233, v225, v232
	s_waitcnt lgkmcnt(0)
	v_add_f32_e32 v232, v232, v233
	ds_bpermute_b32 v233, v224, v232
	s_waitcnt lgkmcnt(0)
	v_add_f32_e32 v232, v232, v233
	v_fmamk_f32 v232, v232, 0x3c800000, v210
	s_nop 0
	v_rsq_f32_e32 v232, v232
	s_nop 0
	v_mul_f32_e32 v232, v223, v232
	v_pk_mul_f32 v[228:229], v[228:229], v[232:233] op_sel_hi:[1,0]
	v_pk_mul_f32 v[230:231], v[230:231], v[232:233] op_sel_hi:[1,0]
	v_pk_mul_f32 v[228:229], v[140:141], v[228:229]
	v_pk_mul_f32 v[230:231], v[142:143], v[230:231]
	v_pk_mul_f32 v[234:235], v[234:235], v[232:233] op_sel_hi:[1,0]
	v_pk_mul_f32 v[236:237], v[236:237], v[232:233] op_sel_hi:[1,0]
	v_pk_mul_f32 v[234:235], v[136:137], v[234:235]
	v_pk_mul_f32 v[236:237], v[138:139], v[236:237]
	v_cvt_pk_bf16_f32 v228, v228, v229
	v_cvt_pk_bf16_f32 v229, v230, v231
	v_cvt_pk_bf16_f32 v230, v234, v235
	v_pk_mul_f32 v[176:177], v[176:177], v[232:233] op_sel_hi:[1,0]
	v_cvt_pk_bf16_f32 v231, v236, v237
	global_store_dwordx4 v[238:239], v[228:231], off
	v_pk_mul_f32 v[176:177], v[128:129], v[176:177]
	s_nop 0
	v_pk_mul_f32 v[228:229], v[242:243], v[232:233] op_sel_hi:[1,0]
	v_pk_mul_f32 v[230:231], v[240:241], v[232:233] op_sel_hi:[1,0]
	v_pk_mul_f32 v[228:229], v[132:133], v[228:229]
	v_pk_mul_f32 v[230:231], v[134:135], v[230:231]
	v_pk_mul_f32 v[232:233], v[248:249], v[232:233] op_sel_hi:[1,0]
	v_cvt_pk_bf16_f32 v228, v228, v229
	v_cvt_pk_bf16_f32 v229, v230, v231
	v_cvt_pk_bf16_f32 v230, v176, v177
	v_ffbh_u32_e32 v176, v163
	v_pk_mul_f32 v[232:233], v[130:131], v[232:233]
	s_nop 0
	v_cvt_pk_bf16_f32 v231, v232, v233
	global_store_dwordx4 v[238:239], v[228:231], off offset:64
	s_nop 1
	v_min_u32_e32 v228, 32, v176
	v_lshlrev_b64 v[176:177], v228, v[162:163]
	v_min_u32_e32 v176, 1, v176
	v_or_b32_e32 v176, v177, v176
	v_cvt_f32_u32_e32 v176, v176
	v_sub_u32_e32 v177, 32, v228
	v_ldexp_f32 v176, v176, v177
	v_mul_f32_e32 v176, 0x35800000, v176
	v_fmamk_f32 v176, v176, 0x3a800000, v210
	s_nop 0
	v_rsq_f32_e32 v176, v176
	s_nop 0
	v_pk_mul_f32 v[228:229], v[28:29], v[176:177] op_sel_hi:[1,0]
	v_pk_mul_f32 v[230:231], v[30:31], v[176:177] op_sel_hi:[1,0]
	v_pk_mul_f32 v[234:235], v[228:229], v[228:229]
	v_pk_mul_f32 v[232:233], v[230:231], v[230:231]
	v_pk_mul_f32 v[248:249], v[18:19], v[176:177] op_sel_hi:[1,0]
	v_pk_mov_b32 v[236:237], v[234:235], v[232:233] op_sel:[1,0]
	v_mov_b32_e32 v235, v233
	v_pk_add_f32 v[232:233], v[236:237], v[234:235]
	v_pk_mul_f32 v[234:235], v[24:25], v[176:177] op_sel_hi:[1,0]
	v_pk_mul_f32 v[236:237], v[26:27], v[176:177] op_sel_hi:[1,0]
	v_pk_mul_f32 v[240:241], v[234:235], v[234:235]
	v_pk_mul_f32 v[238:239], v[236:237], v[236:237]
	v_pk_add_f32 v[232:233], v[232:233], v[232:233] op_sel_hi:[0,1]
	v_pk_mov_b32 v[242:243], v[240:241], v[238:239] op_sel:[1,0]
	v_mov_b32_e32 v241, v239
	v_pk_add_f32 v[238:239], v[242:243], v[240:241]
	v_pk_mul_f32 v[242:243], v[20:21], v[176:177] op_sel_hi:[1,0]
	v_pk_mul_f32 v[240:241], v[22:23], v[176:177] op_sel_hi:[1,0]
	v_mul_f32_e32 v232, v242, v242
	v_pk_fma_f32 v[244:245], v[242:243], v[242:243], v[232:233] op_sel_hi:[1,1,0]
	v_mul_f32_e32 v232, v240, v240
	v_pk_add_f32 v[238:239], v[238:239], v[238:239] op_sel_hi:[0,1]
	v_pk_fma_f32 v[246:247], v[240:241], v[240:241], v[232:233] op_sel_hi:[1,1,0]
	v_pk_mul_f32 v[176:177], v[16:17], v[176:177] op_sel_hi:[1,0]
	v_mul_f32_e32 v232, v248, v248
	v_mul_f32_e32 v244, v176, v176
	v_mul_f32_e32 v246, v177, v177
	v_mul_f32_e32 v238, v249, v249
	v_pk_add_f32 v[244:245], v[244:245], v[246:247]
	v_pk_add_f32 v[232:233], v[232:233], v[238:239]
	v_lshlrev_b64 v[238:239], 10, v[158:159]
	v_pk_add_f32 v[232:233], v[244:245], v[232:233]
	v_lshl_add_u64 v[238:239], v[206:207], 0, v[238:239]
	v_add_f32_e32 v232, v232, v233
	ds_bpermute_b32 v233, v225, v232
	s_waitcnt lgkmcnt(0)
	v_add_f32_e32 v232, v232, v233
	ds_bpermute_b32 v233, v224, v232
	s_waitcnt lgkmcnt(0)
	v_add_f32_e32 v232, v232, v233
	v_fmamk_f32 v232, v232, 0x3c800000, v210
	s_nop 0
	v_rsq_f32_e32 v232, v232
	s_nop 0
	v_mul_f32_e32 v232, v223, v232
	v_pk_mul_f32 v[228:229], v[228:229], v[232:233] op_sel_hi:[1,0]
	v_pk_mul_f32 v[230:231], v[230:231], v[232:233] op_sel_hi:[1,0]
	v_pk_mul_f32 v[228:229], v[140:141], v[228:229]
	v_pk_mul_f32 v[230:231], v[142:143], v[230:231]
	v_pk_mul_f32 v[234:235], v[234:235], v[232:233] op_sel_hi:[1,0]
	v_pk_mul_f32 v[236:237], v[236:237], v[232:233] op_sel_hi:[1,0]
	v_pk_mul_f32 v[234:235], v[136:137], v[234:235]
	v_pk_mul_f32 v[236:237], v[138:139], v[236:237]
	v_cvt_pk_bf16_f32 v228, v228, v229
	v_cvt_pk_bf16_f32 v229, v230, v231
	v_cvt_pk_bf16_f32 v230, v234, v235
	v_pk_mul_f32 v[176:177], v[176:177], v[232:233] op_sel_hi:[1,0]
	v_cvt_pk_bf16_f32 v231, v236, v237
	global_store_dwordx4 v[238:239], v[228:231], off
	v_pk_mul_f32 v[176:177], v[128:129], v[176:177]
	s_nop 0
	v_pk_mul_f32 v[228:229], v[242:243], v[232:233] op_sel_hi:[1,0]
	v_pk_mul_f32 v[230:231], v[240:241], v[232:233] op_sel_hi:[1,0]
	v_pk_mul_f32 v[228:229], v[132:133], v[228:229]
	v_pk_mul_f32 v[230:231], v[134:135], v[230:231]
	v_pk_mul_f32 v[232:233], v[248:249], v[232:233] op_sel_hi:[1,0]
	v_cvt_pk_bf16_f32 v228, v228, v229
	v_cvt_pk_bf16_f32 v229, v230, v231
	v_cvt_pk_bf16_f32 v230, v176, v177
	v_ffbh_u32_e32 v176, v161
	v_pk_mul_f32 v[232:233], v[130:131], v[232:233]
	s_nop 0
	v_cvt_pk_bf16_f32 v231, v232, v233
	global_store_dwordx4 v[238:239], v[228:231], off offset:64
	s_nop 1
	v_min_u32_e32 v228, 32, v176
	v_lshlrev_b64 v[176:177], v228, v[160:161]
	v_min_u32_e32 v176, 1, v176
	v_or_b32_e32 v176, v177, v176
	v_cvt_f32_u32_e32 v176, v176
	v_sub_u32_e32 v177, 32, v228
	v_ldexp_f32 v176, v176, v177
	v_mul_f32_e32 v176, 0x35800000, v176
	v_fmamk_f32 v176, v176, 0x3a800000, v210
	s_nop 0
	v_rsq_f32_e32 v176, v176
	s_nop 0
	v_pk_mul_f32 v[228:229], v[12:13], v[176:177] op_sel_hi:[1,0]
	v_pk_mul_f32 v[230:231], v[14:15], v[176:177] op_sel_hi:[1,0]
	v_pk_mul_f32 v[234:235], v[228:229], v[228:229]
	v_pk_mul_f32 v[232:233], v[230:231], v[230:231]
	v_pk_mul_f32 v[248:249], v[2:3], v[176:177] op_sel_hi:[1,0]
	v_pk_mov_b32 v[236:237], v[234:235], v[232:233] op_sel:[1,0]
	v_mov_b32_e32 v235, v233
	v_pk_add_f32 v[232:233], v[236:237], v[234:235]
	v_pk_mul_f32 v[234:235], v[8:9], v[176:177] op_sel_hi:[1,0]
	v_pk_mul_f32 v[236:237], v[10:11], v[176:177] op_sel_hi:[1,0]
	v_pk_mul_f32 v[240:241], v[234:235], v[234:235]
	v_pk_mul_f32 v[238:239], v[236:237], v[236:237]
	v_pk_add_f32 v[232:233], v[232:233], v[232:233] op_sel_hi:[0,1]
	v_pk_mov_b32 v[242:243], v[240:241], v[238:239] op_sel:[1,0]
	v_mov_b32_e32 v241, v239
	v_pk_add_f32 v[238:239], v[242:243], v[240:241]
	v_pk_mul_f32 v[242:243], v[4:5], v[176:177] op_sel_hi:[1,0]
	v_pk_mul_f32 v[240:241], v[6:7], v[176:177] op_sel_hi:[1,0]
	v_mul_f32_e32 v232, v242, v242
	v_pk_fma_f32 v[244:245], v[242:243], v[242:243], v[232:233] op_sel_hi:[1,1,0]
	v_mul_f32_e32 v232, v240, v240
	v_pk_add_f32 v[238:239], v[238:239], v[238:239] op_sel_hi:[0,1]
	v_pk_fma_f32 v[246:247], v[240:241], v[240:241], v[232:233] op_sel_hi:[1,1,0]
	v_pk_mul_f32 v[176:177], v[0:1], v[176:177] op_sel_hi:[1,0]
	v_mul_f32_e32 v232, v248, v248
	v_mul_f32_e32 v244, v176, v176
	v_mul_f32_e32 v246, v177, v177
	v_mul_f32_e32 v238, v249, v249
	v_pk_add_f32 v[244:245], v[244:245], v[246:247]
	v_pk_add_f32 v[232:233], v[232:233], v[238:239]
	s_nop 0
	v_pk_add_f32 v[232:233], v[244:245], v[232:233]
	s_nop 0
	v_add_f32_e32 v232, v232, v233
	ds_bpermute_b32 v225, v225, v232
	s_waitcnt lgkmcnt(0)
	v_add_f32_e32 v225, v232, v225
	ds_bpermute_b32 v224, v224, v225
	v_lshlrev_b64 v[232:233], 10, v[156:157]
	v_lshl_add_u64 v[206:207], v[206:207], 0, v[232:233]
	s_waitcnt lgkmcnt(0)
	v_add_f32_e32 v224, v225, v224
	v_fmamk_f32 v224, v224, 0x3c800000, v210
	s_nop 0
	v_rsq_f32_e32 v224, v224
	s_nop 0
	v_mul_f32_e32 v224, v223, v224
	v_pk_mul_f32 v[228:229], v[228:229], v[224:225] op_sel_hi:[1,0]
	v_pk_mul_f32 v[230:231], v[230:231], v[224:225] op_sel_hi:[1,0]
	v_pk_mul_f32 v[140:141], v[140:141], v[228:229]
	v_pk_mul_f32 v[142:143], v[142:143], v[230:231]
	v_pk_mul_f32 v[228:229], v[234:235], v[224:225] op_sel_hi:[1,0]
	v_pk_mul_f32 v[230:231], v[236:237], v[224:225] op_sel_hi:[1,0]
	s_nop 0
	v_pk_mul_f32 v[230:231], v[138:139], v[230:231]
	v_pk_mul_f32 v[138:139], v[136:137], v[228:229]
	v_cvt_pk_bf16_f32 v136, v140, v141
	v_cvt_pk_bf16_f32 v137, v142, v143
	s_nop 0
	v_cvt_pk_bf16_f32 v138, v138, v139
	v_cvt_pk_bf16_f32 v139, v230, v231
	global_store_dwordx4 v[206:207], v[136:139], off
	s_nop 1
	v_pk_mul_f32 v[136:137], v[242:243], v[224:225] op_sel_hi:[1,0]
	v_pk_mul_f32 v[138:139], v[240:241], v[224:225] op_sel_hi:[1,0]
	v_pk_mul_f32 v[132:133], v[132:133], v[136:137]
	v_pk_mul_f32 v[134:135], v[134:135], v[138:139]
	v_pk_mul_f32 v[136:137], v[176:177], v[224:225] op_sel_hi:[1,0]
	v_pk_mul_f32 v[138:139], v[248:249], v[224:225] op_sel_hi:[1,0]
	s_nop 0
	v_pk_mul_f32 v[138:139], v[130:131], v[138:139]
	v_pk_mul_f32 v[130:131], v[128:129], v[136:137]
	v_cvt_pk_bf16_f32 v128, v132, v133
	v_cvt_pk_bf16_f32 v129, v134, v135
	s_nop 0
	v_cvt_pk_bf16_f32 v130, v130, v131
	v_cvt_pk_bf16_f32 v131, v138, v139
	s_nop 1

.LBB0_350:
	s_nop 0
	s_lshl_b32 s25, s84, 1
	s_add_i32 s25, s85, s25
	s_and_b32 s85, s25, 3
	s_lshl_b32 s25, s85, 19
	s_add_u32 s92, s74, s25
	v_cmp_lt_i64_e32 vcc, s[52:53], v[180:181]
	s_addc_u32 s93, s75, 0
	s_and_b64 s[30:31], vcc, exec
	s_cselect_b32 s25, s93, s1
	s_cselect_b32 s30, s92, s0
	s_ashr_i32 s47, s46, 31
	s_lshl_b64 s[34:35], s[46:47], 19
	s_add_u32 s94, s54, s34
	s_addc_u32 s95, s55, s35
	s_and_b64 s[34:35], vcc, exec
	s_cselect_b32 s31, s95, s51
	s_cselect_b32 s33, s94, s50
	s_add_u32 s0, s0, 0x40080
	s_addc_u32 s1, s1, 0
	s_add_u32 s34, s50, 0x100
	s_addc_u32 s35, s51, 0
	s_mov_b32 s36, -2
	s_add_u32 s27, s0, 0xfffc0080
	s_addc_u32 s37, s1, -1
	s_add_i32 s47, 0, 0x10000
	ds_read_b128 v[128:131], v192
	ds_read_b128 v[132:135], v192 offset:1024
	ds_read_b128 v[136:139], v192 offset:2048
	ds_read_b128 v[140:143], v192 offset:3072
	s_cmp_eq_u32 s36, 12
	s_cselect_b32 s53, s25, s37
	s_cselect_b32 s52, s30, s27
	s_cselect_b32 s51, s31, s35
	s_cselect_b32 s50, s33, s34
	s_add_i32 m0, s77, 0xc000
	ds_read_b128 v[162:165], v194
	ds_read_b128 v[166:169], v194 offset:1024
	ds_read_b128 v[196:199], v194 offset:2048
	ds_read_b128 v[200:203], v194 offset:3072
	ds_read_b128 v[204:207], v194 offset:4096
	ds_read_b128 v[216:219], v194 offset:5120
	ds_read_b128 v[220:223], v194 offset:6144
	ds_read_b128 v[228:231], v194 offset:7168
	global_load_lds_dwordx4 v156, s[0:1]
	s_add_i32 m0, s77, 0xe000
	s_nop 0
	global_load_lds_dwordx4 v158, s[0:1]
	s_waitcnt lgkmcnt(8)
	s_barrier
	s_waitcnt lgkmcnt(0)
	v_mfma_f32_16x16x32_bf16 v[124:127], v[128:131], v[162:165], 0
	v_mfma_f32_16x16x32_bf16 v[120:123], v[136:139], v[162:165], 0
	v_mfma_f32_16x16x32_bf16 v[116:119], v[128:131], v[196:199], 0
	v_mfma_f32_16x16x32_bf16 v[112:115], v[136:139], v[196:199], 0
	v_mfma_f32_16x16x32_bf16 v[108:111], v[128:131], v[204:207], 0
	v_mfma_f32_16x16x32_bf16 v[104:107], v[136:139], v[204:207], 0
	v_mfma_f32_16x16x32_bf16 v[100:103], v[128:131], v[220:223], 0
	v_mfma_f32_16x16x32_bf16 v[96:99], v[136:139], v[220:223], 0
	v_mfma_f32_16x16x32_bf16 v[124:127], v[132:135], v[166:169], v[124:127]
	v_mfma_f32_16x16x32_bf16 v[120:123], v[140:143], v[166:169], v[120:123]
	v_mfma_f32_16x16x32_bf16 v[116:119], v[132:135], v[200:203], v[116:119]
	v_mfma_f32_16x16x32_bf16 v[112:115], v[140:143], v[200:203], v[112:115]
	v_mfma_f32_16x16x32_bf16 v[108:111], v[132:135], v[216:219], v[108:111]
	v_mfma_f32_16x16x32_bf16 v[104:107], v[140:143], v[216:219], v[104:107]
	v_mfma_f32_16x16x32_bf16 v[100:103], v[132:135], v[228:231], v[100:103]
	v_mfma_f32_16x16x32_bf16 v[96:99], v[140:143], v[228:231], v[96:99]
	s_barrier
	s_add_i32 s27, 0, 0x14000
	s_add_i32 s37, s47, s76
	s_mov_b32 m0, s37
	ds_read_b128 v[232:235], v192 offset:16384
	ds_read_b128 v[236:239], v192 offset:17408
	ds_read_b128 v[240:243], v192 offset:18432
	ds_read_b128 v[244:247], v192 offset:19456
	global_load_lds_dwordx4 v148, s[50:51]
	s_add_i32 m0, s37, 0x2000
	s_nop 0
	global_load_lds_dwordx4 v152, s[50:51]
	s_barrier
	s_waitcnt lgkmcnt(0)
	v_mfma_f32_16x16x32_bf16 v[92:95], v[232:235], v[162:165], 0
	v_mfma_f32_16x16x32_bf16 v[88:91], v[240:243], v[162:165], 0
	v_mfma_f32_16x16x32_bf16 v[84:87], v[232:235], v[196:199], 0
	v_mfma_f32_16x16x32_bf16 v[80:83], v[240:243], v[196:199], 0
	v_mfma_f32_16x16x32_bf16 v[76:79], v[232:235], v[204:207], 0
	v_mfma_f32_16x16x32_bf16 v[72:75], v[240:243], v[204:207], 0
	v_mfma_f32_16x16x32_bf16 v[68:71], v[232:235], v[220:223], 0
	v_mfma_f32_16x16x32_bf16 v[64:67], v[240:243], v[220:223], 0
	v_mfma_f32_16x16x32_bf16 v[92:95], v[236:239], v[166:169], v[92:95]
	v_mfma_f32_16x16x32_bf16 v[88:91], v[244:247], v[166:169], v[88:91]
	v_mfma_f32_16x16x32_bf16 v[84:87], v[236:239], v[200:203], v[84:87]
	v_mfma_f32_16x16x32_bf16 v[80:83], v[244:247], v[200:203], v[80:83]
	v_mfma_f32_16x16x32_bf16 v[76:79], v[236:239], v[216:219], v[76:79]
	v_mfma_f32_16x16x32_bf16 v[72:75], v[244:247], v[216:219], v[72:75]
	v_mfma_f32_16x16x32_bf16 v[68:71], v[236:239], v[228:231], v[68:71]
	v_mfma_f32_16x16x32_bf16 v[64:67], v[244:247], v[228:231], v[64:67]
	s_barrier
	s_mov_b32 m0, s77
	v_lshl_add_u64 v[224:225], s[52:53], 0, v[146:147]
	ds_read_b128 v[162:165], v194 offset:16384
	ds_read_b128 v[166:169], v194 offset:17408
	ds_read_b128 v[196:199], v194 offset:18432
	ds_read_b128 v[200:203], v194 offset:19456
	ds_read_b128 v[204:207], v194 offset:20480
	ds_read_b128 v[216:219], v194 offset:21504
	ds_read_b128 v[220:223], v194 offset:22528
	ds_read_b128 v[228:231], v194 offset:23552
	global_load_lds_dwordx4 v[224:225], off
	v_lshl_add_u64 v[248:249], s[52:53], 0, v[150:151]
	s_mov_b32 m0, s78
	s_nop 0
	global_load_lds_dwordx4 v[248:249], off
	s_barrier
	s_waitcnt lgkmcnt(0)
	v_mfma_f32_16x16x32_bf16 v[60:63], v[128:131], v[162:165], 0
	v_mfma_f32_16x16x32_bf16 v[56:59], v[136:139], v[162:165], 0
	v_mfma_f32_16x16x32_bf16 v[52:55], v[128:131], v[196:199], 0
	v_mfma_f32_16x16x32_bf16 v[48:51], v[136:139], v[196:199], 0
	v_mfma_f32_16x16x32_bf16 v[44:47], v[128:131], v[204:207], 0
	v_mfma_f32_16x16x32_bf16 v[40:43], v[136:139], v[204:207], 0
	v_mfma_f32_16x16x32_bf16 v[36:39], v[128:131], v[220:223], 0
	v_mfma_f32_16x16x32_bf16 v[32:35], v[136:139], v[220:223], 0
	v_mfma_f32_16x16x32_bf16 v[60:63], v[132:135], v[166:169], v[60:63]
	v_mfma_f32_16x16x32_bf16 v[56:59], v[140:143], v[166:169], v[56:59]
	v_mfma_f32_16x16x32_bf16 v[52:55], v[132:135], v[200:203], v[52:55]
	v_mfma_f32_16x16x32_bf16 v[48:51], v[140:143], v[200:203], v[48:51]
	v_mfma_f32_16x16x32_bf16 v[44:47], v[132:135], v[216:219], v[44:47]
	v_mfma_f32_16x16x32_bf16 v[40:43], v[140:143], v[216:219], v[40:43]
	v_mfma_f32_16x16x32_bf16 v[36:39], v[132:135], v[228:231], v[36:39]
	v_mfma_f32_16x16x32_bf16 v[32:35], v[140:143], v[228:231], v[32:35]
	s_barrier
	s_add_u32 s56, s50, 0x40000
	s_addc_u32 s57, s51, 0
	s_add_i32 s27, s27, s76
	s_mov_b32 m0, s27
	s_nop 0
	global_load_lds_dwordx4 v148, s[56:57]
	s_add_i32 m0, s27, 0x2000
	s_nop 0
	global_load_lds_dwordx4 v152, s[56:57]
	s_waitcnt vmcnt(6)
	s_barrier
	v_mfma_f32_16x16x32_bf16 v[28:31], v[232:235], v[162:165], 0
	v_mfma_f32_16x16x32_bf16 v[24:27], v[240:243], v[162:165], 0
	v_mfma_f32_16x16x32_bf16 v[20:23], v[232:235], v[196:199], 0
	v_mfma_f32_16x16x32_bf16 v[16:19], v[240:243], v[196:199], 0
	v_mfma_f32_16x16x32_bf16 v[12:15], v[232:235], v[204:207], 0
	v_mfma_f32_16x16x32_bf16 v[8:11], v[240:243], v[204:207], 0
	v_mfma_f32_16x16x32_bf16 v[4:7], v[232:235], v[220:223], 0
	v_mfma_f32_16x16x32_bf16 v[0:3], v[240:243], v[220:223], 0
	v_mfma_f32_16x16x32_bf16 v[28:31], v[236:239], v[166:169], v[28:31]
	v_mfma_f32_16x16x32_bf16 v[24:27], v[244:247], v[166:169], v[24:27]
	v_mfma_f32_16x16x32_bf16 v[20:23], v[236:239], v[200:203], v[20:23]
	v_mfma_f32_16x16x32_bf16 v[16:19], v[244:247], v[200:203], v[16:19]
	v_mfma_f32_16x16x32_bf16 v[12:15], v[236:239], v[216:219], v[12:15]
	v_mfma_f32_16x16x32_bf16 v[8:11], v[244:247], v[216:219], v[8:11]
	v_mfma_f32_16x16x32_bf16 v[4:7], v[236:239], v[228:231], v[4:7]
	v_mfma_f32_16x16x32_bf16 v[0:3], v[244:247], v[228:231], v[0:3]
	s_barrier
	s_add_i32 s27, 0, 0x18000
	ds_read_b128 v[128:131], v192 offset:32768
	ds_read_b128 v[132:135], v192 offset:33792
	ds_read_b128 v[136:139], v192 offset:34816
	ds_read_b128 v[140:143], v192 offset:35840
	s_add_u32 s52, s52, 0x40000
	s_addc_u32 s53, s53, 0
	s_mov_b32 m0, s81
	ds_read_b128 v[162:165], v194 offset:32768
	ds_read_b128 v[166:169], v194 offset:33792
	ds_read_b128 v[196:199], v194 offset:34816
	ds_read_b128 v[200:203], v194 offset:35840
	ds_read_b128 v[204:207], v194 offset:36864
	ds_read_b128 v[216:219], v194 offset:37888
	ds_read_b128 v[220:223], v194 offset:38912
	ds_read_b128 v[228:231], v194 offset:39936
	global_load_lds_dwordx4 v146, s[52:53]
	s_mov_b32 m0, s82
	s_nop 0
	global_load_lds_dwordx4 v150, s[52:53]
	s_waitcnt lgkmcnt(8)
	s_barrier
	s_waitcnt lgkmcnt(0)
	v_mfma_f32_16x16x32_bf16 v[124:127], v[128:131], v[162:165], v[124:127]
	v_mfma_f32_16x16x32_bf16 v[120:123], v[136:139], v[162:165], v[120:123]
	v_mfma_f32_16x16x32_bf16 v[116:119], v[128:131], v[196:199], v[116:119]
	v_mfma_f32_16x16x32_bf16 v[112:115], v[136:139], v[196:199], v[112:115]
	v_mfma_f32_16x16x32_bf16 v[108:111], v[128:131], v[204:207], v[108:111]
	v_mfma_f32_16x16x32_bf16 v[104:107], v[136:139], v[204:207], v[104:107]
	v_mfma_f32_16x16x32_bf16 v[100:103], v[128:131], v[220:223], v[100:103]
	v_mfma_f32_16x16x32_bf16 v[96:99], v[136:139], v[220:223], v[96:99]
	v_mfma_f32_16x16x32_bf16 v[124:127], v[132:135], v[166:169], v[124:127]
	v_mfma_f32_16x16x32_bf16 v[120:123], v[140:143], v[166:169], v[120:123]
	v_mfma_f32_16x16x32_bf16 v[116:119], v[132:135], v[200:203], v[116:119]
	v_mfma_f32_16x16x32_bf16 v[112:115], v[140:143], v[200:203], v[112:115]
	v_mfma_f32_16x16x32_bf16 v[108:111], v[132:135], v[216:219], v[108:111]
	v_mfma_f32_16x16x32_bf16 v[104:107], v[140:143], v[216:219], v[104:107]
	v_mfma_f32_16x16x32_bf16 v[100:103], v[132:135], v[228:231], v[100:103]
	v_mfma_f32_16x16x32_bf16 v[96:99], v[140:143], v[228:231], v[96:99]
	s_barrier
	s_add_i32 s37, 0, 0x1c000
	s_add_i32 s27, s27, s76
	s_add_u32 s56, s50, s18
	s_addc_u32 s57, s51, s19
	s_mov_b32 m0, s27
	ds_read_b128 v[232:235], v192 offset:49152
	ds_read_b128 v[236:239], v192 offset:50176
	ds_read_b128 v[240:243], v192 offset:51200
	ds_read_b128 v[244:247], v192 offset:52224
	global_load_lds_dwordx4 v148, s[56:57]
	s_add_u32 s56, s50, s18
	s_addc_u32 s57, s51, s19
	s_add_i32 m0, s27, 0x2000
	s_nop 0
	global_load_lds_dwordx4 v152, s[56:57]
	s_barrier
	s_waitcnt lgkmcnt(0)
	v_mfma_f32_16x16x32_bf16 v[92:95], v[232:235], v[162:165], v[92:95]
	v_mfma_f32_16x16x32_bf16 v[88:91], v[240:243], v[162:165], v[88:91]
	v_mfma_f32_16x16x32_bf16 v[84:87], v[232:235], v[196:199], v[84:87]
	v_mfma_f32_16x16x32_bf16 v[80:83], v[240:243], v[196:199], v[80:83]
	v_mfma_f32_16x16x32_bf16 v[76:79], v[232:235], v[204:207], v[76:79]
	v_mfma_f32_16x16x32_bf16 v[72:75], v[240:243], v[204:207], v[72:75]
	v_mfma_f32_16x16x32_bf16 v[68:71], v[232:235], v[220:223], v[68:71]
	v_mfma_f32_16x16x32_bf16 v[64:67], v[240:243], v[220:223], v[64:67]
	v_mfma_f32_16x16x32_bf16 v[92:95], v[236:239], v[166:169], v[92:95]
	v_mfma_f32_16x16x32_bf16 v[88:91], v[244:247], v[166:169], v[88:91]
	v_mfma_f32_16x16x32_bf16 v[84:87], v[236:239], v[200:203], v[84:87]
	v_mfma_f32_16x16x32_bf16 v[80:83], v[244:247], v[200:203], v[80:83]
	v_mfma_f32_16x16x32_bf16 v[76:79], v[236:239], v[216:219], v[76:79]
	v_mfma_f32_16x16x32_bf16 v[72:75], v[244:247], v[216:219], v[72:75]
	v_mfma_f32_16x16x32_bf16 v[68:71], v[236:239], v[228:231], v[68:71]
	v_mfma_f32_16x16x32_bf16 v[64:67], v[244:247], v[228:231], v[64:67]
	s_barrier
	s_mov_b32 m0, s80
	v_lshl_add_u64 v[176:177], v[224:225], 0, s[18:19]
	ds_read_b128 v[162:165], v194 offset:49152
	ds_read_b128 v[166:169], v194 offset:50176
	ds_read_b128 v[196:199], v194 offset:51200
	ds_read_b128 v[200:203], v194 offset:52224
	ds_read_b128 v[204:207], v194 offset:53248
	ds_read_b128 v[216:219], v194 offset:54272
	ds_read_b128 v[220:223], v194 offset:55296
	ds_read_b128 v[228:231], v194 offset:56320
	global_load_lds_dwordx4 v[176:177], off
	v_lshl_add_u64 v[176:177], v[248:249], 0, s[18:19]
	s_mov_b32 m0, s83
	s_nop 0
	global_load_lds_dwordx4 v[176:177], off
	s_barrier
	s_waitcnt lgkmcnt(0)
	v_mfma_f32_16x16x32_bf16 v[60:63], v[128:131], v[162:165], v[60:63]
	v_mfma_f32_16x16x32_bf16 v[56:59], v[136:139], v[162:165], v[56:59]
	v_mfma_f32_16x16x32_bf16 v[52:55], v[128:131], v[196:199], v[52:55]
	v_mfma_f32_16x16x32_bf16 v[48:51], v[136:139], v[196:199], v[48:51]
	v_mfma_f32_16x16x32_bf16 v[44:47], v[128:131], v[204:207], v[44:47]
	v_mfma_f32_16x16x32_bf16 v[40:43], v[136:139], v[204:207], v[40:43]
	v_mfma_f32_16x16x32_bf16 v[36:39], v[128:131], v[220:223], v[36:39]
	v_mfma_f32_16x16x32_bf16 v[32:35], v[136:139], v[220:223], v[32:35]
	v_mfma_f32_16x16x32_bf16 v[60:63], v[132:135], v[166:169], v[60:63]
	v_mfma_f32_16x16x32_bf16 v[56:59], v[140:143], v[166:169], v[56:59]
	v_mfma_f32_16x16x32_bf16 v[52:55], v[132:135], v[200:203], v[52:55]
	v_mfma_f32_16x16x32_bf16 v[48:51], v[140:143], v[200:203], v[48:51]
	v_mfma_f32_16x16x32_bf16 v[44:47], v[132:135], v[216:219], v[44:47]
	v_mfma_f32_16x16x32_bf16 v[40:43], v[140:143], v[216:219], v[40:43]
	v_mfma_f32_16x16x32_bf16 v[36:39], v[132:135], v[228:231], v[36:39]
	v_mfma_f32_16x16x32_bf16 v[32:35], v[140:143], v[228:231], v[32:35]
	s_barrier
	s_add_u32 s50, s50, 0x40080
	s_addc_u32 s51, s51, 0
	s_add_i32 s27, s37, s76
	s_mov_b32 m0, s27
	s_nop 0
	global_load_lds_dwordx4 v148, s[50:51]
	s_add_i32 m0, s27, 0x2000
	s_nop 0
	global_load_lds_dwordx4 v152, s[50:51]
	s_waitcnt vmcnt(6)
	s_barrier
	v_mfma_f32_16x16x32_bf16 v[28:31], v[232:235], v[162:165], v[28:31]
	v_mfma_f32_16x16x32_bf16 v[24:27], v[240:243], v[162:165], v[24:27]
	v_mfma_f32_16x16x32_bf16 v[20:23], v[232:235], v[196:199], v[20:23]
	v_mfma_f32_16x16x32_bf16 v[16:19], v[240:243], v[196:199], v[16:19]
	v_mfma_f32_16x16x32_bf16 v[12:15], v[232:235], v[204:207], v[12:15]
	v_mfma_f32_16x16x32_bf16 v[8:11], v[240:243], v[204:207], v[8:11]
	v_mfma_f32_16x16x32_bf16 v[4:7], v[232:235], v[220:223], v[4:7]
	v_mfma_f32_16x16x32_bf16 v[0:3], v[240:243], v[220:223], v[0:3]
	v_mfma_f32_16x16x32_bf16 v[28:31], v[236:239], v[166:169], v[28:31]
	v_mfma_f32_16x16x32_bf16 v[24:27], v[244:247], v[166:169], v[24:27]
	v_mfma_f32_16x16x32_bf16 v[20:23], v[236:239], v[200:203], v[20:23]
	v_mfma_f32_16x16x32_bf16 v[16:19], v[244:247], v[200:203], v[16:19]
	v_mfma_f32_16x16x32_bf16 v[12:15], v[236:239], v[216:219], v[12:15]
	v_mfma_f32_16x16x32_bf16 v[8:11], v[244:247], v[216:219], v[8:11]
	v_mfma_f32_16x16x32_bf16 v[4:7], v[236:239], v[228:231], v[4:7]
	v_mfma_f32_16x16x32_bf16 v[0:3], v[244:247], v[228:231], v[0:3]
	s_barrier
	s_add_i32 s36, s36, 2
	s_add_u32 s0, s0, 0x100
	s_addc_u32 s1, s1, 0
	s_add_u32 s34, s34, 0x100
	s_addc_u32 s35, s35, 0
	s_cmp_gt_u32 s36, 13
.LBB0_351:
	s_nop 0
	s_add_u32 s27, s0, 0xfffc0080
	s_addc_u32 s37, s1, -1
	s_add_i32 s47, 0, 0x10000
	ds_read_b128 v[128:131], v192
	ds_read_b128 v[132:135], v192 offset:1024
	ds_read_b128 v[136:139], v192 offset:2048
	ds_read_b128 v[140:143], v192 offset:3072
	s_cmp_eq_u32 s36, 12
	s_cselect_b32 s53, s25, s37
	s_cselect_b32 s52, s30, s27
	s_cselect_b32 s51, s31, s35
	s_cselect_b32 s50, s33, s34
	s_add_i32 m0, s77, 0xc000
	ds_read_b128 v[162:165], v194
	ds_read_b128 v[166:169], v194 offset:1024
	ds_read_b128 v[196:199], v194 offset:2048
	ds_read_b128 v[200:203], v194 offset:3072
	ds_read_b128 v[204:207], v194 offset:4096
	ds_read_b128 v[216:219], v194 offset:5120
	ds_read_b128 v[220:223], v194 offset:6144
	ds_read_b128 v[228:231], v194 offset:7168
	global_load_lds_dwordx4 v156, s[0:1]
	s_add_i32 m0, s77, 0xe000
	s_nop 0
	global_load_lds_dwordx4 v158, s[0:1]
	s_waitcnt lgkmcnt(8)
	s_barrier
	s_waitcnt lgkmcnt(0)
	v_mfma_f32_16x16x32_bf16 v[124:127], v[128:131], v[162:165], v[124:127]
	v_mfma_f32_16x16x32_bf16 v[120:123], v[136:139], v[162:165], v[120:123]
	v_mfma_f32_16x16x32_bf16 v[116:119], v[128:131], v[196:199], v[116:119]
	v_mfma_f32_16x16x32_bf16 v[112:115], v[136:139], v[196:199], v[112:115]
	v_mfma_f32_16x16x32_bf16 v[108:111], v[128:131], v[204:207], v[108:111]
	v_mfma_f32_16x16x32_bf16 v[104:107], v[136:139], v[204:207], v[104:107]
	v_mfma_f32_16x16x32_bf16 v[100:103], v[128:131], v[220:223], v[100:103]
	v_mfma_f32_16x16x32_bf16 v[96:99], v[136:139], v[220:223], v[96:99]
	v_mfma_f32_16x16x32_bf16 v[124:127], v[132:135], v[166:169], v[124:127]
	v_mfma_f32_16x16x32_bf16 v[120:123], v[140:143], v[166:169], v[120:123]
	v_mfma_f32_16x16x32_bf16 v[116:119], v[132:135], v[200:203], v[116:119]
	v_mfma_f32_16x16x32_bf16 v[112:115], v[140:143], v[200:203], v[112:115]
	v_mfma_f32_16x16x32_bf16 v[108:111], v[132:135], v[216:219], v[108:111]
	v_mfma_f32_16x16x32_bf16 v[104:107], v[140:143], v[216:219], v[104:107]
	v_mfma_f32_16x16x32_bf16 v[100:103], v[132:135], v[228:231], v[100:103]
	v_mfma_f32_16x16x32_bf16 v[96:99], v[140:143], v[228:231], v[96:99]
	s_barrier
	s_add_i32 s27, 0, 0x14000
	s_add_i32 s37, s47, s76
	s_mov_b32 m0, s37
	ds_read_b128 v[232:235], v192 offset:16384
	ds_read_b128 v[236:239], v192 offset:17408
	ds_read_b128 v[240:243], v192 offset:18432
	ds_read_b128 v[244:247], v192 offset:19456
	global_load_lds_dwordx4 v148, s[50:51]
	s_add_i32 m0, s37, 0x2000
	s_nop 0
	global_load_lds_dwordx4 v152, s[50:51]
	s_barrier
	s_waitcnt lgkmcnt(0)
	v_mfma_f32_16x16x32_bf16 v[92:95], v[232:235], v[162:165], v[92:95]
	v_mfma_f32_16x16x32_bf16 v[88:91], v[240:243], v[162:165], v[88:91]
	v_mfma_f32_16x16x32_bf16 v[84:87], v[232:235], v[196:199], v[84:87]
	v_mfma_f32_16x16x32_bf16 v[80:83], v[240:243], v[196:199], v[80:83]
	v_mfma_f32_16x16x32_bf16 v[76:79], v[232:235], v[204:207], v[76:79]
	v_mfma_f32_16x16x32_bf16 v[72:75], v[240:243], v[204:207], v[72:75]
	v_mfma_f32_16x16x32_bf16 v[68:71], v[232:235], v[220:223], v[68:71]
	v_mfma_f32_16x16x32_bf16 v[64:67], v[240:243], v[220:223], v[64:67]
	v_mfma_f32_16x16x32_bf16 v[92:95], v[236:239], v[166:169], v[92:95]
	v_mfma_f32_16x16x32_bf16 v[88:91], v[244:247], v[166:169], v[88:91]
	v_mfma_f32_16x16x32_bf16 v[84:87], v[236:239], v[200:203], v[84:87]
	v_mfma_f32_16x16x32_bf16 v[80:83], v[244:247], v[200:203], v[80:83]
	v_mfma_f32_16x16x32_bf16 v[76:79], v[236:239], v[216:219], v[76:79]
	v_mfma_f32_16x16x32_bf16 v[72:75], v[244:247], v[216:219], v[72:75]
	v_mfma_f32_16x16x32_bf16 v[68:71], v[236:239], v[228:231], v[68:71]
	v_mfma_f32_16x16x32_bf16 v[64:67], v[244:247], v[228:231], v[64:67]
	s_barrier
	s_mov_b32 m0, s77
	v_lshl_add_u64 v[224:225], s[52:53], 0, v[146:147]
	ds_read_b128 v[162:165], v194 offset:16384
	ds_read_b128 v[166:169], v194 offset:17408
	ds_read_b128 v[196:199], v194 offset:18432
	ds_read_b128 v[200:203], v194 offset:19456
	ds_read_b128 v[204:207], v194 offset:20480
	ds_read_b128 v[216:219], v194 offset:21504
	ds_read_b128 v[220:223], v194 offset:22528
	ds_read_b128 v[228:231], v194 offset:23552
	global_load_lds_dwordx4 v[224:225], off
	v_lshl_add_u64 v[248:249], s[52:53], 0, v[150:151]
	s_mov_b32 m0, s78
	s_nop 0
	global_load_lds_dwordx4 v[248:249], off
	s_barrier
	s_waitcnt lgkmcnt(0)
	v_mfma_f32_16x16x32_bf16 v[60:63], v[128:131], v[162:165], v[60:63]
	v_mfma_f32_16x16x32_bf16 v[56:59], v[136:139], v[162:165], v[56:59]
	v_mfma_f32_16x16x32_bf16 v[52:55], v[128:131], v[196:199], v[52:55]
	v_mfma_f32_16x16x32_bf16 v[48:51], v[136:139], v[196:199], v[48:51]
	v_mfma_f32_16x16x32_bf16 v[44:47], v[128:131], v[204:207], v[44:47]
	v_mfma_f32_16x16x32_bf16 v[40:43], v[136:139], v[204:207], v[40:43]
	v_mfma_f32_16x16x32_bf16 v[36:39], v[128:131], v[220:223], v[36:39]
	v_mfma_f32_16x16x32_bf16 v[32:35], v[136:139], v[220:223], v[32:35]
	v_mfma_f32_16x16x32_bf16 v[60:63], v[132:135], v[166:169], v[60:63]
	v_mfma_f32_16x16x32_bf16 v[56:59], v[140:143], v[166:169], v[56:59]
	v_mfma_f32_16x16x32_bf16 v[52:55], v[132:135], v[200:203], v[52:55]
	v_mfma_f32_16x16x32_bf16 v[48:51], v[140:143], v[200:203], v[48:51]
	v_mfma_f32_16x16x32_bf16 v[44:47], v[132:135], v[216:219], v[44:47]
	v_mfma_f32_16x16x32_bf16 v[40:43], v[140:143], v[216:219], v[40:43]
	v_mfma_f32_16x16x32_bf16 v[36:39], v[132:135], v[228:231], v[36:39]
	v_mfma_f32_16x16x32_bf16 v[32:35], v[140:143], v[228:231], v[32:35]
	s_barrier
	s_add_u32 s56, s50, 0x40000
	s_addc_u32 s57, s51, 0
	s_add_i32 s27, s27, s76
	s_mov_b32 m0, s27
	s_nop 0
	global_load_lds_dwordx4 v148, s[56:57]
	s_add_i32 m0, s27, 0x2000
	s_nop 0
	global_load_lds_dwordx4 v152, s[56:57]
	s_waitcnt vmcnt(6)
	s_barrier
	v_mfma_f32_16x16x32_bf16 v[28:31], v[232:235], v[162:165], v[28:31]
	v_mfma_f32_16x16x32_bf16 v[24:27], v[240:243], v[162:165], v[24:27]
	v_mfma_f32_16x16x32_bf16 v[20:23], v[232:235], v[196:199], v[20:23]
	v_mfma_f32_16x16x32_bf16 v[16:19], v[240:243], v[196:199], v[16:19]
	v_mfma_f32_16x16x32_bf16 v[12:15], v[232:235], v[204:207], v[12:15]
	v_mfma_f32_16x16x32_bf16 v[8:11], v[240:243], v[204:207], v[8:11]
	v_mfma_f32_16x16x32_bf16 v[4:7], v[232:235], v[220:223], v[4:7]
	v_mfma_f32_16x16x32_bf16 v[0:3], v[240:243], v[220:223], v[0:3]
	v_mfma_f32_16x16x32_bf16 v[28:31], v[236:239], v[166:169], v[28:31]
	v_mfma_f32_16x16x32_bf16 v[24:27], v[244:247], v[166:169], v[24:27]
	v_mfma_f32_16x16x32_bf16 v[20:23], v[236:239], v[200:203], v[20:23]
	v_mfma_f32_16x16x32_bf16 v[16:19], v[244:247], v[200:203], v[16:19]
	v_mfma_f32_16x16x32_bf16 v[12:15], v[236:239], v[216:219], v[12:15]
	v_mfma_f32_16x16x32_bf16 v[8:11], v[244:247], v[216:219], v[8:11]
	v_mfma_f32_16x16x32_bf16 v[4:7], v[236:239], v[228:231], v[4:7]
	v_mfma_f32_16x16x32_bf16 v[0:3], v[244:247], v[228:231], v[0:3]
	s_barrier
	s_add_i32 s27, 0, 0x18000
	ds_read_b128 v[128:131], v192 offset:32768
	ds_read_b128 v[132:135], v192 offset:33792
	ds_read_b128 v[136:139], v192 offset:34816
	ds_read_b128 v[140:143], v192 offset:35840
	s_add_u32 s52, s52, 0x40000
	s_addc_u32 s53, s53, 0
	s_mov_b32 m0, s81
	ds_read_b128 v[162:165], v194 offset:32768
	ds_read_b128 v[166:169], v194 offset:33792
	ds_read_b128 v[196:199], v194 offset:34816
	ds_read_b128 v[200:203], v194 offset:35840
	ds_read_b128 v[204:207], v194 offset:36864
	ds_read_b128 v[216:219], v194 offset:37888
	ds_read_b128 v[220:223], v194 offset:38912
	ds_read_b128 v[228:231], v194 offset:39936
	global_load_lds_dwordx4 v146, s[52:53]
	s_mov_b32 m0, s82
	s_nop 0
	global_load_lds_dwordx4 v150, s[52:53]
	s_waitcnt lgkmcnt(8)
	s_barrier
	s_waitcnt lgkmcnt(0)
	v_mfma_f32_16x16x32_bf16 v[124:127], v[128:131], v[162:165], v[124:127]
	v_mfma_f32_16x16x32_bf16 v[120:123], v[136:139], v[162:165], v[120:123]
	v_mfma_f32_16x16x32_bf16 v[116:119], v[128:131], v[196:199], v[116:119]
	v_mfma_f32_16x16x32_bf16 v[112:115], v[136:139], v[196:199], v[112:115]
	v_mfma_f32_16x16x32_bf16 v[108:111], v[128:131], v[204:207], v[108:111]
	v_mfma_f32_16x16x32_bf16 v[104:107], v[136:139], v[204:207], v[104:107]
	v_mfma_f32_16x16x32_bf16 v[100:103], v[128:131], v[220:223], v[100:103]
	v_mfma_f32_16x16x32_bf16 v[96:99], v[136:139], v[220:223], v[96:99]
	v_mfma_f32_16x16x32_bf16 v[124:127], v[132:135], v[166:169], v[124:127]
	v_mfma_f32_16x16x32_bf16 v[120:123], v[140:143], v[166:169], v[120:123]
	v_mfma_f32_16x16x32_bf16 v[116:119], v[132:135], v[200:203], v[116:119]
	v_mfma_f32_16x16x32_bf16 v[112:115], v[140:143], v[200:203], v[112:115]
	v_mfma_f32_16x16x32_bf16 v[108:111], v[132:135], v[216:219], v[108:111]
	v_mfma_f32_16x16x32_bf16 v[104:107], v[140:143], v[216:219], v[104:107]
	v_mfma_f32_16x16x32_bf16 v[100:103], v[132:135], v[228:231], v[100:103]
	v_mfma_f32_16x16x32_bf16 v[96:99], v[140:143], v[228:231], v[96:99]
	s_barrier
	s_add_i32 s37, 0, 0x1c000
	s_add_i32 s27, s27, s76
	s_add_u32 s56, s50, s18
	s_addc_u32 s57, s51, s19
	s_mov_b32 m0, s27
	ds_read_b128 v[232:235], v192 offset:49152
	ds_read_b128 v[236:239], v192 offset:50176
	ds_read_b128 v[240:243], v192 offset:51200
	ds_read_b128 v[244:247], v192 offset:52224
	global_load_lds_dwordx4 v148, s[56:57]
	s_add_u32 s56, s50, s18
	s_addc_u32 s57, s51, s19
	s_add_i32 m0, s27, 0x2000
	s_nop 0
	global_load_lds_dwordx4 v152, s[56:57]
	s_barrier
	s_waitcnt lgkmcnt(0)
	v_mfma_f32_16x16x32_bf16 v[92:95], v[232:235], v[162:165], v[92:95]
	v_mfma_f32_16x16x32_bf16 v[88:91], v[240:243], v[162:165], v[88:91]
	v_mfma_f32_16x16x32_bf16 v[84:87], v[232:235], v[196:199], v[84:87]
	v_mfma_f32_16x16x32_bf16 v[80:83], v[240:243], v[196:199], v[80:83]
	v_mfma_f32_16x16x32_bf16 v[76:79], v[232:235], v[204:207], v[76:79]
	v_mfma_f32_16x16x32_bf16 v[72:75], v[240:243], v[204:207], v[72:75]
	v_mfma_f32_16x16x32_bf16 v[68:71], v[232:235], v[220:223], v[68:71]
	v_mfma_f32_16x16x32_bf16 v[64:67], v[240:243], v[220:223], v[64:67]
	v_mfma_f32_16x16x32_bf16 v[92:95], v[236:239], v[166:169], v[92:95]
	v_mfma_f32_16x16x32_bf16 v[88:91], v[244:247], v[166:169], v[88:91]
	v_mfma_f32_16x16x32_bf16 v[84:87], v[236:239], v[200:203], v[84:87]
	v_mfma_f32_16x16x32_bf16 v[80:83], v[244:247], v[200:203], v[80:83]
	v_mfma_f32_16x16x32_bf16 v[76:79], v[236:239], v[216:219], v[76:79]
	v_mfma_f32_16x16x32_bf16 v[72:75], v[244:247], v[216:219], v[72:75]
	v_mfma_f32_16x16x32_bf16 v[68:71], v[236:239], v[228:231], v[68:71]
	v_mfma_f32_16x16x32_bf16 v[64:67], v[244:247], v[228:231], v[64:67]
	s_barrier
	s_mov_b32 m0, s80
	v_lshl_add_u64 v[176:177], v[224:225], 0, s[18:19]
	ds_read_b128 v[162:165], v194 offset:49152
	ds_read_b128 v[166:169], v194 offset:50176
	ds_read_b128 v[196:199], v194 offset:51200
	ds_read_b128 v[200:203], v194 offset:52224
	ds_read_b128 v[204:207], v194 offset:53248
	ds_read_b128 v[216:219], v194 offset:54272
	ds_read_b128 v[220:223], v194 offset:55296
	ds_read_b128 v[228:231], v194 offset:56320
	global_load_lds_dwordx4 v[176:177], off
	v_lshl_add_u64 v[176:177], v[248:249], 0, s[18:19]
	s_mov_b32 m0, s83
	s_nop 0
	global_load_lds_dwordx4 v[176:177], off
	s_barrier
	s_waitcnt lgkmcnt(0)
	v_mfma_f32_16x16x32_bf16 v[60:63], v[128:131], v[162:165], v[60:63]
	v_mfma_f32_16x16x32_bf16 v[56:59], v[136:139], v[162:165], v[56:59]
	v_mfma_f32_16x16x32_bf16 v[52:55], v[128:131], v[196:199], v[52:55]
	v_mfma_f32_16x16x32_bf16 v[48:51], v[136:139], v[196:199], v[48:51]
	v_mfma_f32_16x16x32_bf16 v[44:47], v[128:131], v[204:207], v[44:47]
	v_mfma_f32_16x16x32_bf16 v[40:43], v[136:139], v[204:207], v[40:43]
	v_mfma_f32_16x16x32_bf16 v[36:39], v[128:131], v[220:223], v[36:39]
	v_mfma_f32_16x16x32_bf16 v[32:35], v[136:139], v[220:223], v[32:35]
	v_mfma_f32_16x16x32_bf16 v[60:63], v[132:135], v[166:169], v[60:63]
	v_mfma_f32_16x16x32_bf16 v[56:59], v[140:143], v[166:169], v[56:59]
	v_mfma_f32_16x16x32_bf16 v[52:55], v[132:135], v[200:203], v[52:55]
	v_mfma_f32_16x16x32_bf16 v[48:51], v[140:143], v[200:203], v[48:51]
	v_mfma_f32_16x16x32_bf16 v[44:47], v[132:135], v[216:219], v[44:47]
	v_mfma_f32_16x16x32_bf16 v[40:43], v[140:143], v[216:219], v[40:43]
	v_mfma_f32_16x16x32_bf16 v[36:39], v[132:135], v[228:231], v[36:39]
	v_mfma_f32_16x16x32_bf16 v[32:35], v[140:143], v[228:231], v[32:35]
	s_barrier
	s_add_u32 s50, s50, 0x40080
	s_addc_u32 s51, s51, 0
	s_add_i32 s27, s37, s76
	s_mov_b32 m0, s27
	s_nop 0
	global_load_lds_dwordx4 v148, s[50:51]
	s_add_i32 m0, s27, 0x2000
	s_nop 0
	global_load_lds_dwordx4 v152, s[50:51]
	s_waitcnt vmcnt(6)
	s_barrier
	v_mfma_f32_16x16x32_bf16 v[28:31], v[232:235], v[162:165], v[28:31]
	v_mfma_f32_16x16x32_bf16 v[24:27], v[240:243], v[162:165], v[24:27]
	v_mfma_f32_16x16x32_bf16 v[20:23], v[232:235], v[196:199], v[20:23]
	v_mfma_f32_16x16x32_bf16 v[16:19], v[240:243], v[196:199], v[16:19]
	v_mfma_f32_16x16x32_bf16 v[12:15], v[232:235], v[204:207], v[12:15]
	v_mfma_f32_16x16x32_bf16 v[8:11], v[240:243], v[204:207], v[8:11]
	v_mfma_f32_16x16x32_bf16 v[4:7], v[232:235], v[220:223], v[4:7]
	v_mfma_f32_16x16x32_bf16 v[0:3], v[240:243], v[220:223], v[0:3]
	v_mfma_f32_16x16x32_bf16 v[28:31], v[236:239], v[166:169], v[28:31]
	v_mfma_f32_16x16x32_bf16 v[24:27], v[244:247], v[166:169], v[24:27]
	v_mfma_f32_16x16x32_bf16 v[20:23], v[236:239], v[200:203], v[20:23]
	v_mfma_f32_16x16x32_bf16 v[16:19], v[244:247], v[200:203], v[16:19]
	v_mfma_f32_16x16x32_bf16 v[12:15], v[236:239], v[216:219], v[12:15]
	v_mfma_f32_16x16x32_bf16 v[8:11], v[244:247], v[216:219], v[8:11]
	v_mfma_f32_16x16x32_bf16 v[4:7], v[236:239], v[228:231], v[4:7]
	v_mfma_f32_16x16x32_bf16 v[0:3], v[244:247], v[228:231], v[0:3]
	s_barrier
	s_add_i32 s36, s36, 2
	s_add_u32 s0, s0, 0x100
	s_addc_u32 s1, s1, 0
	s_add_u32 s34, s34, 0x100
	s_addc_u32 s35, s35, 0
	s_cmp_gt_u32 s36, 13
	s_cbranch_scc0 .LBB0_351
	s_lshl_b32 s0, s11, 8
	s_or_b32 s50, s0, s79
	s_ashr_i32 s51, s50, 31
	v_lshl_add_u64 v[140:141], s[50:51], 3, v[154:155]
	global_load_dwordx4 v[128:131], v[140:141], off offset:48
	global_load_dwordx4 v[132:135], v[140:141], off offset:32
	global_load_dwordx4 v[136:139], v[140:141], off offset:16
	global_load_dwordx4 v[162:165], v[140:141], off
	s_mov_b32 s34, 0x35800000
	s_mov_b32 s0, 0x358637bd
	v_mov_b64_e32 v[168:169], s[0:1]
	s_mov_b32 s30, 0x45800000
	s_cmp_lt_u32 s10, 2
	s_waitcnt vmcnt(0)
	v_ffbh_u32_e32 v142, v165
	v_min_u32_e32 v161, 32, v142
	v_lshlrev_b64 v[142:143], v161, v[164:165]
	v_min_u32_e32 v142, 1, v142
	v_or_b32_e32 v142, v143, v142
	v_cvt_f32_u32_e32 v142, v142
	v_sub_u32_e32 v143, 32, v161
	v_ldexp_f32 v143, v142, v143
	v_ffbh_u32_e32 v142, v163
	v_min_u32_e32 v142, 32, v142
	v_lshlrev_b64 v[162:163], v142, v[162:163]
	v_min_u32_e32 v161, 1, v162
	v_or_b32_e32 v161, v163, v161
	v_cvt_f32_u32_e32 v161, v161
	v_sub_u32_e32 v142, 32, v142
	v_ldexp_f32 v142, v161, v142
	v_pk_mul_f32 v[142:143], v[142:143], s[34:35] op_sel_hi:[1,0]
	s_nop 0
	v_pk_fma_f32 v[142:143], v[142:143], s[2:3], v[168:169] op_sel_hi:[1,0,0]
	s_nop 0
	v_mul_f32_e32 v161, 0x4b800000, v142
	v_cmp_gt_f32_e64 s[0:1], s89, v142
	v_cmp_gt_f32_e32 vcc, s89, v143
	s_nop 0
	v_cndmask_b32_e64 v142, v142, v161, s[0:1]
	v_mul_f32_e32 v161, 0x4b800000, v143
	v_cndmask_b32_e32 v143, v143, v161, vcc
	v_rsq_f32_e32 v142, v142
	v_rsq_f32_e32 v143, v143
	s_nop 0
	v_pk_mul_f32 v[162:163], v[142:143], s[30:31] op_sel_hi:[1,0]
	s_nop 0
	v_cndmask_b32_e64 v166, v142, v162, s[0:1]
	v_ffbh_u32_e32 v142, v139
	v_min_u32_e32 v142, 32, v142
	v_lshlrev_b64 v[138:139], v142, v[138:139]
	v_min_u32_e32 v138, 1, v138
	v_or_b32_e32 v138, v139, v138
	v_cvt_f32_u32_e32 v138, v138
	v_sub_u32_e32 v139, 32, v142
	v_cndmask_b32_e32 v167, v143, v163, vcc
	v_pk_mul_f32 v[60:61], v[60:61], v[166:167]
	v_ldexp_f32 v139, v138, v139
	v_ffbh_u32_e32 v138, v137
	v_min_u32_e32 v138, 32, v138
	v_lshlrev_b64 v[136:137], v138, v[136:137]
	v_min_u32_e32 v136, 1, v136
	v_or_b32_e32 v136, v137, v136
	v_cvt_f32_u32_e32 v136, v136
	v_sub_u32_e32 v137, 32, v138
	v_pk_mul_f32 v[52:53], v[52:53], v[166:167]
	v_pk_mul_f32 v[44:45], v[44:45], v[166:167]
	v_ldexp_f32 v138, v136, v137
	v_pk_mul_f32 v[136:137], v[138:139], s[34:35] op_sel_hi:[1,0]
	v_pk_mul_f32 v[36:37], v[36:37], v[166:167]
	v_pk_fma_f32 v[136:137], v[136:137], s[2:3], v[168:169] op_sel_hi:[1,0,0]
	s_nop 0
	v_mul_f32_e32 v138, 0x4b800000, v136
	v_cmp_gt_f32_e64 s[0:1], s89, v136
	v_cmp_gt_f32_e32 vcc, s89, v137
	s_nop 0
	v_cndmask_b32_e64 v136, v136, v138, s[0:1]
	v_mul_f32_e32 v138, 0x4b800000, v137
	v_cndmask_b32_e32 v137, v137, v138, vcc
	v_rsq_f32_e32 v136, v136
	v_rsq_f32_e32 v137, v137
	s_nop 0
	v_pk_mul_f32 v[138:139], v[136:137], s[30:31] op_sel_hi:[1,0]
	s_nop 0
	v_cndmask_b32_e64 v162, v136, v138, s[0:1]
	v_ffbh_u32_e32 v136, v135
	v_min_u32_e32 v136, 32, v136
	v_lshlrev_b64 v[134:135], v136, v[134:135]
	v_min_u32_e32 v134, 1, v134
	v_or_b32_e32 v134, v135, v134
	v_cvt_f32_u32_e32 v134, v134
	v_sub_u32_e32 v135, 32, v136
	v_cndmask_b32_e32 v163, v137, v139, vcc
	v_ldexp_f32 v135, v134, v135
	v_ffbh_u32_e32 v134, v133
	v_min_u32_e32 v134, 32, v134
	v_lshlrev_b64 v[132:133], v134, v[132:133]
	v_min_u32_e32 v132, 1, v132
	v_or_b32_e32 v132, v133, v132
	v_cvt_f32_u32_e32 v132, v132
	v_sub_u32_e32 v133, 32, v134
	v_ldexp_f32 v134, v132, v133
	v_pk_mul_f32 v[132:133], v[134:135], s[34:35] op_sel_hi:[1,0]
	s_nop 0
	v_pk_fma_f32 v[132:133], v[132:133], s[2:3], v[168:169] op_sel_hi:[1,0,0]
	s_nop 0
	v_mul_f32_e32 v134, 0x4b800000, v132
	v_cmp_gt_f32_e64 s[0:1], s89, v132
	v_cmp_gt_f32_e32 vcc, s89, v133
	s_nop 0
	v_cndmask_b32_e64 v132, v132, v134, s[0:1]
	v_mul_f32_e32 v134, 0x4b800000, v133
	v_cndmask_b32_e32 v133, v133, v134, vcc
	v_rsq_f32_e32 v132, v132
	v_rsq_f32_e32 v133, v133
	s_nop 0
	v_pk_mul_f32 v[134:135], v[132:133], s[30:31] op_sel_hi:[1,0]
	s_nop 0
	v_cndmask_b32_e64 v188, v132, v134, s[0:1]
	v_ffbh_u32_e32 v132, v131
	v_min_u32_e32 v132, 32, v132
	v_lshlrev_b64 v[130:131], v132, v[130:131]
	v_min_u32_e32 v130, 1, v130
	v_or_b32_e32 v130, v131, v130
	v_cvt_f32_u32_e32 v130, v130
	v_sub_u32_e32 v131, 32, v132
	v_cndmask_b32_e32 v189, v133, v135, vcc
	v_pk_mul_f32 v[56:57], v[56:57], v[188:189]
	v_ldexp_f32 v131, v130, v131
	v_ffbh_u32_e32 v130, v129
	v_min_u32_e32 v130, 32, v130
	v_lshlrev_b64 v[128:129], v130, v[128:129]
	v_min_u32_e32 v128, 1, v128
	v_or_b32_e32 v128, v129, v128
	v_cvt_f32_u32_e32 v128, v128
	v_sub_u32_e32 v129, 32, v130
	v_pk_mul_f32 v[48:49], v[48:49], v[188:189]
	v_pk_mul_f32 v[40:41], v[40:41], v[188:189]
	v_ldexp_f32 v130, v128, v129
	v_pk_mul_f32 v[128:129], v[130:131], s[34:35] op_sel_hi:[1,0]
	v_pk_mul_f32 v[32:33], v[32:33], v[188:189]
	v_pk_fma_f32 v[128:129], v[128:129], s[2:3], v[168:169] op_sel_hi:[1,0,0]
	s_nop 0
	v_mul_f32_e32 v130, 0x4b800000, v128
	v_cmp_gt_f32_e64 s[0:1], s89, v128
	v_cmp_gt_f32_e32 vcc, s89, v129
	s_nop 0
	v_cndmask_b32_e64 v128, v128, v130, s[0:1]
	v_mul_f32_e32 v130, 0x4b800000, v129
	v_cndmask_b32_e32 v129, v129, v130, vcc
	v_rsq_f32_e32 v128, v128
	v_rsq_f32_e32 v129, v129
	s_nop 0
	v_pk_mul_f32 v[130:131], v[128:129], s[30:31] op_sel_hi:[1,0]
	s_nop 0
	v_cndmask_b32_e32 v165, v129, v131, vcc
	v_cndmask_b32_e64 v164, v128, v130, s[0:1]
	global_load_dwordx4 v[128:131], v[140:141], off offset:1072
	global_load_dwordx4 v[132:135], v[140:141], off offset:1056
	global_load_dwordx4 v[136:139], v[140:141], off offset:1040
	s_nop 0
	global_load_dwordx4 v[140:143], v[140:141], off offset:1024
	s_waitcnt vmcnt(0)
	v_ffbh_u32_e32 v161, v143
	v_min_u32_e32 v161, 32, v161
	v_lshlrev_b64 v[142:143], v161, v[142:143]
	v_min_u32_e32 v142, 1, v142
	v_or_b32_e32 v142, v143, v142
	v_cvt_f32_u32_e32 v142, v142
	v_sub_u32_e32 v143, 32, v161
	v_ldexp_f32 v143, v142, v143
	v_ffbh_u32_e32 v142, v141
	v_min_u32_e32 v142, 32, v142
	v_lshlrev_b64 v[140:141], v142, v[140:141]
	v_min_u32_e32 v140, 1, v140
	v_or_b32_e32 v140, v141, v140
	v_cvt_f32_u32_e32 v140, v140
	v_sub_u32_e32 v141, 32, v142
	v_ldexp_f32 v142, v140, v141
	v_pk_mul_f32 v[140:141], v[142:143], s[34:35] op_sel_hi:[1,0]
	s_nop 0
	v_pk_fma_f32 v[140:141], v[140:141], s[2:3], v[168:169] op_sel_hi:[1,0,0]
	s_nop 0
	v_mul_f32_e32 v142, 0x4b800000, v140
	v_cmp_gt_f32_e64 s[0:1], s89, v140
	v_cmp_gt_f32_e32 vcc, s89, v141
	s_nop 0
	v_cndmask_b32_e64 v140, v140, v142, s[0:1]
	v_mul_f32_e32 v142, 0x4b800000, v141
	v_cndmask_b32_e32 v141, v141, v142, vcc
	v_rsq_f32_e32 v140, v140
	v_rsq_f32_e32 v141, v141
	s_nop 0
	v_pk_mul_f32 v[142:143], v[140:141], s[30:31] op_sel_hi:[1,0]
	s_nop 0
	v_cndmask_b32_e64 v142, v140, v142, s[0:1]
	v_ffbh_u32_e32 v140, v139
	v_min_u32_e32 v140, 32, v140
	v_lshlrev_b64 v[138:139], v140, v[138:139]
	v_min_u32_e32 v138, 1, v138
	v_or_b32_e32 v138, v139, v138
	v_cvt_f32_u32_e32 v138, v138
	v_sub_u32_e32 v139, 32, v140
	v_cndmask_b32_e32 v143, v141, v143, vcc
	v_pk_mul_f32 v[140:141], v[124:125], v[166:167]
	v_ldexp_f32 v139, v138, v139
	v_ffbh_u32_e32 v138, v137
	v_min_u32_e32 v138, 32, v138
	v_lshlrev_b64 v[136:137], v138, v[136:137]
	v_min_u32_e32 v136, 1, v136
	v_or_b32_e32 v136, v137, v136
	v_cvt_f32_u32_e32 v136, v136
	v_sub_u32_e32 v137, 32, v138
	v_pk_mul_f32 v[28:29], v[28:29], v[142:143]
	v_pk_mul_f32 v[20:21], v[20:21], v[142:143]
	v_ldexp_f32 v138, v136, v137
	v_pk_mul_f32 v[136:137], v[138:139], s[34:35] op_sel_hi:[1,0]
	v_pk_mul_f32 v[12:13], v[12:13], v[142:143]
	v_pk_fma_f32 v[136:137], v[136:137], s[2:3], v[168:169] op_sel_hi:[1,0,0]
	v_pk_mul_f32 v[4:5], v[4:5], v[142:143]
	v_mul_f32_e32 v138, 0x4b800000, v136
	v_cmp_gt_f32_e64 s[0:1], s89, v136
	v_cmp_gt_f32_e32 vcc, s89, v137
	s_nop 0
	v_cndmask_b32_e64 v136, v136, v138, s[0:1]
	v_mul_f32_e32 v138, 0x4b800000, v137
	v_cndmask_b32_e32 v137, v137, v138, vcc
	v_rsq_f32_e32 v136, v136
	v_rsq_f32_e32 v137, v137
	s_nop 0
	v_pk_mul_f32 v[138:139], v[136:137], s[30:31] op_sel_hi:[1,0]
	s_nop 0
	v_cndmask_b32_e64 v136, v136, v138, s[0:1]
	v_ffbh_u32_e32 v138, v135
	v_min_u32_e32 v138, 32, v138
	v_lshlrev_b64 v[134:135], v138, v[134:135]
	v_min_u32_e32 v134, 1, v134
	v_or_b32_e32 v134, v135, v134
	v_cvt_f32_u32_e32 v134, v134
	v_sub_u32_e32 v135, 32, v138
	v_cndmask_b32_e32 v137, v137, v139, vcc
	v_pk_mul_f32 v[138:139], v[120:121], v[188:189]
	v_ldexp_f32 v135, v134, v135
	v_ffbh_u32_e32 v134, v133
	v_min_u32_e32 v134, 32, v134
	v_lshlrev_b64 v[132:133], v134, v[132:133]
	v_min_u32_e32 v132, 1, v132
	v_or_b32_e32 v132, v133, v132
	v_cvt_f32_u32_e32 v132, v132
	v_sub_u32_e32 v133, 32, v134
	v_pk_mul_f32 v[120:121], v[84:85], v[142:143]
	v_ldexp_f32 v134, v132, v133
	v_pk_mul_f32 v[132:133], v[134:135], s[34:35] op_sel_hi:[1,0]
	s_nop 0
	v_pk_fma_f32 v[132:133], v[132:133], s[2:3], v[168:169] op_sel_hi:[1,0,0]
	s_nop 0
	v_mul_f32_e32 v134, 0x4b800000, v132
	v_cmp_gt_f32_e64 s[0:1], s89, v132
	v_cmp_gt_f32_e32 vcc, s89, v133
	s_nop 0
	v_cndmask_b32_e64 v132, v132, v134, s[0:1]
	v_mul_f32_e32 v134, 0x4b800000, v133
	v_cndmask_b32_e32 v133, v133, v134, vcc
	v_rsq_f32_e32 v132, v132
	v_rsq_f32_e32 v133, v133
	s_nop 0
	v_pk_mul_f32 v[134:135], v[132:133], s[30:31] op_sel_hi:[1,0]
	s_nop 0
	v_cndmask_b32_e64 v176, v132, v134, s[0:1]
	v_ffbh_u32_e32 v132, v131
	v_min_u32_e32 v132, 32, v132
	v_lshlrev_b64 v[130:131], v132, v[130:131]
	v_min_u32_e32 v130, 1, v130
	v_or_b32_e32 v130, v131, v130
	v_cvt_f32_u32_e32 v130, v130
	v_sub_u32_e32 v131, 32, v132
	v_cndmask_b32_e32 v177, v133, v135, vcc
	v_pk_mul_f32 v[124:125], v[88:89], v[176:177]
	v_ldexp_f32 v131, v130, v131
	v_ffbh_u32_e32 v130, v129
	v_min_u32_e32 v130, 32, v130
	v_lshlrev_b64 v[128:129], v130, v[128:129]
	v_min_u32_e32 v128, 1, v128
	v_or_b32_e32 v128, v129, v128
	v_cvt_f32_u32_e32 v128, v128
	v_sub_u32_e32 v129, 32, v130
	v_pk_mul_f32 v[134:135], v[116:117], v[166:167]
	v_pk_mul_f32 v[132:133], v[112:113], v[188:189]
	v_ldexp_f32 v130, v128, v129
	v_pk_mul_f32 v[128:129], v[130:131], s[34:35] op_sel_hi:[1,0]
	v_pk_mul_f32 v[116:117], v[80:81], v[176:177]
	v_pk_fma_f32 v[128:129], v[128:129], s[2:3], v[168:169] op_sel_hi:[1,0,0]
	v_pk_mul_f32 v[88:89], v[104:105], v[188:189]
	v_mul_f32_e32 v130, 0x4b800000, v128
	v_cmp_gt_f32_e64 s[0:1], s89, v128
	v_cmp_gt_f32_e32 vcc, s89, v129
	v_pk_mul_f32 v[112:113], v[76:77], v[142:143]
	v_cndmask_b32_e64 v128, v128, v130, s[0:1]
	v_mul_f32_e32 v130, 0x4b800000, v129
	v_cndmask_b32_e32 v129, v129, v130, vcc
	v_rsq_f32_e32 v128, v128
	v_rsq_f32_e32 v129, v129
	v_pk_mul_f32 v[76:77], v[100:101], v[166:167]
	v_pk_mul_f32 v[104:105], v[68:69], v[142:143]
	v_pk_mul_f32 v[24:25], v[24:25], v[176:177]
	v_pk_mul_f32 v[130:131], v[128:129], s[30:31] op_sel_hi:[1,0]
	v_pk_mul_f32 v[16:17], v[16:17], v[176:177]
	v_cndmask_b32_e32 v129, v129, v131, vcc
	v_cndmask_b32_e64 v128, v128, v130, s[0:1]
	s_mov_b64 s[0:1], -1
	v_pk_mul_f32 v[130:131], v[92:93], v[142:143]
	v_pk_mul_f32 v[92:93], v[108:109], v[166:167]
	v_pk_mul_f32 v[108:109], v[72:73], v[176:177]
	v_pk_mul_f32 v[72:73], v[96:97], v[188:189]
	v_pk_mul_f32 v[96:97], v[64:65], v[176:177]
	v_pk_mul_f32 v[8:9], v[8:9], v[176:177]
	v_pk_mul_f32 v[0:1], v[0:1], v[176:177]
	s_cbranch_scc1 .LBB0_354
	v_lshl_add_u32 v68, s10, 8, v193
	v_ashrrev_i32_e32 v69, 31, v68
	v_pk_mul_f32 v[64:65], v[126:127], v[162:163]
	v_cvt_pk_bf16_f32 v80, v140, v141
	s_lshl_b64 s[0:1], s[50:51], 1
	v_cvt_pk_bf16_f32 v81, v64, v65
	v_lshlrev_b64 v[64:65], 13, v[68:69]
	v_lshl_add_u64 v[64:65], s[44:45], 0, v[64:65]
	v_lshl_add_u64 v[64:65], v[64:65], 0, s[0:1]
	v_lshl_add_u64 v[64:65], v[64:65], 0, v[144:145]
	v_mov_b32_e32 v161, v145
	v_lshl_add_u64 v[64:65], v[64:65], 0, v[160:161]
	global_store_dwordx2 v[64:65], v[80:81], off
	v_pk_mul_f32 v[80:81], v[122:123], v[164:165]
	v_cvt_pk_bf16_f32 v84, v138, v139
	s_nop 0
	v_cvt_pk_bf16_f32 v85, v80, v81
	v_pk_mul_f32 v[80:81], v[94:95], v[136:137]
	global_store_dwordx2 v[64:65], v[84:85], off offset:16
	v_cvt_pk_bf16_f32 v84, v130, v131
	v_cvt_pk_bf16_f32 v85, v80, v81
	v_pk_mul_f32 v[80:81], v[90:91], v[128:129]
	global_store_dwordx2 v[64:65], v[84:85], off offset:256
	v_cvt_pk_bf16_f32 v84, v124, v125
	v_cvt_pk_bf16_f32 v85, v80, v81
	v_or_b32_e32 v80, 16, v68
	v_ashrrev_i32_e32 v81, 31, v80
	v_lshlrev_b64 v[80:81], 13, v[80:81]
	v_lshl_add_u64 v[80:81], s[44:45], 0, v[80:81]
	v_lshl_add_u64 v[80:81], v[80:81], 0, s[0:1]
	v_lshl_add_u64 v[80:81], v[80:81], 0, v[144:145]
	global_store_dwordx2 v[64:65], v[84:85], off offset:272
	v_pk_mul_f32 v[84:85], v[118:119], v[162:163]
	v_cvt_pk_bf16_f32 v100, v134, v135
	v_lshl_add_u64 v[80:81], v[80:81], 0, v[160:161]
	v_cvt_pk_bf16_f32 v101, v84, v85
	global_store_dwordx2 v[80:81], v[100:101], off
	v_pk_mul_f32 v[84:85], v[114:115], v[164:165]
	v_cvt_pk_bf16_f32 v100, v132, v133
	s_nop 0
	v_cvt_pk_bf16_f32 v101, v84, v85
	global_store_dwordx2 v[80:81], v[100:101], off offset:16
	v_pk_mul_f32 v[84:85], v[86:87], v[136:137]
	v_cvt_pk_bf16_f32 v100, v120, v121
	s_nop 0
	v_cvt_pk_bf16_f32 v101, v84, v85
	global_store_dwordx2 v[80:81], v[100:101], off offset:256
	v_pk_mul_f32 v[84:85], v[82:83], v[128:129]
	v_cvt_pk_bf16_f32 v100, v116, v117
	s_nop 0
	v_cvt_pk_bf16_f32 v101, v84, v85
	global_store_dwordx2 v[80:81], v[100:101], off offset:272
	v_or_b32_e32 v80, 32, v68
	v_ashrrev_i32_e32 v81, 31, v80
	v_lshlrev_b64 v[80:81], 13, v[80:81]
	v_lshl_add_u64 v[80:81], s[44:45], 0, v[80:81]
	v_or_b32_e32 v68, 48, v68
	v_lshl_add_u64 v[80:81], v[80:81], 0, s[0:1]
	v_ashrrev_i32_e32 v69, 31, v68
	v_pk_mul_f32 v[84:85], v[110:111], v[162:163]
	v_lshl_add_u64 v[80:81], v[80:81], 0, v[144:145]
	v_lshlrev_b64 v[68:69], 13, v[68:69]
	v_cvt_pk_bf16_f32 v100, v92, v93
	v_cvt_pk_bf16_f32 v101, v84, v85
	v_lshl_add_u64 v[80:81], v[80:81], 0, v[160:161]
	v_pk_mul_f32 v[84:85], v[106:107], v[164:165]
	v_lshl_add_u64 v[68:69], s[44:45], 0, v[68:69]
	global_store_dwordx2 v[80:81], v[100:101], off
	v_cvt_pk_bf16_f32 v100, v88, v89
	v_cvt_pk_bf16_f32 v101, v84, v85
	v_pk_mul_f32 v[84:85], v[78:79], v[136:137]
	v_lshl_add_u64 v[68:69], v[68:69], 0, s[0:1]
	global_store_dwordx2 v[80:81], v[100:101], off offset:16
	v_cvt_pk_bf16_f32 v100, v112, v113
	v_cvt_pk_bf16_f32 v101, v84, v85
	v_pk_mul_f32 v[84:85], v[74:75], v[128:129]
	v_lshl_add_u64 v[68:69], v[68:69], 0, v[144:145]
	global_store_dwordx2 v[80:81], v[100:101], off offset:256
	v_cvt_pk_bf16_f32 v100, v108, v109
	v_cvt_pk_bf16_f32 v101, v84, v85
	global_store_dwordx2 v[80:81], v[100:101], off offset:272
	v_cvt_pk_bf16_f32 v84, v76, v77
	v_lshl_add_u64 v[68:69], v[68:69], 0, v[160:161]
	v_pk_mul_f32 v[80:81], v[102:103], v[162:163]
	s_mov_b64 s[0:1], 0x100000
	v_cvt_pk_bf16_f32 v85, v80, v81
	global_store_dwordx2 v[68:69], v[84:85], off
	v_cvt_pk_bf16_f32 v84, v72, v73
	v_pk_mul_f32 v[80:81], v[98:99], v[164:165]
	s_nop 0
	v_cvt_pk_bf16_f32 v85, v80, v81
	global_store_dwordx2 v[68:69], v[84:85], off offset:16
	v_cvt_pk_bf16_f32 v84, v104, v105
	v_pk_mul_f32 v[80:81], v[70:71], v[136:137]
	s_nop 0
	v_cvt_pk_bf16_f32 v85, v80, v81
	global_store_dwordx2 v[68:69], v[84:85], off offset:256
	v_cvt_pk_bf16_f32 v84, v96, v97
	v_pk_mul_f32 v[80:81], v[66:67], v[128:129]
	s_nop 0
	v_cvt_pk_bf16_f32 v85, v80, v81
	global_store_dwordx2 v[68:69], v[84:85], off offset:272
	v_add_co_u32_e32 v84, vcc, s29, v64
	v_pk_mul_f32 v[68:69], v[62:63], v[162:163]
	s_nop 0
	v_addc_co_u32_e32 v85, vcc, 0, v65, vcc
	v_cvt_pk_bf16_f32 v80, v60, v61
	v_cvt_pk_bf16_f32 v81, v68, v69
	v_lshl_add_u64 v[68:69], v[64:65], 0, s[0:1]
	global_store_dwordx2 v[84:85], v[80:81], off
	v_cvt_pk_bf16_f32 v84, v56, v57
	v_pk_mul_f32 v[80:81], v[58:59], v[164:165]
	s_mov_b64 s[0:1], 0x120000
	v_cvt_pk_bf16_f32 v85, v80, v81
	global_store_dwordx2 v[68:69], v[84:85], off offset:16
	v_cvt_pk_bf16_f32 v84, v28, v29
	v_pk_mul_f32 v[80:81], v[30:31], v[136:137]
	s_nop 0
	v_cvt_pk_bf16_f32 v85, v80, v81
	global_store_dwordx2 v[68:69], v[84:85], off offset:256
	v_cvt_pk_bf16_f32 v84, v24, v25
	v_pk_mul_f32 v[80:81], v[26:27], v[128:129]
	s_nop 0
	v_cvt_pk_bf16_f32 v85, v80, v81
	global_store_dwordx2 v[68:69], v[84:85], off offset:272
	v_add_co_u32_e32 v84, vcc, s49, v64
	v_pk_mul_f32 v[68:69], v[54:55], v[162:163]
	v_cvt_pk_bf16_f32 v80, v52, v53
	s_nop 0
	v_addc_co_u32_e32 v85, vcc, 0, v65, vcc
	v_cvt_pk_bf16_f32 v81, v68, v69
	v_lshl_add_u64 v[68:69], v[64:65], 0, s[0:1]
	global_store_dwordx2 v[84:85], v[80:81], off
	v_pk_mul_f32 v[80:81], v[50:51], v[164:165]
	v_cvt_pk_bf16_f32 v84, v48, v49
	s_mov_b64 s[0:1], 0x140000
	v_cvt_pk_bf16_f32 v85, v80, v81
	global_store_dwordx2 v[68:69], v[84:85], off offset:16
	v_pk_mul_f32 v[80:81], v[22:23], v[136:137]
	v_cvt_pk_bf16_f32 v84, v20, v21
	s_nop 0
	v_cvt_pk_bf16_f32 v85, v80, v81
	global_store_dwordx2 v[68:69], v[84:85], off offset:256
	v_pk_mul_f32 v[80:81], v[18:19], v[128:129]
	v_cvt_pk_bf16_f32 v84, v16, v17
	s_nop 0
	v_cvt_pk_bf16_f32 v85, v80, v81
	global_store_dwordx2 v[68:69], v[84:85], off offset:272
	v_pk_mul_f32 v[68:69], v[46:47], v[162:163]
	v_cvt_pk_bf16_f32 v80, v44, v45
	s_nop 0
	v_cvt_pk_bf16_f32 v81, v68, v69
	v_lshl_add_u64 v[68:69], v[64:65], 0, s[0:1]
	s_mov_b32 s0, 0x140000
	v_add_co_u32_e32 v84, vcc, s0, v64
	s_mov_b64 s[0:1], 0x160000
	s_nop 0
	v_addc_co_u32_e32 v85, vcc, 0, v65, vcc
	global_store_dwordx2 v[84:85], v[80:81], off
	v_pk_mul_f32 v[80:81], v[42:43], v[164:165]
	v_cvt_pk_bf16_f32 v84, v40, v41
	s_nop 0
	v_cvt_pk_bf16_f32 v85, v80, v81
	global_store_dwordx2 v[68:69], v[84:85], off offset:16
	v_pk_mul_f32 v[80:81], v[14:15], v[136:137]
	v_cvt_pk_bf16_f32 v84, v12, v13
	s_nop 0
	v_cvt_pk_bf16_f32 v85, v80, v81
	global_store_dwordx2 v[68:69], v[84:85], off offset:256
	v_pk_mul_f32 v[80:81], v[10:11], v[128:129]
	v_cvt_pk_bf16_f32 v84, v8, v9
	s_nop 0
	v_cvt_pk_bf16_f32 v85, v80, v81
	global_store_dwordx2 v[68:69], v[84:85], off offset:272
	v_pk_mul_f32 v[68:69], v[38:39], v[162:163]
	v_cvt_pk_bf16_f32 v80, v36, v37
	s_nop 0
	v_cvt_pk_bf16_f32 v81, v68, v69
	v_lshl_add_u64 v[68:69], v[64:65], 0, s[0:1]
	s_mov_b32 s0, 0x160000
	v_add_co_u32_e32 v64, vcc, s0, v64
	s_mov_b64 s[0:1], 0
	s_nop 0
	v_addc_co_u32_e32 v65, vcc, 0, v65, vcc
	global_store_dwordx2 v[64:65], v[80:81], off
	v_pk_mul_f32 v[64:65], v[34:35], v[164:165]
	v_cvt_pk_bf16_f32 v80, v32, v33
	s_nop 0
	v_cvt_pk_bf16_f32 v81, v64, v65
	global_store_dwordx2 v[68:69], v[80:81], off offset:16
	v_pk_mul_f32 v[64:65], v[6:7], v[136:137]
	v_cvt_pk_bf16_f32 v80, v4, v5
	s_nop 0
	v_cvt_pk_bf16_f32 v81, v64, v65
	global_store_dwordx2 v[68:69], v[80:81], off offset:256
	v_pk_mul_f32 v[64:65], v[2:3], v[128:129]
	v_cvt_pk_bf16_f32 v80, v0, v1
	s_nop 0
	v_cvt_pk_bf16_f32 v81, v64, v65
	s_nop 1
	global_store_dwordx2 v[68:69], v[80:81], off offset:272
